# GEMM K-loops without any s_setprio toggling (on top of v83)
# speedup vs baseline: 1.0148x; 1.0024x over previous
; #define PG8_STAGE(bufoff, gbase, voff) do { _Pragma("unroll") for (int _i = 0; _i < 2; ++_i) \
;         __builtin_amdgcn_global_load_lds((const unsigned*)((const char*)(gbase) + (voff)[_i]), (LAS unsigned*)(lds + (bufoff) + ldsw + _i * 8192), 16, 0, 0); } while (0)
; #define PG8_LDA(dst, b, h) do { _Pragma("unroll") for (int m = 0; m < 4; ++m) _Pragma("unroll") for (int k = 0; k < 2; ++k) dst[m][k] = *(const LAS bf16x8*)(lds + PG8_SA(b, h) + aoff + m * 2048 + k * 1024); } while (0)
; #define PG8_LDB(dst, b, h) do { _Pragma("unroll") for (int n = 0; n < 2; ++n) _Pragma("unroll") for (int k = 0; k < 2; ++k) dst[n][k] = *(const LAS bf16x8*)(lds + PG8_SB(b, h) + boff + n * 2048 + k * 1024); } while (0)
; #define PG8_MMA(ai, bj, At, Bt) do { __builtin_amdgcn_s_setprio(1); _Pragma("unroll") for (int m = 0; m < 4; ++m) _Pragma("unroll") for (int n = 0; n < 2; ++n) _Pragma("unroll") for (int k = 0; k < 2; ++k) \
;         acc[ai][bj][m][n] = __builtin_amdgcn_mfma_f32_16x16x32_bf16(Bt[n][k], At[m][k], acc[ai][bj][m][n], 0, 0, 0); __builtin_amdgcn_s_setprio(0); } while (0)
; #define PG8_WAIT_V(n) asm volatile("s_waitcnt vmcnt(" #n ")" ::: "memory")
; #define PG8_WAIT_L(n) asm volatile("s_waitcnt lgkmcnt(" #n ")" ::: "memory")
; #define PG8_BAR __builtin_amdgcn_s_barrier()
; template <class Epi, bool SP2 = false>
; __device__ __forceinline__ void gemm_phase(LAS unsigned char* lds, const Gemm g, const StaticOrder& S, const Epi& E) {
;     ...
;         for (int t = 0; t < nt; t += 2) {
;             const bool last = (t == nt - 2);
;             const char* a1 = cA + (size_t)(t + 1) * kstep;
;             const char* a2 = last ? nA : cA + (size_t)(t + 2) * kstep; const char* b2 = last ? nB : cB + (size_t)(t + 2) * kstep;
;             const char* a3 = a2 + kstep; const char* b3 = b2 + kstep;
;             if constexpr (SP2) {
;             PG8_LDB(B0, 0, 0); PG8_LDB(B1, 0, 1); PG8_SCHED; PG8_LDA(At, 0, 0); PG8_STAGE(PG8_SA(1, 1), a1 + hstepA, voffA);
;             PG8_WAIT_V(8); PG8_WAIT_L(0); PG8_BAR; PG8_MMA(0, 0, At, B0); PG8_MMA(0, 1, At, B1); PG8_BAR; PG8_SCHED;
;             PG8_LDA(At, 0, 1); PG8_STAGE(PG8_SB(0, 0), b2, voffB); PG8_STAGE(PG8_SB(0, 1), b2 + hstepB, voffB); PG8_STAGE(PG8_SA(0, 0), a2, voffA);
;             PG8_WAIT_V(8); PG8_WAIT_L(0); PG8_BAR; PG8_MMA(1, 0, At, B0); PG8_MMA(1, 1, At, B1); PG8_BAR; PG8_SCHED;
.LBB0_263:
	ds_read_b128 v[152:155], v149
	ds_read_b128 v[156:159], v149 offset:1024
	ds_read_b128 v[160:163], v149 offset:2048
	ds_read_b128 v[164:167], v149 offset:3072
	ds_read_b128 v[168:171], v150
	ds_read_b128 v[172:175], v150 offset:1024
	ds_read_b128 v[176:179], v150 offset:2048
	ds_read_b128 v[180:183], v150 offset:3072
	s_add_u32 s44, s34, 0xfffc0080
	s_addc_u32 s45, s35, -1
	s_cmp_eq_u32 s75, 12
	s_cselect_b32 s51, s27, s45
	s_cselect_b32 s50, s67, s44
	s_cselect_b32 s45, s25, s74
	s_cselect_b32 s44, s72, s73
	v_lshl_add_u64 v[146:147], s[34:35], 0, v[138:139]
	s_add_i32 m0, s41, 0xc000
	ds_read_b128 v[184:187], v151
	ds_read_b128 v[188:191], v151 offset:1024
	ds_read_b128 v[192:195], v151 offset:2048
	ds_read_b128 v[196:199], v151 offset:3072
	ds_read_b128 v[200:203], v151 offset:4096
	ds_read_b128 v[204:207], v151 offset:5120
	ds_read_b128 v[208:211], v151 offset:6144
	ds_read_b128 v[212:215], v151 offset:7168
	global_load_lds_dwordx4 v[146:147], off
	v_lshl_add_u64 v[146:147], s[34:35], 0, v[140:141]
	s_add_i32 m0, s41, 0xe000
	s_nop 0
	global_load_lds_dwordx4 v[146:147], off
	s_waitcnt vmcnt(8)
	s_waitcnt lgkmcnt(0)
	s_barrier
	v_mfma_f32_16x16x32_bf16 v[124:127], v[152:155], v[184:187], v[124:127]
	v_mfma_f32_16x16x32_bf16 v[120:123], v[160:163], v[184:187], v[120:123]
	v_mfma_f32_16x16x32_bf16 v[108:111], v[152:155], v[192:195], v[108:111]
	v_mfma_f32_16x16x32_bf16 v[104:107], v[160:163], v[192:195], v[104:107]
	v_mfma_f32_16x16x32_bf16 v[92:95], v[152:155], v[200:203], v[92:95]
	v_mfma_f32_16x16x32_bf16 v[88:91], v[160:163], v[200:203], v[88:91]
	v_mfma_f32_16x16x32_bf16 v[76:79], v[152:155], v[208:211], v[76:79]
	v_mfma_f32_16x16x32_bf16 v[72:75], v[160:163], v[208:211], v[72:75]
	v_mfma_f32_16x16x32_bf16 v[124:127], v[156:159], v[188:191], v[124:127]
	v_mfma_f32_16x16x32_bf16 v[120:123], v[164:167], v[188:191], v[120:123]
	v_mfma_f32_16x16x32_bf16 v[108:111], v[156:159], v[196:199], v[108:111]
	v_mfma_f32_16x16x32_bf16 v[104:107], v[164:167], v[196:199], v[104:107]
	v_mfma_f32_16x16x32_bf16 v[92:95], v[156:159], v[204:207], v[92:95]
	v_mfma_f32_16x16x32_bf16 v[88:91], v[164:167], v[204:207], v[88:91]
	v_mfma_f32_16x16x32_bf16 v[76:79], v[156:159], v[212:215], v[76:79]
	v_mfma_f32_16x16x32_bf16 v[72:75], v[164:167], v[212:215], v[72:75]
	v_mfma_f32_16x16x32_bf16 v[116:119], v[168:171], v[184:187], v[116:119]
	v_mfma_f32_16x16x32_bf16 v[112:115], v[176:179], v[184:187], v[112:115]
	v_mfma_f32_16x16x32_bf16 v[100:103], v[168:171], v[192:195], v[100:103]
	v_mfma_f32_16x16x32_bf16 v[96:99], v[176:179], v[192:195], v[96:99]
	v_mfma_f32_16x16x32_bf16 v[84:87], v[168:171], v[200:203], v[84:87]
	v_mfma_f32_16x16x32_bf16 v[80:83], v[176:179], v[200:203], v[80:83]
	v_mfma_f32_16x16x32_bf16 v[68:71], v[168:171], v[208:211], v[68:71]
	v_mfma_f32_16x16x32_bf16 v[64:67], v[176:179], v[208:211], v[64:67]
	v_mfma_f32_16x16x32_bf16 v[116:119], v[172:175], v[188:191], v[116:119]
	v_mfma_f32_16x16x32_bf16 v[112:115], v[180:183], v[188:191], v[112:115]
	v_mfma_f32_16x16x32_bf16 v[100:103], v[172:175], v[196:199], v[100:103]
	v_mfma_f32_16x16x32_bf16 v[96:99], v[180:183], v[196:199], v[96:99]
	v_mfma_f32_16x16x32_bf16 v[84:87], v[172:175], v[204:207], v[84:87]
	v_mfma_f32_16x16x32_bf16 v[80:83], v[180:183], v[204:207], v[80:83]
	v_mfma_f32_16x16x32_bf16 v[68:71], v[172:175], v[212:215], v[68:71]
	v_mfma_f32_16x16x32_bf16 v[64:67], v[180:183], v[212:215], v[64:67]
	s_barrier
	s_add_i32 s68, s64, s3
	v_lshl_add_u64 v[146:147], s[44:45], 0, v[134:135]
	s_mov_b32 m0, s68
	ds_read_b128 v[184:187], v151 offset:16384
	ds_read_b128 v[188:191], v151 offset:17408
	ds_read_b128 v[192:195], v151 offset:18432
	ds_read_b128 v[196:199], v151 offset:19456
	ds_read_b128 v[200:203], v151 offset:20480
	ds_read_b128 v[204:207], v151 offset:21504
	ds_read_b128 v[208:211], v151 offset:22528
	ds_read_b128 v[212:215], v151 offset:23552
	global_load_lds_dwordx4 v[146:147], off
	s_add_i32 m0, s68, 0x2000
	s_add_u32 s68, s44, 0x40000
	v_lshl_add_u64 v[216:217], s[44:45], 0, v[130:131]
	s_addc_u32 s69, s45, 0
	s_add_i32 s70, s65, s3
	global_load_lds_dwordx4 v[216:217], off
	v_lshl_add_u64 v[218:219], s[68:69], 0, v[134:135]
	s_mov_b32 m0, s70
	v_lshl_add_u64 v[220:221], s[50:51], 0, v[132:133]
	global_load_lds_dwordx4 v[218:219], off
	v_lshl_add_u64 v[218:219], s[68:69], 0, v[130:131]
	s_add_i32 m0, s70, 0x2000
	s_nop 0
	global_load_lds_dwordx4 v[218:219], off
	v_lshl_add_u64 v[218:219], s[50:51], 0, v[136:137]
	s_mov_b32 m0, s41
	s_nop 0
	global_load_lds_dwordx4 v[218:219], off
	s_mov_b32 m0, s54
	s_nop 0
	global_load_lds_dwordx4 v[220:221], off
	s_waitcnt vmcnt(8)
	s_waitcnt lgkmcnt(0)
	s_barrier
; #define PG8_STAGE(bufoff, gbase, voff) do { _Pragma("unroll") for (int _i = 0; _i < 2; ++_i) \
;         __builtin_amdgcn_global_load_lds((const unsigned*)((const char*)(gbase) + (voff)[_i]), (LAS unsigned*)(lds + (bufoff) + ldsw + _i * 8192), 16, 0, 0); } while (0)
; #define PG8_LDA(dst, b, h) do { _Pragma("unroll") for (int m = 0; m < 4; ++m) _Pragma("unroll") for (int k = 0; k < 2; ++k) dst[m][k] = *(const LAS bf16x8*)(lds + PG8_SA(b, h) + aoff + m * 2048 + k * 1024); } while (0)
; #define PG8_LDB(dst, b, h) do { _Pragma("unroll") for (int n = 0; n < 2; ++n) _Pragma("unroll") for (int k = 0; k < 2; ++k) dst[n][k] = *(const LAS bf16x8*)(lds + PG8_SB(b, h) + boff + n * 2048 + k * 1024); } while (0)
; #define PG8_MMA(ai, bj, At, Bt) do { __builtin_amdgcn_s_setprio(1); _Pragma("unroll") for (int m = 0; m < 4; ++m) _Pragma("unroll") for (int n = 0; n < 2; ++n) _Pragma("unroll") for (int k = 0; k < 2; ++k) \
;         acc[ai][bj][m][n] = __builtin_amdgcn_mfma_f32_16x16x32_bf16(Bt[n][k], At[m][k], acc[ai][bj][m][n], 0, 0, 0); __builtin_amdgcn_s_setprio(0); } while (0)
; #define PG8_WAIT_V(n) asm volatile("s_waitcnt vmcnt(" #n ")" ::: "memory")
; #define PG8_WAIT_L(n) asm volatile("s_waitcnt lgkmcnt(" #n ")" ::: "memory")
; #define PG8_BAR __builtin_amdgcn_s_barrier()
; #define PG8_SCHED __builtin_amdgcn_sched_barrier(0)
; template <class Epi, bool SP2 = false>
; __device__ __forceinline__ void gemm_phase(LAS unsigned char* lds, const Gemm g, const StaticOrder& S, const Epi& E) {
;     ...
;             PG8_WAIT_V(8); PG8_WAIT_L(0); PG8_BAR; PG8_MMA(1, 0, At, B0); PG8_MMA(1, 1, At, B1); PG8_BAR; PG8_SCHED;
;             PG8_LDB(B0, 1, 0); PG8_LDB(B1, 1, 1); PG8_SCHED; PG8_LDA(At, 1, 0); PG8_STAGE(PG8_SA(0, 1), a2 + hstepA, voffA);
;             PG8_WAIT_V(8); PG8_WAIT_L(0); PG8_BAR; PG8_MMA(0, 0, At, B0); PG8_MMA(0, 1, At, B1); PG8_BAR; PG8_SCHED;
	v_mfma_f32_16x16x32_bf16 v[60:63], v[152:155], v[184:187], v[60:63]
	v_mfma_f32_16x16x32_bf16 v[56:59], v[160:163], v[184:187], v[56:59]
	v_mfma_f32_16x16x32_bf16 v[44:47], v[152:155], v[192:195], v[44:47]
	v_mfma_f32_16x16x32_bf16 v[40:43], v[160:163], v[192:195], v[40:43]
	v_mfma_f32_16x16x32_bf16 v[28:31], v[152:155], v[200:203], v[28:31]
	v_mfma_f32_16x16x32_bf16 v[24:27], v[160:163], v[200:203], v[24:27]
	v_mfma_f32_16x16x32_bf16 v[12:15], v[152:155], v[208:211], v[12:15]
	v_mfma_f32_16x16x32_bf16 v[8:11], v[160:163], v[208:211], v[8:11]
	v_mfma_f32_16x16x32_bf16 v[60:63], v[156:159], v[188:191], v[60:63]
	v_mfma_f32_16x16x32_bf16 v[56:59], v[164:167], v[188:191], v[56:59]
	v_mfma_f32_16x16x32_bf16 v[44:47], v[156:159], v[196:199], v[44:47]
	v_mfma_f32_16x16x32_bf16 v[40:43], v[164:167], v[196:199], v[40:43]
	v_mfma_f32_16x16x32_bf16 v[28:31], v[156:159], v[204:207], v[28:31]
	v_mfma_f32_16x16x32_bf16 v[24:27], v[164:167], v[204:207], v[24:27]
	v_mfma_f32_16x16x32_bf16 v[12:15], v[156:159], v[212:215], v[12:15]
	v_mfma_f32_16x16x32_bf16 v[8:11], v[164:167], v[212:215], v[8:11]
	v_mfma_f32_16x16x32_bf16 v[52:55], v[168:171], v[184:187], v[52:55]
	v_mfma_f32_16x16x32_bf16 v[48:51], v[176:179], v[184:187], v[48:51]
	v_mfma_f32_16x16x32_bf16 v[36:39], v[168:171], v[192:195], v[36:39]
	v_mfma_f32_16x16x32_bf16 v[32:35], v[176:179], v[192:195], v[32:35]
	v_mfma_f32_16x16x32_bf16 v[20:23], v[168:171], v[200:203], v[20:23]
	v_mfma_f32_16x16x32_bf16 v[16:19], v[176:179], v[200:203], v[16:19]
	v_mfma_f32_16x16x32_bf16 v[4:7], v[168:171], v[208:211], v[4:7]
	v_mfma_f32_16x16x32_bf16 v[0:3], v[176:179], v[208:211], v[0:3]
	v_mfma_f32_16x16x32_bf16 v[52:55], v[172:175], v[188:191], v[52:55]
	v_mfma_f32_16x16x32_bf16 v[48:51], v[180:183], v[188:191], v[48:51]
	v_mfma_f32_16x16x32_bf16 v[36:39], v[172:175], v[196:199], v[36:39]
	v_mfma_f32_16x16x32_bf16 v[32:35], v[180:183], v[196:199], v[32:35]
	v_mfma_f32_16x16x32_bf16 v[20:23], v[172:175], v[204:207], v[20:23]
	v_mfma_f32_16x16x32_bf16 v[16:19], v[180:183], v[204:207], v[16:19]
	v_mfma_f32_16x16x32_bf16 v[4:7], v[172:175], v[212:215], v[4:7]
	v_mfma_f32_16x16x32_bf16 v[0:3], v[180:183], v[212:215], v[0:3]
	s_barrier
	s_add_i32 s68, 0, 0x18000
	s_add_i32 s69, 0, 0x1c000
	v_add_u32_e32 v164, s68, v148
	v_add_u32_e32 v180, s69, v148
	ds_read_b128 v[152:155], v164
	ds_read_b128 v[156:159], v164 offset:1024
	ds_read_b128 v[160:163], v164 offset:2048
	ds_read_b128 v[164:167], v164 offset:3072
	ds_read_b128 v[168:171], v180
	ds_read_b128 v[172:175], v180 offset:1024
	ds_read_b128 v[176:179], v180 offset:2048
	ds_read_b128 v[180:183], v180 offset:3072
	s_add_u32 s50, s50, 0x40000
	s_addc_u32 s51, s51, 0
	s_mov_b32 m0, s55
	v_lshl_add_u64 v[222:223], s[50:51], 0, v[136:137]
	ds_read_b128 v[184:187], v151 offset:32768
	ds_read_b128 v[188:191], v151 offset:33792
	ds_read_b128 v[192:195], v151 offset:34816
	ds_read_b128 v[196:199], v151 offset:35840
	ds_read_b128 v[200:203], v151 offset:36864
	ds_read_b128 v[204:207], v151 offset:37888
	ds_read_b128 v[208:211], v151 offset:38912
	ds_read_b128 v[212:215], v151 offset:39936
	global_load_lds_dwordx4 v[222:223], off
	v_lshl_add_u64 v[222:223], s[50:51], 0, v[132:133]
	s_mov_b32 m0, s56
	s_nop 0
	global_load_lds_dwordx4 v[222:223], off
	s_waitcnt vmcnt(8)
	s_waitcnt lgkmcnt(0)
	s_barrier
	v_mfma_f32_16x16x32_bf16 v[124:127], v[152:155], v[184:187], v[124:127]
	v_mfma_f32_16x16x32_bf16 v[120:123], v[160:163], v[184:187], v[120:123]
	v_mfma_f32_16x16x32_bf16 v[108:111], v[152:155], v[192:195], v[108:111]
	v_mfma_f32_16x16x32_bf16 v[104:107], v[160:163], v[192:195], v[104:107]
	v_mfma_f32_16x16x32_bf16 v[92:95], v[152:155], v[200:203], v[92:95]
	v_mfma_f32_16x16x32_bf16 v[88:91], v[160:163], v[200:203], v[88:91]
	v_mfma_f32_16x16x32_bf16 v[76:79], v[152:155], v[208:211], v[76:79]
	v_mfma_f32_16x16x32_bf16 v[72:75], v[160:163], v[208:211], v[72:75]
	v_mfma_f32_16x16x32_bf16 v[124:127], v[156:159], v[188:191], v[124:127]
	v_mfma_f32_16x16x32_bf16 v[120:123], v[164:167], v[188:191], v[120:123]
	v_mfma_f32_16x16x32_bf16 v[108:111], v[156:159], v[196:199], v[108:111]
	v_mfma_f32_16x16x32_bf16 v[104:107], v[164:167], v[196:199], v[104:107]
	v_mfma_f32_16x16x32_bf16 v[92:95], v[156:159], v[204:207], v[92:95]
	v_mfma_f32_16x16x32_bf16 v[88:91], v[164:167], v[204:207], v[88:91]
	v_mfma_f32_16x16x32_bf16 v[76:79], v[156:159], v[212:215], v[76:79]
	v_mfma_f32_16x16x32_bf16 v[72:75], v[164:167], v[212:215], v[72:75]
	v_mfma_f32_16x16x32_bf16 v[116:119], v[168:171], v[184:187], v[116:119]
	v_mfma_f32_16x16x32_bf16 v[112:115], v[176:179], v[184:187], v[112:115]
	v_mfma_f32_16x16x32_bf16 v[100:103], v[168:171], v[192:195], v[100:103]
	v_mfma_f32_16x16x32_bf16 v[96:99], v[176:179], v[192:195], v[96:99]
	v_mfma_f32_16x16x32_bf16 v[84:87], v[168:171], v[200:203], v[84:87]
	v_mfma_f32_16x16x32_bf16 v[80:83], v[176:179], v[200:203], v[80:83]
	v_mfma_f32_16x16x32_bf16 v[68:71], v[168:171], v[208:211], v[68:71]
	v_mfma_f32_16x16x32_bf16 v[64:67], v[176:179], v[208:211], v[64:67]
	v_mfma_f32_16x16x32_bf16 v[116:119], v[172:175], v[188:191], v[116:119]
	v_mfma_f32_16x16x32_bf16 v[112:115], v[180:183], v[188:191], v[112:115]
	v_mfma_f32_16x16x32_bf16 v[100:103], v[172:175], v[196:199], v[100:103]
	v_mfma_f32_16x16x32_bf16 v[96:99], v[180:183], v[196:199], v[96:99]
	v_mfma_f32_16x16x32_bf16 v[84:87], v[172:175], v[204:207], v[84:87]
	v_mfma_f32_16x16x32_bf16 v[80:83], v[180:183], v[204:207], v[80:83]
	v_mfma_f32_16x16x32_bf16 v[68:71], v[172:175], v[212:215], v[68:71]
	v_mfma_f32_16x16x32_bf16 v[64:67], v[180:183], v[212:215], v[64:67]
	s_barrier
; #define PG8_STAGE(bufoff, gbase, voff) do { _Pragma("unroll") for (int _i = 0; _i < 2; ++_i) \
;         __builtin_amdgcn_global_load_lds((const unsigned*)((const char*)(gbase) + (voff)[_i]), (LAS unsigned*)(lds + (bufoff) + ldsw + _i * 8192), 16, 0, 0); } while (0)
; #define PG8_LDA(dst, b, h) do { _Pragma("unroll") for (int m = 0; m < 4; ++m) _Pragma("unroll") for (int k = 0; k < 2; ++k) dst[m][k] = *(const LAS bf16x8*)(lds + PG8_SA(b, h) + aoff + m * 2048 + k * 1024); } while (0)
; #define PG8_LDB(dst, b, h) do { _Pragma("unroll") for (int n = 0; n < 2; ++n) _Pragma("unroll") for (int k = 0; k < 2; ++k) dst[n][k] = *(const LAS bf16x8*)(lds + PG8_SB(b, h) + boff + n * 2048 + k * 1024); } while (0)
; #define PG8_WAIT_V(n) asm volatile("s_waitcnt vmcnt(" #n ")" ::: "memory")
; template <class Epi, bool SP2 = false>
; __device__ __forceinline__ void gemm_phase(LAS unsigned char* lds, const Gemm g, const StaticOrder& S, const Epi& E) {
;     ...
;         for (int t = 0; t < nt; t += 2) {
;             const bool last = (t == nt - 2);
;             const char* a1 = cA + (size_t)(t + 1) * kstep;
;             const char* a2 = last ? nA : cA + (size_t)(t + 2) * kstep; const char* b2 = last ? nB : cB + (size_t)(t + 2) * kstep;
;             const char* a3 = a2 + kstep; const char* b3 = b2 + kstep;
;             if constexpr (SP2) {
;             PG8_LDB(B0, 0, 0); PG8_LDB(B1, 0, 1); PG8_SCHED; PG8_LDA(At, 0, 0); PG8_STAGE(PG8_SA(1, 1), a1 + hstepA, voffA);
;             PG8_WAIT_V(8); PG8_WAIT_L(0); PG8_BAR; PG8_MMA(0, 0, At, B0); PG8_MMA(0, 1, At, B1); PG8_BAR; PG8_SCHED;
;             PG8_LDA(At, 0, 1); PG8_STAGE(PG8_SB(0, 0), b2, voffB); PG8_STAGE(PG8_SB(0, 1), b2 + hstepB, voffB); PG8_STAGE(PG8_SA(0, 0), a2, voffA);
;             PG8_WAIT_V(8); PG8_WAIT_L(0); PG8_BAR; PG8_MMA(1, 0, At, B0); PG8_MMA(1, 1, At, B1); PG8_BAR; PG8_SCHED;
;             PG8_LDB(B0, 1, 0); PG8_LDB(B1, 1, 1); PG8_SCHED; PG8_LDA(At, 1, 0); PG8_STAGE(PG8_SA(0, 1), a2 + hstepA, voffA);
;             PG8_WAIT_V(8); PG8_WAIT_L(0); PG8_BAR; PG8_MMA(0, 0, At, B0); PG8_MMA(0, 1, At, B1); PG8_BAR; PG8_SCHED;
;             PG8_LDA(At, 1, 1); PG8_STAGE(PG8_SB(1, 0), b3, voffB); PG8_STAGE(PG8_SB(1, 1), b3 + hstepB, voffB); PG8_STAGE(PG8_SA(1, 0), a3, voffA);
;             PG8_WAIT_V(8); PG8_WAIT_L(0); PG8_BAR; PG8_MMA(1, 0, At, B0); PG8_MMA(1, 1, At, B1); PG8_BAR; PG8_SCHED;
	s_add_i32 s50, s68, s3
	v_lshl_add_u64 v[146:147], v[146:147], 0, s[12:13]
	s_mov_b32 m0, s50
	ds_read_b128 v[184:187], v151 offset:49152
	ds_read_b128 v[188:191], v151 offset:50176
	ds_read_b128 v[192:195], v151 offset:51200
	ds_read_b128 v[196:199], v151 offset:52224
	ds_read_b128 v[200:203], v151 offset:53248
	ds_read_b128 v[204:207], v151 offset:54272
	ds_read_b128 v[208:211], v151 offset:55296
	ds_read_b128 v[212:215], v151 offset:56320
	global_load_lds_dwordx4 v[146:147], off
	s_add_i32 m0, s50, 0x2000
	s_add_u32 s44, s44, 0x40080
	v_lshl_add_u64 v[146:147], v[216:217], 0, s[12:13]
	s_addc_u32 s45, s45, 0
	s_add_i32 s50, s69, s3
	global_load_lds_dwordx4 v[146:147], off
	v_lshl_add_u64 v[146:147], s[44:45], 0, v[134:135]
	s_mov_b32 m0, s50
	s_nop 0
	global_load_lds_dwordx4 v[146:147], off
	v_lshl_add_u64 v[146:147], s[44:45], 0, v[130:131]
	s_add_i32 m0, s50, 0x2000
	s_nop 0
	global_load_lds_dwordx4 v[146:147], off
	v_lshl_add_u64 v[146:147], v[218:219], 0, s[12:13]
	s_mov_b32 m0, s60
	s_nop 0
	global_load_lds_dwordx4 v[146:147], off
	v_lshl_add_u64 v[146:147], v[220:221], 0, s[12:13]
	s_mov_b32 m0, s61
	s_nop 0
	global_load_lds_dwordx4 v[146:147], off
	s_waitcnt vmcnt(8)
	s_waitcnt lgkmcnt(0)
	s_barrier
	v_mfma_f32_16x16x32_bf16 v[60:63], v[152:155], v[184:187], v[60:63]
	v_mfma_f32_16x16x32_bf16 v[56:59], v[160:163], v[184:187], v[56:59]
	v_mfma_f32_16x16x32_bf16 v[44:47], v[152:155], v[192:195], v[44:47]
	v_mfma_f32_16x16x32_bf16 v[40:43], v[160:163], v[192:195], v[40:43]
	v_mfma_f32_16x16x32_bf16 v[28:31], v[152:155], v[200:203], v[28:31]
	v_mfma_f32_16x16x32_bf16 v[24:27], v[160:163], v[200:203], v[24:27]
	v_mfma_f32_16x16x32_bf16 v[12:15], v[152:155], v[208:211], v[12:15]
	v_mfma_f32_16x16x32_bf16 v[8:11], v[160:163], v[208:211], v[8:11]
	v_mfma_f32_16x16x32_bf16 v[60:63], v[156:159], v[188:191], v[60:63]
	v_mfma_f32_16x16x32_bf16 v[56:59], v[164:167], v[188:191], v[56:59]
	v_mfma_f32_16x16x32_bf16 v[44:47], v[156:159], v[196:199], v[44:47]
	v_mfma_f32_16x16x32_bf16 v[40:43], v[164:167], v[196:199], v[40:43]
	v_mfma_f32_16x16x32_bf16 v[28:31], v[156:159], v[204:207], v[28:31]
	v_mfma_f32_16x16x32_bf16 v[24:27], v[164:167], v[204:207], v[24:27]
	v_mfma_f32_16x16x32_bf16 v[12:15], v[156:159], v[212:215], v[12:15]
	v_mfma_f32_16x16x32_bf16 v[8:11], v[164:167], v[212:215], v[8:11]
	v_mfma_f32_16x16x32_bf16 v[52:55], v[168:171], v[184:187], v[52:55]
	v_mfma_f32_16x16x32_bf16 v[48:51], v[176:179], v[184:187], v[48:51]
	v_mfma_f32_16x16x32_bf16 v[36:39], v[168:171], v[192:195], v[36:39]
	v_mfma_f32_16x16x32_bf16 v[32:35], v[176:179], v[192:195], v[32:35]
	v_mfma_f32_16x16x32_bf16 v[20:23], v[168:171], v[200:203], v[20:23]
	v_mfma_f32_16x16x32_bf16 v[16:19], v[176:179], v[200:203], v[16:19]
	v_mfma_f32_16x16x32_bf16 v[4:7], v[168:171], v[208:211], v[4:7]
	v_mfma_f32_16x16x32_bf16 v[0:3], v[176:179], v[208:211], v[0:3]
	v_mfma_f32_16x16x32_bf16 v[52:55], v[172:175], v[188:191], v[52:55]
	v_mfma_f32_16x16x32_bf16 v[48:51], v[180:183], v[188:191], v[48:51]
	v_mfma_f32_16x16x32_bf16 v[36:39], v[172:175], v[196:199], v[36:39]
	v_mfma_f32_16x16x32_bf16 v[32:35], v[180:183], v[196:199], v[32:35]
	v_mfma_f32_16x16x32_bf16 v[20:23], v[172:175], v[204:207], v[20:23]
	v_mfma_f32_16x16x32_bf16 v[16:19], v[180:183], v[204:207], v[16:19]
	v_mfma_f32_16x16x32_bf16 v[4:7], v[172:175], v[212:215], v[4:7]
	v_mfma_f32_16x16x32_bf16 v[0:3], v[180:183], v[212:215], v[0:3]
	s_barrier
	s_add_i32 s75, s75, 2
	s_add_u32 s34, s34, 0x100
	s_addc_u32 s35, s35, 0
	s_add_u32 s73, s73, 0x100
	s_addc_u32 s74, s74, 0
	s_cmp_gt_u32 s75, 13
	s_cbranch_scc0 .LBB0_263
	s_and_b64 vcc, exec, s[18:19]
	s_cbranch_vccz .LBB0_266
	s_barrier

; #define PG8_STAGE(bufoff, gbase, voff) do { _Pragma("unroll") for (int _i = 0; _i < 2; ++_i) \
;         __builtin_amdgcn_global_load_lds((const unsigned*)((const char*)(gbase) + (voff)[_i]), (LAS unsigned*)(lds + (bufoff) + ldsw + _i * 8192), 16, 0, 0); } while (0)
; #define PG8_LDA(dst, b, h) do { _Pragma("unroll") for (int m = 0; m < 4; ++m) _Pragma("unroll") for (int k = 0; k < 2; ++k) dst[m][k] = *(const LAS bf16x8*)(lds + PG8_SA(b, h) + aoff + m * 2048 + k * 1024); } while (0)
; #define PG8_LDB(dst, b, h) do { _Pragma("unroll") for (int n = 0; n < 2; ++n) _Pragma("unroll") for (int k = 0; k < 2; ++k) dst[n][k] = *(const LAS bf16x8*)(lds + PG8_SB(b, h) + boff + n * 2048 + k * 1024); } while (0)
; #define PG8_MMA(ai, bj, At, Bt) do { __builtin_amdgcn_s_setprio(1); _Pragma("unroll") for (int m = 0; m < 4; ++m) _Pragma("unroll") for (int n = 0; n < 2; ++n) _Pragma("unroll") for (int k = 0; k < 2; ++k) \
;         acc[ai][bj][m][n] = __builtin_amdgcn_mfma_f32_16x16x32_bf16(Bt[n][k], At[m][k], acc[ai][bj][m][n], 0, 0, 0); __builtin_amdgcn_s_setprio(0); } while (0)
; #define PG8_WAIT_V(n) asm volatile("s_waitcnt vmcnt(" #n ")" ::: "memory")
; #define PG8_WAIT_L(n) asm volatile("s_waitcnt lgkmcnt(" #n ")" ::: "memory")
; #define PG8_BAR __builtin_amdgcn_s_barrier()
; template <class Epi, bool SP2 = false>
; __device__ __forceinline__ void gemm_phase(LAS unsigned char* lds, const Gemm g, const StaticOrder& S, const Epi& E) {
;     ...
;         for (int t = 0; t < nt; t += 2) {
;             const bool last = (t == nt - 2);
;             const char* a1 = cA + (size_t)(t + 1) * kstep;
;             const char* a2 = last ? nA : cA + (size_t)(t + 2) * kstep; const char* b2 = last ? nB : cB + (size_t)(t + 2) * kstep;
;             const char* a3 = a2 + kstep; const char* b3 = b2 + kstep;
;             if constexpr (SP2) {
;             PG8_LDB(B0, 0, 0); PG8_LDB(B1, 0, 1); PG8_SCHED; PG8_LDA(At, 0, 0); PG8_STAGE(PG8_SA(1, 1), a1 + hstepA, voffA);
;             PG8_WAIT_V(8); PG8_WAIT_L(0); PG8_BAR; PG8_MMA(0, 0, At, B0); PG8_MMA(0, 1, At, B1); PG8_BAR; PG8_SCHED;
;             PG8_LDA(At, 0, 1); PG8_STAGE(PG8_SB(0, 0), b2, voffB); PG8_STAGE(PG8_SB(0, 1), b2 + hstepB, voffB); PG8_STAGE(PG8_SA(0, 0), a2, voffA);
;             PG8_WAIT_V(8); PG8_WAIT_L(0); PG8_BAR; PG8_MMA(1, 0, At, B0); PG8_MMA(1, 1, At, B1); PG8_BAR; PG8_SCHED;
.LBB0_334:
	ds_read_b128 v[150:153], v147
	ds_read_b128 v[154:157], v147 offset:1024
	ds_read_b128 v[158:161], v147 offset:2048
	ds_read_b128 v[162:165], v147 offset:3072
	ds_read_b128 v[166:169], v148
	ds_read_b128 v[170:173], v148 offset:1024
	ds_read_b128 v[174:177], v148 offset:2048
	ds_read_b128 v[178:181], v148 offset:3072
	s_add_u32 s52, s34, 0xfff50080
	s_addc_u32 s53, s35, -1
	s_cmp_eq_u32 s86, 40
	s_cselect_b32 s55, s5, s53
	s_cselect_b32 s54, s4, s52
	s_cselect_b32 s53, s51, s85
	s_cselect_b32 s52, s50, s84
	v_lshl_add_u64 v[214:215], s[34:35], 0, v[138:139]
	s_add_i32 m0, s59, 0xc000
	ds_read_b128 v[182:185], v149
	ds_read_b128 v[186:189], v149 offset:1024
	ds_read_b128 v[190:193], v149 offset:2048
	ds_read_b128 v[194:197], v149 offset:3072
	ds_read_b128 v[198:201], v149 offset:4096
	ds_read_b128 v[202:205], v149 offset:5120
	ds_read_b128 v[206:209], v149 offset:6144
	ds_read_b128 v[210:213], v149 offset:7168
	global_load_lds_dwordx4 v[214:215], off
	v_lshl_add_u64 v[214:215], s[34:35], 0, v[140:141]
	s_add_i32 m0, s59, 0xe000
	s_nop 0
	global_load_lds_dwordx4 v[214:215], off
	s_waitcnt vmcnt(8)
	s_waitcnt lgkmcnt(0)
	s_barrier
	v_mfma_f32_16x16x32_bf16 v[124:127], v[150:153], v[182:185], v[124:127]
	v_mfma_f32_16x16x32_bf16 v[120:123], v[158:161], v[182:185], v[120:123]
	v_mfma_f32_16x16x32_bf16 v[116:119], v[150:153], v[190:193], v[116:119]
	v_mfma_f32_16x16x32_bf16 v[112:115], v[158:161], v[190:193], v[112:115]
	v_mfma_f32_16x16x32_bf16 v[100:103], v[150:153], v[198:201], v[100:103]
	v_mfma_f32_16x16x32_bf16 v[96:99], v[158:161], v[198:201], v[96:99]
	v_mfma_f32_16x16x32_bf16 v[84:87], v[150:153], v[206:209], v[84:87]
	v_mfma_f32_16x16x32_bf16 v[80:83], v[158:161], v[206:209], v[80:83]
	v_mfma_f32_16x16x32_bf16 v[124:127], v[154:157], v[186:189], v[124:127]
	v_mfma_f32_16x16x32_bf16 v[120:123], v[162:165], v[186:189], v[120:123]
	v_mfma_f32_16x16x32_bf16 v[116:119], v[154:157], v[194:197], v[116:119]
	v_mfma_f32_16x16x32_bf16 v[112:115], v[162:165], v[194:197], v[112:115]
	v_mfma_f32_16x16x32_bf16 v[100:103], v[154:157], v[202:205], v[100:103]
	v_mfma_f32_16x16x32_bf16 v[96:99], v[162:165], v[202:205], v[96:99]
	v_mfma_f32_16x16x32_bf16 v[84:87], v[154:157], v[210:213], v[84:87]
	v_mfma_f32_16x16x32_bf16 v[80:83], v[162:165], v[210:213], v[80:83]
	v_mfma_f32_16x16x32_bf16 v[108:111], v[166:169], v[182:185], v[108:111]
	v_mfma_f32_16x16x32_bf16 v[104:107], v[174:177], v[182:185], v[104:107]
	v_mfma_f32_16x16x32_bf16 v[92:95], v[166:169], v[190:193], v[92:95]
	v_mfma_f32_16x16x32_bf16 v[88:91], v[174:177], v[190:193], v[88:91]
	v_mfma_f32_16x16x32_bf16 v[76:79], v[166:169], v[198:201], v[76:79]
	v_mfma_f32_16x16x32_bf16 v[72:75], v[174:177], v[198:201], v[72:75]
	v_mfma_f32_16x16x32_bf16 v[68:71], v[166:169], v[206:209], v[68:71]
	v_mfma_f32_16x16x32_bf16 v[64:67], v[174:177], v[206:209], v[64:67]
	v_mfma_f32_16x16x32_bf16 v[108:111], v[170:173], v[186:189], v[108:111]
	v_mfma_f32_16x16x32_bf16 v[104:107], v[178:181], v[186:189], v[104:107]
	v_mfma_f32_16x16x32_bf16 v[92:95], v[170:173], v[194:197], v[92:95]
	v_mfma_f32_16x16x32_bf16 v[88:91], v[178:181], v[194:197], v[88:91]
	v_mfma_f32_16x16x32_bf16 v[76:79], v[170:173], v[202:205], v[76:79]
	v_mfma_f32_16x16x32_bf16 v[72:75], v[178:181], v[202:205], v[72:75]
	v_mfma_f32_16x16x32_bf16 v[68:71], v[170:173], v[210:213], v[68:71]
	v_mfma_f32_16x16x32_bf16 v[64:67], v[178:181], v[210:213], v[64:67]
	s_barrier
	s_add_i32 s68, s74, s56
	v_lshl_add_u64 v[214:215], s[52:53], 0, v[134:135]
	s_mov_b32 m0, s68
	ds_read_b128 v[182:185], v149 offset:16384
	ds_read_b128 v[186:189], v149 offset:17408
	ds_read_b128 v[190:193], v149 offset:18432
	ds_read_b128 v[194:197], v149 offset:19456
	ds_read_b128 v[198:201], v149 offset:20480
	ds_read_b128 v[202:205], v149 offset:21504
	ds_read_b128 v[206:209], v149 offset:22528
	ds_read_b128 v[210:213], v149 offset:23552
	global_load_lds_dwordx4 v[214:215], off
	s_add_i32 m0, s68, 0x2000
	s_add_u32 s68, s52, 0xb0000
	v_lshl_add_u64 v[216:217], s[52:53], 0, v[130:131]
	s_addc_u32 s69, s53, 0
	s_add_i32 s70, s75, s56
	global_load_lds_dwordx4 v[216:217], off
	v_lshl_add_u64 v[218:219], s[68:69], 0, v[134:135]
	s_mov_b32 m0, s70
	v_lshl_add_u64 v[220:221], s[54:55], 0, v[132:133]
	global_load_lds_dwordx4 v[218:219], off
	v_lshl_add_u64 v[218:219], s[68:69], 0, v[130:131]
	s_add_i32 m0, s70, 0x2000
	s_nop 0
	global_load_lds_dwordx4 v[218:219], off
	v_lshl_add_u64 v[218:219], s[54:55], 0, v[136:137]
	s_mov_b32 m0, s59
	s_nop 0
	global_load_lds_dwordx4 v[218:219], off
	s_mov_b32 m0, s60
	s_nop 0
	global_load_lds_dwordx4 v[220:221], off
	s_waitcnt vmcnt(8)
	s_waitcnt lgkmcnt(0)
	s_barrier
; #define PG8_STAGE(bufoff, gbase, voff) do { _Pragma("unroll") for (int _i = 0; _i < 2; ++_i) \
;         __builtin_amdgcn_global_load_lds((const unsigned*)((const char*)(gbase) + (voff)[_i]), (LAS unsigned*)(lds + (bufoff) + ldsw + _i * 8192), 16, 0, 0); } while (0)
; #define PG8_LDA(dst, b, h) do { _Pragma("unroll") for (int m = 0; m < 4; ++m) _Pragma("unroll") for (int k = 0; k < 2; ++k) dst[m][k] = *(const LAS bf16x8*)(lds + PG8_SA(b, h) + aoff + m * 2048 + k * 1024); } while (0)
; #define PG8_LDB(dst, b, h) do { _Pragma("unroll") for (int n = 0; n < 2; ++n) _Pragma("unroll") for (int k = 0; k < 2; ++k) dst[n][k] = *(const LAS bf16x8*)(lds + PG8_SB(b, h) + boff + n * 2048 + k * 1024); } while (0)
; #define PG8_MMA(ai, bj, At, Bt) do { __builtin_amdgcn_s_setprio(1); _Pragma("unroll") for (int m = 0; m < 4; ++m) _Pragma("unroll") for (int n = 0; n < 2; ++n) _Pragma("unroll") for (int k = 0; k < 2; ++k) \
;         acc[ai][bj][m][n] = __builtin_amdgcn_mfma_f32_16x16x32_bf16(Bt[n][k], At[m][k], acc[ai][bj][m][n], 0, 0, 0); __builtin_amdgcn_s_setprio(0); } while (0)
; #define PG8_WAIT_V(n) asm volatile("s_waitcnt vmcnt(" #n ")" ::: "memory")
; #define PG8_WAIT_L(n) asm volatile("s_waitcnt lgkmcnt(" #n ")" ::: "memory")
; #define PG8_BAR __builtin_amdgcn_s_barrier()
; #define PG8_SCHED __builtin_amdgcn_sched_barrier(0)
; template <class Epi, bool SP2 = false>
; __device__ __forceinline__ void gemm_phase(LAS unsigned char* lds, const Gemm g, const StaticOrder& S, const Epi& E) {
;     ...
;             PG8_WAIT_V(8); PG8_WAIT_L(0); PG8_BAR; PG8_MMA(1, 0, At, B0); PG8_MMA(1, 1, At, B1); PG8_BAR; PG8_SCHED;
;             PG8_LDB(B0, 1, 0); PG8_LDB(B1, 1, 1); PG8_SCHED; PG8_LDA(At, 1, 0); PG8_STAGE(PG8_SA(0, 1), a2 + hstepA, voffA);
;             PG8_WAIT_V(8); PG8_WAIT_L(0); PG8_BAR; PG8_MMA(0, 0, At, B0); PG8_MMA(0, 1, At, B1); PG8_BAR; PG8_SCHED;
	v_mfma_f32_16x16x32_bf16 v[60:63], v[150:153], v[182:185], v[60:63]
	v_mfma_f32_16x16x32_bf16 v[56:59], v[158:161], v[182:185], v[56:59]
	v_mfma_f32_16x16x32_bf16 v[52:55], v[150:153], v[190:193], v[52:55]
	v_mfma_f32_16x16x32_bf16 v[48:51], v[158:161], v[190:193], v[48:51]
	v_mfma_f32_16x16x32_bf16 v[36:39], v[150:153], v[198:201], v[36:39]
	v_mfma_f32_16x16x32_bf16 v[32:35], v[158:161], v[198:201], v[32:35]
	v_mfma_f32_16x16x32_bf16 v[20:23], v[150:153], v[206:209], v[20:23]
	v_mfma_f32_16x16x32_bf16 v[16:19], v[158:161], v[206:209], v[16:19]
	v_mfma_f32_16x16x32_bf16 v[60:63], v[154:157], v[186:189], v[60:63]
	v_mfma_f32_16x16x32_bf16 v[56:59], v[162:165], v[186:189], v[56:59]
	v_mfma_f32_16x16x32_bf16 v[52:55], v[154:157], v[194:197], v[52:55]
	v_mfma_f32_16x16x32_bf16 v[48:51], v[162:165], v[194:197], v[48:51]
	v_mfma_f32_16x16x32_bf16 v[36:39], v[154:157], v[202:205], v[36:39]
	v_mfma_f32_16x16x32_bf16 v[32:35], v[162:165], v[202:205], v[32:35]
	v_mfma_f32_16x16x32_bf16 v[20:23], v[154:157], v[210:213], v[20:23]
	v_mfma_f32_16x16x32_bf16 v[16:19], v[162:165], v[210:213], v[16:19]
	v_mfma_f32_16x16x32_bf16 v[44:47], v[166:169], v[182:185], v[44:47]
	v_mfma_f32_16x16x32_bf16 v[40:43], v[174:177], v[182:185], v[40:43]
	v_mfma_f32_16x16x32_bf16 v[28:31], v[166:169], v[190:193], v[28:31]
	v_mfma_f32_16x16x32_bf16 v[24:27], v[174:177], v[190:193], v[24:27]
	v_mfma_f32_16x16x32_bf16 v[12:15], v[166:169], v[198:201], v[12:15]
	v_mfma_f32_16x16x32_bf16 v[8:11], v[174:177], v[198:201], v[8:11]
	v_mfma_f32_16x16x32_bf16 v[4:7], v[166:169], v[206:209], v[4:7]
	v_mfma_f32_16x16x32_bf16 v[0:3], v[174:177], v[206:209], v[0:3]
	v_mfma_f32_16x16x32_bf16 v[44:47], v[170:173], v[186:189], v[44:47]
	v_mfma_f32_16x16x32_bf16 v[40:43], v[178:181], v[186:189], v[40:43]
	v_mfma_f32_16x16x32_bf16 v[28:31], v[170:173], v[194:197], v[28:31]
	v_mfma_f32_16x16x32_bf16 v[24:27], v[178:181], v[194:197], v[24:27]
	v_mfma_f32_16x16x32_bf16 v[12:15], v[170:173], v[202:205], v[12:15]
	v_mfma_f32_16x16x32_bf16 v[8:11], v[178:181], v[202:205], v[8:11]
	v_mfma_f32_16x16x32_bf16 v[4:7], v[170:173], v[210:213], v[4:7]
	v_mfma_f32_16x16x32_bf16 v[0:3], v[178:181], v[210:213], v[0:3]
	s_barrier
	s_add_i32 s68, 0, 0x18000
	s_add_i32 s69, 0, 0x1c000
	v_add_u32_e32 v162, s68, v146
	v_add_u32_e32 v178, s69, v146
	ds_read_b128 v[150:153], v162
	ds_read_b128 v[154:157], v162 offset:1024
	ds_read_b128 v[158:161], v162 offset:2048
	ds_read_b128 v[162:165], v162 offset:3072
	ds_read_b128 v[166:169], v178
	ds_read_b128 v[170:173], v178 offset:1024
	ds_read_b128 v[174:177], v178 offset:2048
	ds_read_b128 v[178:181], v178 offset:3072
	s_add_u32 s54, s54, 0xb0000
	s_addc_u32 s55, s55, 0
	s_mov_b32 m0, s61
	v_lshl_add_u64 v[222:223], s[54:55], 0, v[136:137]
	ds_read_b128 v[182:185], v149 offset:32768
	ds_read_b128 v[186:189], v149 offset:33792
	ds_read_b128 v[190:193], v149 offset:34816
	ds_read_b128 v[194:197], v149 offset:35840
	ds_read_b128 v[198:201], v149 offset:36864
	ds_read_b128 v[202:205], v149 offset:37888
	ds_read_b128 v[206:209], v149 offset:38912
	ds_read_b128 v[210:213], v149 offset:39936
	global_load_lds_dwordx4 v[222:223], off
	v_lshl_add_u64 v[222:223], s[54:55], 0, v[132:133]
	s_mov_b32 m0, s62
	s_nop 0
	global_load_lds_dwordx4 v[222:223], off
	s_waitcnt vmcnt(8)
	s_waitcnt lgkmcnt(0)
	s_barrier
	v_mfma_f32_16x16x32_bf16 v[124:127], v[150:153], v[182:185], v[124:127]
	v_mfma_f32_16x16x32_bf16 v[120:123], v[158:161], v[182:185], v[120:123]
	v_mfma_f32_16x16x32_bf16 v[116:119], v[150:153], v[190:193], v[116:119]
	v_mfma_f32_16x16x32_bf16 v[112:115], v[158:161], v[190:193], v[112:115]
	v_mfma_f32_16x16x32_bf16 v[100:103], v[150:153], v[198:201], v[100:103]
	v_mfma_f32_16x16x32_bf16 v[96:99], v[158:161], v[198:201], v[96:99]
	v_mfma_f32_16x16x32_bf16 v[84:87], v[150:153], v[206:209], v[84:87]
	v_mfma_f32_16x16x32_bf16 v[80:83], v[158:161], v[206:209], v[80:83]
	v_mfma_f32_16x16x32_bf16 v[124:127], v[154:157], v[186:189], v[124:127]
	v_mfma_f32_16x16x32_bf16 v[120:123], v[162:165], v[186:189], v[120:123]
	v_mfma_f32_16x16x32_bf16 v[116:119], v[154:157], v[194:197], v[116:119]
	v_mfma_f32_16x16x32_bf16 v[112:115], v[162:165], v[194:197], v[112:115]
	v_mfma_f32_16x16x32_bf16 v[100:103], v[154:157], v[202:205], v[100:103]
	v_mfma_f32_16x16x32_bf16 v[96:99], v[162:165], v[202:205], v[96:99]
	v_mfma_f32_16x16x32_bf16 v[84:87], v[154:157], v[210:213], v[84:87]
	v_mfma_f32_16x16x32_bf16 v[80:83], v[162:165], v[210:213], v[80:83]
	v_mfma_f32_16x16x32_bf16 v[108:111], v[166:169], v[182:185], v[108:111]
	v_mfma_f32_16x16x32_bf16 v[104:107], v[174:177], v[182:185], v[104:107]
	v_mfma_f32_16x16x32_bf16 v[92:95], v[166:169], v[190:193], v[92:95]
	v_mfma_f32_16x16x32_bf16 v[88:91], v[174:177], v[190:193], v[88:91]
	v_mfma_f32_16x16x32_bf16 v[76:79], v[166:169], v[198:201], v[76:79]
	v_mfma_f32_16x16x32_bf16 v[72:75], v[174:177], v[198:201], v[72:75]
	v_mfma_f32_16x16x32_bf16 v[68:71], v[166:169], v[206:209], v[68:71]
	v_mfma_f32_16x16x32_bf16 v[64:67], v[174:177], v[206:209], v[64:67]
	v_mfma_f32_16x16x32_bf16 v[108:111], v[170:173], v[186:189], v[108:111]
	v_mfma_f32_16x16x32_bf16 v[104:107], v[178:181], v[186:189], v[104:107]
	v_mfma_f32_16x16x32_bf16 v[92:95], v[170:173], v[194:197], v[92:95]
	v_mfma_f32_16x16x32_bf16 v[88:91], v[178:181], v[194:197], v[88:91]
	v_mfma_f32_16x16x32_bf16 v[76:79], v[170:173], v[202:205], v[76:79]
	v_mfma_f32_16x16x32_bf16 v[72:75], v[178:181], v[202:205], v[72:75]
	v_mfma_f32_16x16x32_bf16 v[68:71], v[170:173], v[210:213], v[68:71]
	v_mfma_f32_16x16x32_bf16 v[64:67], v[178:181], v[210:213], v[64:67]
	s_barrier
; #define PG8_STAGE(bufoff, gbase, voff) do { _Pragma("unroll") for (int _i = 0; _i < 2; ++_i) \
;         __builtin_amdgcn_global_load_lds((const unsigned*)((const char*)(gbase) + (voff)[_i]), (LAS unsigned*)(lds + (bufoff) + ldsw + _i * 8192), 16, 0, 0); } while (0)
; #define PG8_LDA(dst, b, h) do { _Pragma("unroll") for (int m = 0; m < 4; ++m) _Pragma("unroll") for (int k = 0; k < 2; ++k) dst[m][k] = *(const LAS bf16x8*)(lds + PG8_SA(b, h) + aoff + m * 2048 + k * 1024); } while (0)
; #define PG8_LDB(dst, b, h) do { _Pragma("unroll") for (int n = 0; n < 2; ++n) _Pragma("unroll") for (int k = 0; k < 2; ++k) dst[n][k] = *(const LAS bf16x8*)(lds + PG8_SB(b, h) + boff + n * 2048 + k * 1024); } while (0)
; #define PG8_WAIT_V(n) asm volatile("s_waitcnt vmcnt(" #n ")" ::: "memory")
; template <class Epi, bool SP2 = false>
; __device__ __forceinline__ void gemm_phase(LAS unsigned char* lds, const Gemm g, const StaticOrder& S, const Epi& E) {
;     ...
;         for (int t = 0; t < nt; t += 2) {
;             const bool last = (t == nt - 2);
;             const char* a1 = cA + (size_t)(t + 1) * kstep;
;             const char* a2 = last ? nA : cA + (size_t)(t + 2) * kstep; const char* b2 = last ? nB : cB + (size_t)(t + 2) * kstep;
;             const char* a3 = a2 + kstep; const char* b3 = b2 + kstep;
;             if constexpr (SP2) {
;             PG8_LDB(B0, 0, 0); PG8_LDB(B1, 0, 1); PG8_SCHED; PG8_LDA(At, 0, 0); PG8_STAGE(PG8_SA(1, 1), a1 + hstepA, voffA);
;             PG8_WAIT_V(8); PG8_WAIT_L(0); PG8_BAR; PG8_MMA(0, 0, At, B0); PG8_MMA(0, 1, At, B1); PG8_BAR; PG8_SCHED;
;             PG8_LDA(At, 0, 1); PG8_STAGE(PG8_SB(0, 0), b2, voffB); PG8_STAGE(PG8_SB(0, 1), b2 + hstepB, voffB); PG8_STAGE(PG8_SA(0, 0), a2, voffA);
;             PG8_WAIT_V(8); PG8_WAIT_L(0); PG8_BAR; PG8_MMA(1, 0, At, B0); PG8_MMA(1, 1, At, B1); PG8_BAR; PG8_SCHED;
;             PG8_LDB(B0, 1, 0); PG8_LDB(B1, 1, 1); PG8_SCHED; PG8_LDA(At, 1, 0); PG8_STAGE(PG8_SA(0, 1), a2 + hstepA, voffA);
;             PG8_WAIT_V(8); PG8_WAIT_L(0); PG8_BAR; PG8_MMA(0, 0, At, B0); PG8_MMA(0, 1, At, B1); PG8_BAR; PG8_SCHED;
;             PG8_LDA(At, 1, 1); PG8_STAGE(PG8_SB(1, 0), b3, voffB); PG8_STAGE(PG8_SB(1, 1), b3 + hstepB, voffB); PG8_STAGE(PG8_SA(1, 0), a3, voffA);
;             PG8_WAIT_V(8); PG8_WAIT_L(0); PG8_BAR; PG8_MMA(1, 0, At, B0); PG8_MMA(1, 1, At, B1); PG8_BAR; PG8_SCHED;
	s_add_i32 s54, s68, s56
	v_lshl_add_u64 v[214:215], v[214:215], 0, s[24:25]
	s_mov_b32 m0, s54
	ds_read_b128 v[182:185], v149 offset:49152
	ds_read_b128 v[186:189], v149 offset:50176
	ds_read_b128 v[190:193], v149 offset:51200
	ds_read_b128 v[194:197], v149 offset:52224
	ds_read_b128 v[198:201], v149 offset:53248
	ds_read_b128 v[202:205], v149 offset:54272
	ds_read_b128 v[206:209], v149 offset:55296
	ds_read_b128 v[210:213], v149 offset:56320
	global_load_lds_dwordx4 v[214:215], off
	s_add_i32 m0, s54, 0x2000
	s_add_u32 s52, s52, 0xb0080
	v_lshl_add_u64 v[214:215], v[216:217], 0, s[24:25]
	s_addc_u32 s53, s53, 0
	s_add_i32 s54, s69, s56
	global_load_lds_dwordx4 v[214:215], off
	v_lshl_add_u64 v[214:215], s[52:53], 0, v[134:135]
	s_mov_b32 m0, s54
	s_nop 0
	global_load_lds_dwordx4 v[214:215], off
	v_lshl_add_u64 v[214:215], s[52:53], 0, v[130:131]
	s_add_i32 m0, s54, 0x2000
	s_nop 0
	global_load_lds_dwordx4 v[214:215], off
	v_lshl_add_u64 v[214:215], v[218:219], 0, s[24:25]
	s_mov_b32 m0, s66
	s_nop 0
	global_load_lds_dwordx4 v[214:215], off
	v_lshl_add_u64 v[214:215], v[220:221], 0, s[24:25]
	s_mov_b32 m0, s67
	s_nop 0
	global_load_lds_dwordx4 v[214:215], off
	s_waitcnt vmcnt(8)
	s_waitcnt lgkmcnt(0)
	s_barrier
	v_mfma_f32_16x16x32_bf16 v[60:63], v[150:153], v[182:185], v[60:63]
	v_mfma_f32_16x16x32_bf16 v[56:59], v[158:161], v[182:185], v[56:59]
	v_mfma_f32_16x16x32_bf16 v[52:55], v[150:153], v[190:193], v[52:55]
	v_mfma_f32_16x16x32_bf16 v[48:51], v[158:161], v[190:193], v[48:51]
	v_mfma_f32_16x16x32_bf16 v[36:39], v[150:153], v[198:201], v[36:39]
	v_mfma_f32_16x16x32_bf16 v[32:35], v[158:161], v[198:201], v[32:35]
	v_mfma_f32_16x16x32_bf16 v[20:23], v[150:153], v[206:209], v[20:23]
	v_mfma_f32_16x16x32_bf16 v[16:19], v[158:161], v[206:209], v[16:19]
	v_mfma_f32_16x16x32_bf16 v[60:63], v[154:157], v[186:189], v[60:63]
	v_mfma_f32_16x16x32_bf16 v[56:59], v[162:165], v[186:189], v[56:59]
	v_mfma_f32_16x16x32_bf16 v[52:55], v[154:157], v[194:197], v[52:55]
	v_mfma_f32_16x16x32_bf16 v[48:51], v[162:165], v[194:197], v[48:51]
	v_mfma_f32_16x16x32_bf16 v[36:39], v[154:157], v[202:205], v[36:39]
	v_mfma_f32_16x16x32_bf16 v[32:35], v[162:165], v[202:205], v[32:35]
	v_mfma_f32_16x16x32_bf16 v[20:23], v[154:157], v[210:213], v[20:23]
	v_mfma_f32_16x16x32_bf16 v[16:19], v[162:165], v[210:213], v[16:19]
	v_mfma_f32_16x16x32_bf16 v[44:47], v[166:169], v[182:185], v[44:47]
	v_mfma_f32_16x16x32_bf16 v[40:43], v[174:177], v[182:185], v[40:43]
	v_mfma_f32_16x16x32_bf16 v[28:31], v[166:169], v[190:193], v[28:31]
	v_mfma_f32_16x16x32_bf16 v[24:27], v[174:177], v[190:193], v[24:27]
	v_mfma_f32_16x16x32_bf16 v[12:15], v[166:169], v[198:201], v[12:15]
	v_mfma_f32_16x16x32_bf16 v[8:11], v[174:177], v[198:201], v[8:11]
	v_mfma_f32_16x16x32_bf16 v[4:7], v[166:169], v[206:209], v[4:7]
	v_mfma_f32_16x16x32_bf16 v[0:3], v[174:177], v[206:209], v[0:3]
	v_mfma_f32_16x16x32_bf16 v[44:47], v[170:173], v[186:189], v[44:47]
	v_mfma_f32_16x16x32_bf16 v[40:43], v[178:181], v[186:189], v[40:43]
	v_mfma_f32_16x16x32_bf16 v[28:31], v[170:173], v[194:197], v[28:31]
	v_mfma_f32_16x16x32_bf16 v[24:27], v[178:181], v[194:197], v[24:27]
	v_mfma_f32_16x16x32_bf16 v[12:15], v[170:173], v[202:205], v[12:15]
	v_mfma_f32_16x16x32_bf16 v[8:11], v[178:181], v[202:205], v[8:11]
	v_mfma_f32_16x16x32_bf16 v[4:7], v[170:173], v[210:213], v[4:7]
	v_mfma_f32_16x16x32_bf16 v[0:3], v[178:181], v[210:213], v[0:3]
	s_barrier
	s_add_i32 s86, s86, 2
	s_add_u32 s34, s34, 0x100
	s_addc_u32 s35, s35, 0
	s_add_u32 s84, s84, 0x100
	s_addc_u32 s85, s85, 0
	s_cmp_gt_u32 s86, 41
	s_cbranch_scc0 .LBB0_334
	s_and_b64 vcc, exec, s[26:27]
	s_cbranch_vccz .LBB0_337
	s_barrier

; #define PG8_STAGE(bufoff, gbase, voff) do { _Pragma("unroll") for (int _i = 0; _i < 2; ++_i) \
;         __builtin_amdgcn_global_load_lds((const unsigned*)((const char*)(gbase) + (voff)[_i]), (LAS unsigned*)(lds + (bufoff) + ldsw + _i * 8192), 16, 0, 0); } while (0)
; #define PG8_LDA(dst, b, h) do { _Pragma("unroll") for (int m = 0; m < 4; ++m) _Pragma("unroll") for (int k = 0; k < 2; ++k) dst[m][k] = *(const LAS bf16x8*)(lds + PG8_SA(b, h) + aoff + m * 2048 + k * 1024); } while (0)
; #define PG8_LDB(dst, b, h) do { _Pragma("unroll") for (int n = 0; n < 2; ++n) _Pragma("unroll") for (int k = 0; k < 2; ++k) dst[n][k] = *(const LAS bf16x8*)(lds + PG8_SB(b, h) + boff + n * 2048 + k * 1024); } while (0)
; #define PG8_MMA(ai, bj, At, Bt) do { __builtin_amdgcn_s_setprio(1); _Pragma("unroll") for (int m = 0; m < 4; ++m) _Pragma("unroll") for (int n = 0; n < 2; ++n) _Pragma("unroll") for (int k = 0; k < 2; ++k) \
;         acc[ai][bj][m][n] = __builtin_amdgcn_mfma_f32_16x16x32_bf16(Bt[n][k], At[m][k], acc[ai][bj][m][n], 0, 0, 0); __builtin_amdgcn_s_setprio(0); } while (0)
; #define PG8_WAIT_V(n) asm volatile("s_waitcnt vmcnt(" #n ")" ::: "memory")
; #define PG8_WAIT_L(n) asm volatile("s_waitcnt lgkmcnt(" #n ")" ::: "memory")
; #define PG8_BAR __builtin_amdgcn_s_barrier()
; template <class Epi, bool SP2 = false>
; __device__ __forceinline__ void gemm_phase(LAS unsigned char* lds, const Gemm g, const StaticOrder& S, const Epi& E) {
;     ...
;         for (int t = 0; t < nt; t += 2) {
;             const bool last = (t == nt - 2);
;             const char* a1 = cA + (size_t)(t + 1) * kstep;
;             const char* a2 = last ? nA : cA + (size_t)(t + 2) * kstep; const char* b2 = last ? nB : cB + (size_t)(t + 2) * kstep;
;             const char* a3 = a2 + kstep; const char* b3 = b2 + kstep;
;             if constexpr (SP2) {
;             PG8_LDB(B0, 0, 0); PG8_LDB(B1, 0, 1); PG8_SCHED; PG8_LDA(At, 0, 0); PG8_STAGE(PG8_SA(1, 1), a1 + hstepA, voffA);
;             PG8_WAIT_V(8); PG8_WAIT_L(0); PG8_BAR; PG8_MMA(0, 0, At, B0); PG8_MMA(0, 1, At, B1); PG8_BAR; PG8_SCHED;
;             PG8_LDA(At, 0, 1); PG8_STAGE(PG8_SB(0, 0), b2, voffB); PG8_STAGE(PG8_SB(0, 1), b2 + hstepB, voffB); PG8_STAGE(PG8_SA(0, 0), a2, voffA);
;             PG8_WAIT_V(8); PG8_WAIT_L(0); PG8_BAR; PG8_MMA(1, 0, At, B0); PG8_MMA(1, 1, At, B1); PG8_BAR; PG8_SCHED;
.LBB0_462:
	ds_read_b128 v[146:149], v153
	ds_read_b128 v[156:159], v153 offset:1024
	ds_read_b128 v[160:163], v153 offset:2048
	ds_read_b128 v[164:167], v153 offset:3072
	ds_read_b128 v[168:171], v154
	ds_read_b128 v[172:175], v154 offset:1024
	ds_read_b128 v[176:179], v154 offset:2048
	ds_read_b128 v[180:183], v154 offset:3072
	s_add_u32 s44, s34, 0xfffc0080
	s_addc_u32 s45, s35, -1
	s_cmp_eq_u32 s74, 12
	s_cselect_b32 s51, s5, s45
	s_cselect_b32 s50, s27, s44
	s_cselect_b32 s45, s25, s73
	s_cselect_b32 s44, s33, s72
	v_lshl_add_u64 v[150:151], s[34:35], 0, v[138:139]
	s_add_i32 m0, s31, 0xc000
	ds_read_b128 v[184:187], v155
	ds_read_b128 v[188:191], v155 offset:1024
	ds_read_b128 v[192:195], v155 offset:2048
	ds_read_b128 v[196:199], v155 offset:3072
	ds_read_b128 v[200:203], v155 offset:4096
	ds_read_b128 v[204:207], v155 offset:5120
	ds_read_b128 v[208:211], v155 offset:6144
	ds_read_b128 v[212:215], v155 offset:7168
	global_load_lds_dwordx4 v[150:151], off
	v_lshl_add_u64 v[150:151], s[34:35], 0, v[140:141]
	s_add_i32 m0, s31, 0xe000
	s_nop 0
	global_load_lds_dwordx4 v[150:151], off
	s_waitcnt vmcnt(8)
	s_waitcnt lgkmcnt(0)
	s_barrier
	v_mfma_f32_16x16x32_bf16 v[124:127], v[146:149], v[184:187], v[124:127]
	v_mfma_f32_16x16x32_bf16 v[120:123], v[160:163], v[184:187], v[120:123]
	v_mfma_f32_16x16x32_bf16 v[108:111], v[146:149], v[192:195], v[108:111]
	v_mfma_f32_16x16x32_bf16 v[104:107], v[160:163], v[192:195], v[104:107]
	v_mfma_f32_16x16x32_bf16 v[92:95], v[146:149], v[200:203], v[92:95]
	v_mfma_f32_16x16x32_bf16 v[88:91], v[160:163], v[200:203], v[88:91]
	v_mfma_f32_16x16x32_bf16 v[76:79], v[146:149], v[208:211], v[76:79]
	v_mfma_f32_16x16x32_bf16 v[72:75], v[160:163], v[208:211], v[72:75]
	v_mfma_f32_16x16x32_bf16 v[124:127], v[156:159], v[188:191], v[124:127]
	v_mfma_f32_16x16x32_bf16 v[120:123], v[164:167], v[188:191], v[120:123]
	v_mfma_f32_16x16x32_bf16 v[108:111], v[156:159], v[196:199], v[108:111]
	v_mfma_f32_16x16x32_bf16 v[104:107], v[164:167], v[196:199], v[104:107]
	v_mfma_f32_16x16x32_bf16 v[92:95], v[156:159], v[204:207], v[92:95]
	v_mfma_f32_16x16x32_bf16 v[88:91], v[164:167], v[204:207], v[88:91]
	v_mfma_f32_16x16x32_bf16 v[76:79], v[156:159], v[212:215], v[76:79]
	v_mfma_f32_16x16x32_bf16 v[72:75], v[164:167], v[212:215], v[72:75]
	v_mfma_f32_16x16x32_bf16 v[116:119], v[168:171], v[184:187], v[116:119]
	v_mfma_f32_16x16x32_bf16 v[112:115], v[176:179], v[184:187], v[112:115]
	v_mfma_f32_16x16x32_bf16 v[100:103], v[168:171], v[192:195], v[100:103]
	v_mfma_f32_16x16x32_bf16 v[96:99], v[176:179], v[192:195], v[96:99]
	v_mfma_f32_16x16x32_bf16 v[84:87], v[168:171], v[200:203], v[84:87]
	v_mfma_f32_16x16x32_bf16 v[80:83], v[176:179], v[200:203], v[80:83]
	v_mfma_f32_16x16x32_bf16 v[68:71], v[168:171], v[208:211], v[68:71]
	v_mfma_f32_16x16x32_bf16 v[64:67], v[176:179], v[208:211], v[64:67]
	v_mfma_f32_16x16x32_bf16 v[116:119], v[172:175], v[188:191], v[116:119]
	v_mfma_f32_16x16x32_bf16 v[112:115], v[180:183], v[188:191], v[112:115]
	v_mfma_f32_16x16x32_bf16 v[100:103], v[172:175], v[196:199], v[100:103]
	v_mfma_f32_16x16x32_bf16 v[96:99], v[180:183], v[196:199], v[96:99]
	v_mfma_f32_16x16x32_bf16 v[84:87], v[172:175], v[204:207], v[84:87]
	v_mfma_f32_16x16x32_bf16 v[80:83], v[180:183], v[204:207], v[80:83]
	v_mfma_f32_16x16x32_bf16 v[68:71], v[172:175], v[212:215], v[68:71]
	v_mfma_f32_16x16x32_bf16 v[64:67], v[180:183], v[212:215], v[64:67]
	s_barrier
	s_add_i32 s68, s66, s53
	v_lshl_add_u64 v[150:151], s[44:45], 0, v[132:133]
	s_mov_b32 m0, s68
	ds_read_b128 v[184:187], v155 offset:16384
	ds_read_b128 v[188:191], v155 offset:17408
	ds_read_b128 v[192:195], v155 offset:18432
	ds_read_b128 v[196:199], v155 offset:19456
	ds_read_b128 v[200:203], v155 offset:20480
	ds_read_b128 v[204:207], v155 offset:21504
	ds_read_b128 v[208:211], v155 offset:22528
	ds_read_b128 v[212:215], v155 offset:23552
	global_load_lds_dwordx4 v[150:151], off
	s_add_i32 m0, s68, 0x2000
	s_add_u32 s68, s44, 0x40000
	v_lshl_add_u64 v[216:217], s[44:45], 0, v[136:137]
	s_addc_u32 s69, s45, 0
	s_add_i32 s70, s67, s53
	global_load_lds_dwordx4 v[216:217], off
	v_lshl_add_u64 v[218:219], s[68:69], 0, v[132:133]
	s_mov_b32 m0, s70
	v_lshl_add_u64 v[220:221], s[50:51], 0, v[134:135]
	global_load_lds_dwordx4 v[218:219], off
	v_lshl_add_u64 v[218:219], s[68:69], 0, v[136:137]
	s_add_i32 m0, s70, 0x2000
	s_nop 0
	global_load_lds_dwordx4 v[218:219], off
	v_lshl_add_u64 v[218:219], s[50:51], 0, v[130:131]
	s_mov_b32 m0, s31
	s_nop 0
	global_load_lds_dwordx4 v[218:219], off
	s_mov_b32 m0, s54
	s_nop 0
	global_load_lds_dwordx4 v[220:221], off
	s_waitcnt vmcnt(8)
	s_waitcnt lgkmcnt(0)
	s_barrier
; #define PG8_STAGE(bufoff, gbase, voff) do { _Pragma("unroll") for (int _i = 0; _i < 2; ++_i) \
;         __builtin_amdgcn_global_load_lds((const unsigned*)((const char*)(gbase) + (voff)[_i]), (LAS unsigned*)(lds + (bufoff) + ldsw + _i * 8192), 16, 0, 0); } while (0)
; #define PG8_LDA(dst, b, h) do { _Pragma("unroll") for (int m = 0; m < 4; ++m) _Pragma("unroll") for (int k = 0; k < 2; ++k) dst[m][k] = *(const LAS bf16x8*)(lds + PG8_SA(b, h) + aoff + m * 2048 + k * 1024); } while (0)
; #define PG8_LDB(dst, b, h) do { _Pragma("unroll") for (int n = 0; n < 2; ++n) _Pragma("unroll") for (int k = 0; k < 2; ++k) dst[n][k] = *(const LAS bf16x8*)(lds + PG8_SB(b, h) + boff + n * 2048 + k * 1024); } while (0)
; #define PG8_MMA(ai, bj, At, Bt) do { __builtin_amdgcn_s_setprio(1); _Pragma("unroll") for (int m = 0; m < 4; ++m) _Pragma("unroll") for (int n = 0; n < 2; ++n) _Pragma("unroll") for (int k = 0; k < 2; ++k) \
;         acc[ai][bj][m][n] = __builtin_amdgcn_mfma_f32_16x16x32_bf16(Bt[n][k], At[m][k], acc[ai][bj][m][n], 0, 0, 0); __builtin_amdgcn_s_setprio(0); } while (0)
; #define PG8_WAIT_V(n) asm volatile("s_waitcnt vmcnt(" #n ")" ::: "memory")
; #define PG8_WAIT_L(n) asm volatile("s_waitcnt lgkmcnt(" #n ")" ::: "memory")
; #define PG8_BAR __builtin_amdgcn_s_barrier()
; #define PG8_SCHED __builtin_amdgcn_sched_barrier(0)
; template <class Epi, bool SP2 = false>
; __device__ __forceinline__ void gemm_phase(LAS unsigned char* lds, const Gemm g, const StaticOrder& S, const Epi& E) {
;     ...
;             PG8_WAIT_V(8); PG8_WAIT_L(0); PG8_BAR; PG8_MMA(1, 0, At, B0); PG8_MMA(1, 1, At, B1); PG8_BAR; PG8_SCHED;
;             PG8_LDB(B0, 1, 0); PG8_LDB(B1, 1, 1); PG8_SCHED; PG8_LDA(At, 1, 0); PG8_STAGE(PG8_SA(0, 1), a2 + hstepA, voffA);
;             PG8_WAIT_V(8); PG8_WAIT_L(0); PG8_BAR; PG8_MMA(0, 0, At, B0); PG8_MMA(0, 1, At, B1); PG8_BAR; PG8_SCHED;
	v_mfma_f32_16x16x32_bf16 v[60:63], v[146:149], v[184:187], v[60:63]
	v_mfma_f32_16x16x32_bf16 v[56:59], v[160:163], v[184:187], v[56:59]
	v_mfma_f32_16x16x32_bf16 v[44:47], v[146:149], v[192:195], v[44:47]
	v_mfma_f32_16x16x32_bf16 v[40:43], v[160:163], v[192:195], v[40:43]
	v_mfma_f32_16x16x32_bf16 v[28:31], v[146:149], v[200:203], v[28:31]
	v_mfma_f32_16x16x32_bf16 v[24:27], v[160:163], v[200:203], v[24:27]
	v_mfma_f32_16x16x32_bf16 v[12:15], v[146:149], v[208:211], v[12:15]
	v_mfma_f32_16x16x32_bf16 v[8:11], v[160:163], v[208:211], v[8:11]
	v_mfma_f32_16x16x32_bf16 v[60:63], v[156:159], v[188:191], v[60:63]
	v_mfma_f32_16x16x32_bf16 v[56:59], v[164:167], v[188:191], v[56:59]
	v_mfma_f32_16x16x32_bf16 v[44:47], v[156:159], v[196:199], v[44:47]
	v_mfma_f32_16x16x32_bf16 v[40:43], v[164:167], v[196:199], v[40:43]
	v_mfma_f32_16x16x32_bf16 v[28:31], v[156:159], v[204:207], v[28:31]
	v_mfma_f32_16x16x32_bf16 v[24:27], v[164:167], v[204:207], v[24:27]
	v_mfma_f32_16x16x32_bf16 v[12:15], v[156:159], v[212:215], v[12:15]
	v_mfma_f32_16x16x32_bf16 v[8:11], v[164:167], v[212:215], v[8:11]
	v_mfma_f32_16x16x32_bf16 v[52:55], v[168:171], v[184:187], v[52:55]
	v_mfma_f32_16x16x32_bf16 v[48:51], v[176:179], v[184:187], v[48:51]
	v_mfma_f32_16x16x32_bf16 v[36:39], v[168:171], v[192:195], v[36:39]
	v_mfma_f32_16x16x32_bf16 v[32:35], v[176:179], v[192:195], v[32:35]
	v_mfma_f32_16x16x32_bf16 v[20:23], v[168:171], v[200:203], v[20:23]
	v_mfma_f32_16x16x32_bf16 v[16:19], v[176:179], v[200:203], v[16:19]
	v_mfma_f32_16x16x32_bf16 v[4:7], v[168:171], v[208:211], v[4:7]
	v_mfma_f32_16x16x32_bf16 v[0:3], v[176:179], v[208:211], v[0:3]
	v_mfma_f32_16x16x32_bf16 v[52:55], v[172:175], v[188:191], v[52:55]
	v_mfma_f32_16x16x32_bf16 v[48:51], v[180:183], v[188:191], v[48:51]
	v_mfma_f32_16x16x32_bf16 v[36:39], v[172:175], v[196:199], v[36:39]
	v_mfma_f32_16x16x32_bf16 v[32:35], v[180:183], v[196:199], v[32:35]
	v_mfma_f32_16x16x32_bf16 v[20:23], v[172:175], v[204:207], v[20:23]
	v_mfma_f32_16x16x32_bf16 v[16:19], v[180:183], v[204:207], v[16:19]
	v_mfma_f32_16x16x32_bf16 v[4:7], v[172:175], v[212:215], v[4:7]
	v_mfma_f32_16x16x32_bf16 v[0:3], v[180:183], v[212:215], v[0:3]
	s_barrier
	s_add_i32 s68, 0, 0x18000
	s_add_i32 s69, 0, 0x1c000
	v_add_u32_e32 v164, s68, v152
	v_add_u32_e32 v180, s69, v152
	ds_read_b128 v[146:149], v164
	ds_read_b128 v[156:159], v164 offset:1024
	ds_read_b128 v[160:163], v164 offset:2048
	ds_read_b128 v[164:167], v164 offset:3072
	ds_read_b128 v[168:171], v180
	ds_read_b128 v[172:175], v180 offset:1024
	ds_read_b128 v[176:179], v180 offset:2048
	ds_read_b128 v[180:183], v180 offset:3072
	s_add_u32 s50, s50, 0x40000
	s_addc_u32 s51, s51, 0
	s_mov_b32 m0, s55
	v_lshl_add_u64 v[222:223], s[50:51], 0, v[130:131]
	ds_read_b128 v[184:187], v155 offset:32768
	ds_read_b128 v[188:191], v155 offset:33792
	ds_read_b128 v[192:195], v155 offset:34816
	ds_read_b128 v[196:199], v155 offset:35840
	ds_read_b128 v[200:203], v155 offset:36864
	ds_read_b128 v[204:207], v155 offset:37888
	ds_read_b128 v[208:211], v155 offset:38912
	ds_read_b128 v[212:215], v155 offset:39936
	global_load_lds_dwordx4 v[222:223], off
	v_lshl_add_u64 v[222:223], s[50:51], 0, v[134:135]
	s_mov_b32 m0, s56
	s_nop 0
	global_load_lds_dwordx4 v[222:223], off
	s_waitcnt vmcnt(8)
	s_waitcnt lgkmcnt(0)
	s_barrier
	v_mfma_f32_16x16x32_bf16 v[124:127], v[146:149], v[184:187], v[124:127]
	v_mfma_f32_16x16x32_bf16 v[120:123], v[160:163], v[184:187], v[120:123]
	v_mfma_f32_16x16x32_bf16 v[108:111], v[146:149], v[192:195], v[108:111]
	v_mfma_f32_16x16x32_bf16 v[104:107], v[160:163], v[192:195], v[104:107]
	v_mfma_f32_16x16x32_bf16 v[92:95], v[146:149], v[200:203], v[92:95]
	v_mfma_f32_16x16x32_bf16 v[88:91], v[160:163], v[200:203], v[88:91]
	v_mfma_f32_16x16x32_bf16 v[76:79], v[146:149], v[208:211], v[76:79]
	v_mfma_f32_16x16x32_bf16 v[72:75], v[160:163], v[208:211], v[72:75]
	v_mfma_f32_16x16x32_bf16 v[124:127], v[156:159], v[188:191], v[124:127]
	v_mfma_f32_16x16x32_bf16 v[120:123], v[164:167], v[188:191], v[120:123]
	v_mfma_f32_16x16x32_bf16 v[108:111], v[156:159], v[196:199], v[108:111]
	v_mfma_f32_16x16x32_bf16 v[104:107], v[164:167], v[196:199], v[104:107]
	v_mfma_f32_16x16x32_bf16 v[92:95], v[156:159], v[204:207], v[92:95]
	v_mfma_f32_16x16x32_bf16 v[88:91], v[164:167], v[204:207], v[88:91]
	v_mfma_f32_16x16x32_bf16 v[76:79], v[156:159], v[212:215], v[76:79]
	v_mfma_f32_16x16x32_bf16 v[72:75], v[164:167], v[212:215], v[72:75]
	v_mfma_f32_16x16x32_bf16 v[116:119], v[168:171], v[184:187], v[116:119]
	v_mfma_f32_16x16x32_bf16 v[112:115], v[176:179], v[184:187], v[112:115]
	v_mfma_f32_16x16x32_bf16 v[100:103], v[168:171], v[192:195], v[100:103]
	v_mfma_f32_16x16x32_bf16 v[96:99], v[176:179], v[192:195], v[96:99]
	v_mfma_f32_16x16x32_bf16 v[84:87], v[168:171], v[200:203], v[84:87]
	v_mfma_f32_16x16x32_bf16 v[80:83], v[176:179], v[200:203], v[80:83]
	v_mfma_f32_16x16x32_bf16 v[68:71], v[168:171], v[208:211], v[68:71]
	v_mfma_f32_16x16x32_bf16 v[64:67], v[176:179], v[208:211], v[64:67]
	v_mfma_f32_16x16x32_bf16 v[116:119], v[172:175], v[188:191], v[116:119]
	v_mfma_f32_16x16x32_bf16 v[112:115], v[180:183], v[188:191], v[112:115]
	v_mfma_f32_16x16x32_bf16 v[100:103], v[172:175], v[196:199], v[100:103]
	v_mfma_f32_16x16x32_bf16 v[96:99], v[180:183], v[196:199], v[96:99]
	v_mfma_f32_16x16x32_bf16 v[84:87], v[172:175], v[204:207], v[84:87]
	v_mfma_f32_16x16x32_bf16 v[80:83], v[180:183], v[204:207], v[80:83]
	v_mfma_f32_16x16x32_bf16 v[68:71], v[172:175], v[212:215], v[68:71]
	v_mfma_f32_16x16x32_bf16 v[64:67], v[180:183], v[212:215], v[64:67]
	s_barrier
; #define PG8_STAGE(bufoff, gbase, voff) do { _Pragma("unroll") for (int _i = 0; _i < 2; ++_i) \
;         __builtin_amdgcn_global_load_lds((const unsigned*)((const char*)(gbase) + (voff)[_i]), (LAS unsigned*)(lds + (bufoff) + ldsw + _i * 8192), 16, 0, 0); } while (0)
; #define PG8_LDA(dst, b, h) do { _Pragma("unroll") for (int m = 0; m < 4; ++m) _Pragma("unroll") for (int k = 0; k < 2; ++k) dst[m][k] = *(const LAS bf16x8*)(lds + PG8_SA(b, h) + aoff + m * 2048 + k * 1024); } while (0)
; #define PG8_LDB(dst, b, h) do { _Pragma("unroll") for (int n = 0; n < 2; ++n) _Pragma("unroll") for (int k = 0; k < 2; ++k) dst[n][k] = *(const LAS bf16x8*)(lds + PG8_SB(b, h) + boff + n * 2048 + k * 1024); } while (0)
; #define PG8_WAIT_V(n) asm volatile("s_waitcnt vmcnt(" #n ")" ::: "memory")
; template <class Epi, bool SP2 = false>
; __device__ __forceinline__ void gemm_phase(LAS unsigned char* lds, const Gemm g, const StaticOrder& S, const Epi& E) {
;     ...
;         for (int t = 0; t < nt; t += 2) {
;             const bool last = (t == nt - 2);
;             const char* a1 = cA + (size_t)(t + 1) * kstep;
;             const char* a2 = last ? nA : cA + (size_t)(t + 2) * kstep; const char* b2 = last ? nB : cB + (size_t)(t + 2) * kstep;
;             const char* a3 = a2 + kstep; const char* b3 = b2 + kstep;
;             if constexpr (SP2) {
;             PG8_LDB(B0, 0, 0); PG8_LDB(B1, 0, 1); PG8_SCHED; PG8_LDA(At, 0, 0); PG8_STAGE(PG8_SA(1, 1), a1 + hstepA, voffA);
;             PG8_WAIT_V(8); PG8_WAIT_L(0); PG8_BAR; PG8_MMA(0, 0, At, B0); PG8_MMA(0, 1, At, B1); PG8_BAR; PG8_SCHED;
;             PG8_LDA(At, 0, 1); PG8_STAGE(PG8_SB(0, 0), b2, voffB); PG8_STAGE(PG8_SB(0, 1), b2 + hstepB, voffB); PG8_STAGE(PG8_SA(0, 0), a2, voffA);
;             PG8_WAIT_V(8); PG8_WAIT_L(0); PG8_BAR; PG8_MMA(1, 0, At, B0); PG8_MMA(1, 1, At, B1); PG8_BAR; PG8_SCHED;
;             PG8_LDB(B0, 1, 0); PG8_LDB(B1, 1, 1); PG8_SCHED; PG8_LDA(At, 1, 0); PG8_STAGE(PG8_SA(0, 1), a2 + hstepA, voffA);
;             PG8_WAIT_V(8); PG8_WAIT_L(0); PG8_BAR; PG8_MMA(0, 0, At, B0); PG8_MMA(0, 1, At, B1); PG8_BAR; PG8_SCHED;
;             PG8_LDA(At, 1, 1); PG8_STAGE(PG8_SB(1, 0), b3, voffB); PG8_STAGE(PG8_SB(1, 1), b3 + hstepB, voffB); PG8_STAGE(PG8_SA(1, 0), a3, voffA);
;             PG8_WAIT_V(8); PG8_WAIT_L(0); PG8_BAR; PG8_MMA(1, 0, At, B0); PG8_MMA(1, 1, At, B1); PG8_BAR; PG8_SCHED;
	s_add_i32 s50, s68, s53
	v_lshl_add_u64 v[150:151], v[150:151], 0, s[10:11]
	s_mov_b32 m0, s50
	ds_read_b128 v[184:187], v155 offset:49152
	ds_read_b128 v[188:191], v155 offset:50176
	ds_read_b128 v[192:195], v155 offset:51200
	ds_read_b128 v[196:199], v155 offset:52224
	ds_read_b128 v[200:203], v155 offset:53248
	ds_read_b128 v[204:207], v155 offset:54272
	ds_read_b128 v[208:211], v155 offset:55296
	ds_read_b128 v[212:215], v155 offset:56320
	global_load_lds_dwordx4 v[150:151], off
	s_add_i32 m0, s50, 0x2000
	s_add_u32 s44, s44, 0x40080
	v_lshl_add_u64 v[150:151], v[216:217], 0, s[10:11]
	s_addc_u32 s45, s45, 0
	s_add_i32 s50, s69, s53
	global_load_lds_dwordx4 v[150:151], off
	v_lshl_add_u64 v[150:151], s[44:45], 0, v[132:133]
	s_mov_b32 m0, s50
	s_nop 0
	global_load_lds_dwordx4 v[150:151], off
	v_lshl_add_u64 v[150:151], s[44:45], 0, v[136:137]
	s_add_i32 m0, s50, 0x2000
	s_nop 0
	global_load_lds_dwordx4 v[150:151], off
	v_lshl_add_u64 v[150:151], v[218:219], 0, s[10:11]
	s_mov_b32 m0, s60
	s_nop 0
	global_load_lds_dwordx4 v[150:151], off
	v_lshl_add_u64 v[150:151], v[220:221], 0, s[10:11]
	s_mov_b32 m0, s61
	s_nop 0
	global_load_lds_dwordx4 v[150:151], off
	s_waitcnt vmcnt(8)
	s_waitcnt lgkmcnt(0)
	s_barrier
	v_mfma_f32_16x16x32_bf16 v[60:63], v[146:149], v[184:187], v[60:63]
	v_mfma_f32_16x16x32_bf16 v[56:59], v[160:163], v[184:187], v[56:59]
	v_mfma_f32_16x16x32_bf16 v[44:47], v[146:149], v[192:195], v[44:47]
	v_mfma_f32_16x16x32_bf16 v[40:43], v[160:163], v[192:195], v[40:43]
	v_mfma_f32_16x16x32_bf16 v[28:31], v[146:149], v[200:203], v[28:31]
	v_mfma_f32_16x16x32_bf16 v[24:27], v[160:163], v[200:203], v[24:27]
	v_mfma_f32_16x16x32_bf16 v[12:15], v[146:149], v[208:211], v[12:15]
	v_mfma_f32_16x16x32_bf16 v[8:11], v[160:163], v[208:211], v[8:11]
	v_mfma_f32_16x16x32_bf16 v[60:63], v[156:159], v[188:191], v[60:63]
	v_mfma_f32_16x16x32_bf16 v[56:59], v[164:167], v[188:191], v[56:59]
	v_mfma_f32_16x16x32_bf16 v[44:47], v[156:159], v[196:199], v[44:47]
	v_mfma_f32_16x16x32_bf16 v[40:43], v[164:167], v[196:199], v[40:43]
	v_mfma_f32_16x16x32_bf16 v[28:31], v[156:159], v[204:207], v[28:31]
	v_mfma_f32_16x16x32_bf16 v[24:27], v[164:167], v[204:207], v[24:27]
	v_mfma_f32_16x16x32_bf16 v[12:15], v[156:159], v[212:215], v[12:15]
	v_mfma_f32_16x16x32_bf16 v[8:11], v[164:167], v[212:215], v[8:11]
	v_mfma_f32_16x16x32_bf16 v[52:55], v[168:171], v[184:187], v[52:55]
	v_mfma_f32_16x16x32_bf16 v[48:51], v[176:179], v[184:187], v[48:51]
	v_mfma_f32_16x16x32_bf16 v[36:39], v[168:171], v[192:195], v[36:39]
	v_mfma_f32_16x16x32_bf16 v[32:35], v[176:179], v[192:195], v[32:35]
	v_mfma_f32_16x16x32_bf16 v[20:23], v[168:171], v[200:203], v[20:23]
	v_mfma_f32_16x16x32_bf16 v[16:19], v[176:179], v[200:203], v[16:19]
	v_mfma_f32_16x16x32_bf16 v[4:7], v[168:171], v[208:211], v[4:7]
	v_mfma_f32_16x16x32_bf16 v[0:3], v[176:179], v[208:211], v[0:3]
	v_mfma_f32_16x16x32_bf16 v[52:55], v[172:175], v[188:191], v[52:55]
	v_mfma_f32_16x16x32_bf16 v[48:51], v[180:183], v[188:191], v[48:51]
	v_mfma_f32_16x16x32_bf16 v[36:39], v[172:175], v[196:199], v[36:39]
	v_mfma_f32_16x16x32_bf16 v[32:35], v[180:183], v[196:199], v[32:35]
	v_mfma_f32_16x16x32_bf16 v[20:23], v[172:175], v[204:207], v[20:23]
	v_mfma_f32_16x16x32_bf16 v[16:19], v[180:183], v[204:207], v[16:19]
	v_mfma_f32_16x16x32_bf16 v[4:7], v[172:175], v[212:215], v[4:7]
	v_mfma_f32_16x16x32_bf16 v[0:3], v[180:183], v[212:215], v[0:3]
	s_barrier
	s_add_i32 s74, s74, 2
	s_add_u32 s34, s34, 0x100
	s_addc_u32 s35, s35, 0
	s_add_u32 s72, s72, 0x100
	s_addc_u32 s73, s73, 0
	s_cmp_gt_u32 s74, 13
	s_cbranch_scc0 .LBB0_462
	s_and_b64 vcc, exec, s[12:13]
	s_cbranch_vccz .LBB0_465
	s_barrier

; #define PG8_STAGE(bufoff, gbase, voff) do { _Pragma("unroll") for (int _i = 0; _i < 2; ++_i) \
;         __builtin_amdgcn_global_load_lds((const unsigned*)((const char*)(gbase) + (voff)[_i]), (LAS unsigned*)(lds + (bufoff) + ldsw + _i * 8192), 16, 0, 0); } while (0)
; #define PG8_LDA(dst, b, h) do { _Pragma("unroll") for (int m = 0; m < 4; ++m) _Pragma("unroll") for (int k = 0; k < 2; ++k) dst[m][k] = *(const LAS bf16x8*)(lds + PG8_SA(b, h) + aoff + m * 2048 + k * 1024); } while (0)
; #define PG8_LDB(dst, b, h) do { _Pragma("unroll") for (int n = 0; n < 2; ++n) _Pragma("unroll") for (int k = 0; k < 2; ++k) dst[n][k] = *(const LAS bf16x8*)(lds + PG8_SB(b, h) + boff + n * 2048 + k * 1024); } while (0)
; #define PG8_MMA(ai, bj, At, Bt) do { __builtin_amdgcn_s_setprio(1); _Pragma("unroll") for (int m = 0; m < 4; ++m) _Pragma("unroll") for (int n = 0; n < 2; ++n) _Pragma("unroll") for (int k = 0; k < 2; ++k) \
;         acc[ai][bj][m][n] = __builtin_amdgcn_mfma_f32_16x16x32_bf16(Bt[n][k], At[m][k], acc[ai][bj][m][n], 0, 0, 0); __builtin_amdgcn_s_setprio(0); } while (0)
; #define PG8_WAIT_L(n) asm volatile("s_waitcnt lgkmcnt(" #n ")" ::: "memory")
; #define PG8_BAR __builtin_amdgcn_s_barrier()
; #define PG8_SCHED __builtin_amdgcn_sched_barrier(0)
; template <class Epi, bool SP2 = false>
; __device__ __forceinline__ void gemm_phase(LAS unsigned char* lds, const Gemm g, const StaticOrder& S, const Epi& E) {
;     ...
;             PG8_LDB(B0, 0, 0); PG8_SCHED; PG8_LDA(At, 0, 0); PG8_STAGE(PG8_SA(1, 1), a1 + hstepA, voffA);
;             PG8_WAIT_L(8); PG8_BAR; PG8_WAIT_L(0); PG8_MMA(0, 0, At, B0); PG8_BAR; PG8_SCHED;
;             PG8_LDB(B1, 0, 1); PG8_STAGE(PG8_SB(0, 0), b2, voffB);
;             PG8_BAR; PG8_WAIT_L(0); PG8_MMA(0, 1, At, B1); PG8_BAR;
;             PG8_LDA(At, 0, 1); PG8_STAGE(PG8_SA(0, 0), a2, voffA);
;             PG8_BAR; PG8_WAIT_L(0); PG8_MMA(1, 0, At, B0); PG8_BAR; PG8_SCHED;
.LBB0_664:
	ds_read_b128 v[24:27], v22
	ds_read_b128 v[28:31], v22 offset:1024
	ds_read_b128 v[32:35], v22 offset:2048
	ds_read_b128 v[36:39], v22 offset:3072
	s_ashr_i32 s39, s38, 31
	s_lshl_b64 s[42:43], s[38:39], 18
	s_add_u32 s42, s16, s42
	s_addc_u32 s43, s17, s43
	s_and_b64 s[4:5], s[4:5], exec
	s_cselect_b32 s5, s43, s45
	s_cselect_b32 s4, s42, s44
	s_add_u32 s66, s44, 0x20080
	s_addc_u32 s67, s45, 0
	s_add_i32 s72, s35, 0xc000
	v_lshl_add_u64 v[12:13], s[66:67], 0, v[6:7]
	s_mov_b32 m0, s72
	s_add_i32 s39, s35, 0xe000
	ds_read_b128 v[16:19], v21
	ds_read_b128 v[40:43], v21 offset:1024
	ds_read_b128 v[44:47], v21 offset:2048
	ds_read_b128 v[48:51], v21 offset:3072
	ds_read_b128 v[52:55], v21 offset:4096
	ds_read_b128 v[56:59], v21 offset:5120
	ds_read_b128 v[60:63], v21 offset:6144
	ds_read_b128 v[64:67], v21 offset:7168
	global_load_lds_dwordx4 v[12:13], off
	v_lshl_add_u64 v[12:13], s[66:67], 0, v[2:3]
	s_mov_b32 m0, s39
	s_nop 0
	global_load_lds_dwordx4 v[12:13], off
	s_waitcnt lgkmcnt(8)
	s_barrier
	s_waitcnt lgkmcnt(0)
	s_waitcnt lgkmcnt(0)
	v_mfma_f32_16x16x32_bf16 v[12:15], v[24:27], v[16:19], 0
	v_mfma_f32_16x16x32_bf16 v[68:71], v[28:31], v[40:43], v[12:15]
	v_mfma_f32_16x16x32_bf16 v[12:15], v[32:35], v[16:19], 0
	v_mfma_f32_16x16x32_bf16 v[72:75], v[36:39], v[40:43], v[12:15]
	v_mfma_f32_16x16x32_bf16 v[12:15], v[24:27], v[44:47], 0
	v_mfma_f32_16x16x32_bf16 v[76:79], v[28:31], v[48:51], v[12:15]
	v_mfma_f32_16x16x32_bf16 v[12:15], v[32:35], v[44:47], 0
	v_mfma_f32_16x16x32_bf16 v[80:83], v[36:39], v[48:51], v[12:15]
	v_mfma_f32_16x16x32_bf16 v[12:15], v[24:27], v[52:55], 0
	v_mfma_f32_16x16x32_bf16 v[84:87], v[28:31], v[56:59], v[12:15]
	v_mfma_f32_16x16x32_bf16 v[12:15], v[32:35], v[52:55], 0
	v_mfma_f32_16x16x32_bf16 v[88:91], v[36:39], v[56:59], v[12:15]
	v_mfma_f32_16x16x32_bf16 v[12:15], v[24:27], v[60:63], 0
	v_mfma_f32_16x16x32_bf16 v[92:95], v[28:31], v[64:67], v[12:15]
	v_mfma_f32_16x16x32_bf16 v[12:15], v[32:35], v[60:63], 0
	v_mfma_f32_16x16x32_bf16 v[96:99], v[36:39], v[64:67], v[12:15]
	s_barrier
	s_nop 4
	v_lshl_add_u64 v[12:13], s[46:47], 0, v[4:5]
	s_add_i32 s68, s62, s50
	v_lshl_add_u64 v[14:15], v[12:13], 0, s[10:11]
	s_mov_b32 m0, s68
	ds_read_b128 v[100:103], v23
	ds_read_b128 v[104:107], v23 offset:1024
	ds_read_b128 v[108:111], v23 offset:2048
	ds_read_b128 v[112:115], v23 offset:3072
	global_load_lds_dwordx4 v[14:15], off
	v_lshl_add_u64 v[14:15], s[46:47], 0, v[0:1]
	s_add_i32 s66, s68, 0x2000
	v_lshl_add_u64 v[116:117], v[14:15], 0, s[10:11]
	s_mov_b32 m0, s66
	s_nop 0
	global_load_lds_dwordx4 v[116:117], off
	s_barrier
	s_waitcnt lgkmcnt(0)
	s_waitcnt lgkmcnt(0)
	v_mfma_f32_16x16x32_bf16 v[116:119], v[100:103], v[16:19], 0
	v_mfma_f32_16x16x32_bf16 v[16:19], v[108:111], v[16:19], 0
	v_mfma_f32_16x16x32_bf16 v[116:119], v[104:107], v[40:43], v[116:119]
	v_mfma_f32_16x16x32_bf16 v[40:43], v[112:115], v[40:43], v[16:19]
	v_mfma_f32_16x16x32_bf16 v[16:19], v[100:103], v[44:47], 0
	v_mfma_f32_16x16x32_bf16 v[120:123], v[104:107], v[48:51], v[16:19]
	v_mfma_f32_16x16x32_bf16 v[16:19], v[108:111], v[44:47], 0
	v_mfma_f32_16x16x32_bf16 v[44:47], v[112:115], v[48:51], v[16:19]
	v_mfma_f32_16x16x32_bf16 v[16:19], v[100:103], v[52:55], 0
	v_mfma_f32_16x16x32_bf16 v[48:51], v[104:107], v[56:59], v[16:19]
	v_mfma_f32_16x16x32_bf16 v[16:19], v[108:111], v[52:55], 0
	v_mfma_f32_16x16x32_bf16 v[52:55], v[112:115], v[56:59], v[16:19]
	v_mfma_f32_16x16x32_bf16 v[16:19], v[100:103], v[60:63], 0
	v_mfma_f32_16x16x32_bf16 v[56:59], v[104:107], v[64:67], v[16:19]
	v_mfma_f32_16x16x32_bf16 v[16:19], v[108:111], v[60:63], 0
	v_mfma_f32_16x16x32_bf16 v[60:63], v[112:115], v[64:67], v[16:19]
	s_nop 5
	v_lshl_add_u64 v[16:17], s[44:45], 0, v[6:7]
	s_mov_b32 m0, s35
	v_lshl_add_u64 v[18:19], v[16:17], 0, s[10:11]
	s_barrier
	ds_read_b128 v[64:67], v21 offset:16384
	ds_read_b128 v[124:127], v21 offset:17408
	ds_read_b128 v[130:133], v21 offset:18432
	ds_read_b128 v[134:137], v21 offset:19456
	ds_read_b128 v[138:141], v21 offset:20480
	ds_read_b128 v[142:145], v21 offset:21504
	ds_read_b128 v[146:149], v21 offset:22528
	ds_read_b128 v[150:153], v21 offset:23552
	global_load_lds_dwordx4 v[18:19], off
	v_lshl_add_u64 v[18:19], s[44:45], 0, v[2:3]
	v_lshl_add_u64 v[154:155], v[18:19], 0, s[10:11]
	s_mov_b32 m0, s52
	s_nop 0
	global_load_lds_dwordx4 v[154:155], off
	s_barrier
	s_waitcnt lgkmcnt(0)
	s_waitcnt lgkmcnt(0)
	v_mfma_f32_16x16x32_bf16 v[154:157], v[24:27], v[64:67], 0
	v_mfma_f32_16x16x32_bf16 v[162:165], v[24:27], v[130:133], 0
	v_mfma_f32_16x16x32_bf16 v[170:173], v[24:27], v[138:141], 0
	v_mfma_f32_16x16x32_bf16 v[24:27], v[24:27], v[146:149], 0
	v_mfma_f32_16x16x32_bf16 v[154:157], v[28:31], v[124:127], v[154:157]
	v_mfma_f32_16x16x32_bf16 v[158:161], v[32:35], v[64:67], 0
	v_mfma_f32_16x16x32_bf16 v[162:165], v[28:31], v[134:137], v[162:165]
	v_mfma_f32_16x16x32_bf16 v[166:169], v[32:35], v[130:133], 0
	v_mfma_f32_16x16x32_bf16 v[170:173], v[28:31], v[142:145], v[170:173]
	v_mfma_f32_16x16x32_bf16 v[174:177], v[32:35], v[138:141], 0
	v_mfma_f32_16x16x32_bf16 v[26:29], v[28:31], v[150:153], v[24:27]
	v_mfma_f32_16x16x32_bf16 v[30:33], v[32:35], v[146:149], 0
	v_mfma_f32_16x16x32_bf16 v[158:161], v[36:39], v[124:127], v[158:161]
	v_mfma_f32_16x16x32_bf16 v[166:169], v[36:39], v[134:137], v[166:169]
	v_mfma_f32_16x16x32_bf16 v[174:177], v[36:39], v[142:145], v[174:177]
	v_mfma_f32_16x16x32_bf16 v[30:33], v[36:39], v[150:153], v[30:33]
	s_barrier
; #define PG8_STAGE(bufoff, gbase, voff) do { _Pragma("unroll") for (int _i = 0; _i < 2; ++_i) \
;         __builtin_amdgcn_global_load_lds((const unsigned*)((const char*)(gbase) + (voff)[_i]), (LAS unsigned*)(lds + (bufoff) + ldsw + _i * 8192), 16, 0, 0); } while (0)
; #define PG8_LDA(dst, b, h) do { _Pragma("unroll") for (int m = 0; m < 4; ++m) _Pragma("unroll") for (int k = 0; k < 2; ++k) dst[m][k] = *(const LAS bf16x8*)(lds + PG8_SA(b, h) + aoff + m * 2048 + k * 1024); } while (0)
; #define PG8_LDB(dst, b, h) do { _Pragma("unroll") for (int n = 0; n < 2; ++n) _Pragma("unroll") for (int k = 0; k < 2; ++k) dst[n][k] = *(const LAS bf16x8*)(lds + PG8_SB(b, h) + boff + n * 2048 + k * 1024); } while (0)
; #define PG8_MMA(ai, bj, At, Bt) do { __builtin_amdgcn_s_setprio(1); _Pragma("unroll") for (int m = 0; m < 4; ++m) _Pragma("unroll") for (int n = 0; n < 2; ++n) _Pragma("unroll") for (int k = 0; k < 2; ++k) \
;         acc[ai][bj][m][n] = __builtin_amdgcn_mfma_f32_16x16x32_bf16(Bt[n][k], At[m][k], acc[ai][bj][m][n], 0, 0, 0); __builtin_amdgcn_s_setprio(0); } while (0)
; #define PG8_WAIT_V(n) asm volatile("s_waitcnt vmcnt(" #n ")" ::: "memory")
; #define PG8_WAIT_L(n) asm volatile("s_waitcnt lgkmcnt(" #n ")" ::: "memory")
; #define PG8_BAR __builtin_amdgcn_s_barrier()
; #define PG8_SCHED __builtin_amdgcn_sched_barrier(0)
; template <class Epi, bool SP2 = false>
; __device__ __forceinline__ void gemm_phase(LAS unsigned char* lds, const Gemm g, const StaticOrder& S, const Epi& E) {
;     ...
;             PG8_STAGE(PG8_SB(0, 1), b2 + hstepB, voffB);
;             PG8_WAIT_V(6); PG8_BAR; PG8_MMA(1, 1, At, B1); PG8_BAR;
;             PG8_LDB(B0, 1, 0); PG8_SCHED; PG8_LDA(At, 1, 0); PG8_STAGE(PG8_SA(0, 1), a2 + hstepA, voffA);
;             PG8_WAIT_L(8); PG8_BAR; PG8_WAIT_L(0); PG8_MMA(0, 0, At, B0); PG8_BAR; PG8_SCHED;
;             PG8_LDB(B1, 1, 1); PG8_STAGE(PG8_SB(1, 0), b3, voffB);
;             PG8_BAR; PG8_WAIT_L(0); PG8_MMA(0, 1, At, B1); PG8_BAR;
;             PG8_LDA(At, 1, 1); PG8_STAGE(PG8_SA(1, 0), a3, voffA);
;             PG8_BAR; PG8_WAIT_L(0); PG8_MMA(1, 0, At, B0); PG8_BAR; PG8_SCHED;
	s_add_u32 s70, s46, 0x18100
	s_addc_u32 s71, s47, 0
	s_add_i32 s69, s63, s50
	v_lshl_add_u64 v[24:25], s[70:71], 0, v[4:5]
	s_mov_b32 m0, s69
	s_add_i32 s67, s69, 0x2000
	global_load_lds_dwordx4 v[24:25], off
	v_lshl_add_u64 v[24:25], s[70:71], 0, v[0:1]
	s_mov_b32 m0, s67
	s_nop 0
	global_load_lds_dwordx4 v[24:25], off
	s_waitcnt vmcnt(6)
	s_barrier
	v_mfma_f32_16x16x32_bf16 v[34:37], v[100:103], v[64:67], 0
	v_mfma_f32_16x16x32_bf16 v[64:67], v[108:111], v[64:67], 0
	v_mfma_f32_16x16x32_bf16 v[34:37], v[104:107], v[124:127], v[34:37]
	v_mfma_f32_16x16x32_bf16 v[64:67], v[112:115], v[124:127], v[64:67]
	v_mfma_f32_16x16x32_bf16 v[124:127], v[100:103], v[130:133], 0
	v_mfma_f32_16x16x32_bf16 v[130:133], v[108:111], v[130:133], 0
	v_mfma_f32_16x16x32_bf16 v[124:127], v[104:107], v[134:137], v[124:127]
	v_mfma_f32_16x16x32_bf16 v[130:133], v[112:115], v[134:137], v[130:133]
	v_mfma_f32_16x16x32_bf16 v[134:137], v[100:103], v[138:141], 0
	v_mfma_f32_16x16x32_bf16 v[100:103], v[100:103], v[146:149], 0
	v_mfma_f32_16x16x32_bf16 v[134:137], v[104:107], v[142:145], v[134:137]
	v_mfma_f32_16x16x32_bf16 v[138:141], v[108:111], v[138:141], 0
	v_mfma_f32_16x16x32_bf16 v[100:103], v[104:107], v[150:153], v[100:103]
	v_mfma_f32_16x16x32_bf16 v[104:107], v[108:111], v[146:149], 0
	v_mfma_f32_16x16x32_bf16 v[138:141], v[112:115], v[142:145], v[138:141]
	v_mfma_f32_16x16x32_bf16 v[104:107], v[112:115], v[150:153], v[104:107]
	s_add_i32 s73, 0, 0x18000
	v_add_u32_e32 v24, s73, v20
	s_barrier
	ds_read_b128 v[108:111], v24
	ds_read_b128 v[112:115], v24 offset:1024
	ds_read_b128 v[142:145], v24 offset:2048
	ds_read_b128 v[146:149], v24 offset:3072
	s_add_u32 s70, s44, 0x20100
	s_addc_u32 s71, s45, 0
	s_mov_b32 m0, s53
	v_lshl_add_u64 v[38:39], s[70:71], 0, v[6:7]
	ds_read_b128 v[150:153], v21 offset:32768
	ds_read_b128 v[178:181], v21 offset:33792
	ds_read_b128 v[182:185], v21 offset:34816
	ds_read_b128 v[186:189], v21 offset:35840
	ds_read_b128 v[190:193], v21 offset:36864
	ds_read_b128 v[194:197], v21 offset:37888
	ds_read_b128 v[198:201], v21 offset:38912
	ds_read_b128 v[202:205], v21 offset:39936
	global_load_lds_dwordx4 v[38:39], off
	v_lshl_add_u64 v[38:39], s[70:71], 0, v[2:3]
	s_mov_b32 m0, s54
	s_nop 0
	global_load_lds_dwordx4 v[38:39], off
	s_waitcnt lgkmcnt(8)
	s_barrier
	s_waitcnt lgkmcnt(0)
	s_waitcnt lgkmcnt(0)
	v_mfma_f32_16x16x32_bf16 v[68:71], v[108:111], v[150:153], v[68:71]
	v_mfma_f32_16x16x32_bf16 v[72:75], v[142:145], v[150:153], v[72:75]
	v_mfma_f32_16x16x32_bf16 v[76:79], v[108:111], v[182:185], v[76:79]
	v_mfma_f32_16x16x32_bf16 v[80:83], v[142:145], v[182:185], v[80:83]
	v_mfma_f32_16x16x32_bf16 v[84:87], v[108:111], v[190:193], v[84:87]
	v_mfma_f32_16x16x32_bf16 v[88:91], v[142:145], v[190:193], v[88:91]
	v_mfma_f32_16x16x32_bf16 v[92:95], v[108:111], v[198:201], v[92:95]
	v_mfma_f32_16x16x32_bf16 v[96:99], v[142:145], v[198:201], v[96:99]
	v_mfma_f32_16x16x32_bf16 v[68:71], v[112:115], v[178:181], v[68:71]
	v_mfma_f32_16x16x32_bf16 v[72:75], v[146:149], v[178:181], v[72:75]
	v_mfma_f32_16x16x32_bf16 v[76:79], v[112:115], v[186:189], v[76:79]
	v_mfma_f32_16x16x32_bf16 v[80:83], v[146:149], v[186:189], v[80:83]
	v_mfma_f32_16x16x32_bf16 v[84:87], v[112:115], v[194:197], v[84:87]
	v_mfma_f32_16x16x32_bf16 v[88:91], v[146:149], v[194:197], v[88:91]
	v_mfma_f32_16x16x32_bf16 v[92:95], v[112:115], v[202:205], v[92:95]
	v_mfma_f32_16x16x32_bf16 v[96:99], v[146:149], v[202:205], v[96:99]
	s_barrier
	s_add_i32 s74, 0, 0x1c000
	s_add_i32 s73, s73, s50
	v_add_u32_e32 v25, s74, v20
	v_lshl_add_u64 v[38:39], v[12:13], 0, s[12:13]
	s_mov_b32 m0, s73
	s_add_i32 s70, s73, 0x2000
	ds_read_b128 v[206:209], v25
	ds_read_b128 v[210:213], v25 offset:1024
	ds_read_b128 v[214:217], v25 offset:2048
	ds_read_b128 v[218:221], v25 offset:3072
	global_load_lds_dwordx4 v[38:39], off
	v_lshl_add_u64 v[38:39], v[14:15], 0, s[12:13]
	s_mov_b32 m0, s70
	s_nop 0
	global_load_lds_dwordx4 v[38:39], off
	s_barrier
	s_waitcnt lgkmcnt(0)
	s_waitcnt lgkmcnt(0)
	v_mfma_f32_16x16x32_bf16 v[116:119], v[206:209], v[150:153], v[116:119]
	v_mfma_f32_16x16x32_bf16 v[38:41], v[214:217], v[150:153], v[40:43]
	v_mfma_f32_16x16x32_bf16 v[120:123], v[206:209], v[182:185], v[120:123]
	v_mfma_f32_16x16x32_bf16 v[42:45], v[214:217], v[182:185], v[44:47]
	v_mfma_f32_16x16x32_bf16 v[46:49], v[206:209], v[190:193], v[48:51]
	v_mfma_f32_16x16x32_bf16 v[50:53], v[214:217], v[190:193], v[52:55]
	v_mfma_f32_16x16x32_bf16 v[54:57], v[206:209], v[198:201], v[56:59]
	v_mfma_f32_16x16x32_bf16 v[58:61], v[214:217], v[198:201], v[60:63]
	v_mfma_f32_16x16x32_bf16 v[116:119], v[210:213], v[178:181], v[116:119]
	v_mfma_f32_16x16x32_bf16 v[38:41], v[218:221], v[178:181], v[38:41]
	v_mfma_f32_16x16x32_bf16 v[120:123], v[210:213], v[186:189], v[120:123]
	v_mfma_f32_16x16x32_bf16 v[42:45], v[218:221], v[186:189], v[42:45]
	v_mfma_f32_16x16x32_bf16 v[46:49], v[210:213], v[194:197], v[46:49]
	v_mfma_f32_16x16x32_bf16 v[50:53], v[218:221], v[194:197], v[50:53]
	v_mfma_f32_16x16x32_bf16 v[54:57], v[210:213], v[202:205], v[54:57]
	v_mfma_f32_16x16x32_bf16 v[58:61], v[218:221], v[202:205], v[58:61]
	s_mov_b32 m0, s57
	v_lshl_add_u64 v[62:63], v[16:17], 0, s[12:13]
	s_barrier
	ds_read_b128 v[150:153], v21 offset:49152
	ds_read_b128 v[178:181], v21 offset:50176
	ds_read_b128 v[182:185], v21 offset:51200
	ds_read_b128 v[186:189], v21 offset:52224
	ds_read_b128 v[190:193], v21 offset:53248
	ds_read_b128 v[194:197], v21 offset:54272
	ds_read_b128 v[198:201], v21 offset:55296
	ds_read_b128 v[202:205], v21 offset:56320
	global_load_lds_dwordx4 v[62:63], off
	v_lshl_add_u64 v[62:63], v[18:19], 0, s[12:13]
	s_mov_b32 m0, s58
	s_nop 0
	global_load_lds_dwordx4 v[62:63], off
	s_barrier
; #define PG8_STAGE(bufoff, gbase, voff) do { _Pragma("unroll") for (int _i = 0; _i < 2; ++_i) \
;         __builtin_amdgcn_global_load_lds((const unsigned*)((const char*)(gbase) + (voff)[_i]), (LAS unsigned*)(lds + (bufoff) + ldsw + _i * 8192), 16, 0, 0); } while (0)
; #define PG8_LDA(dst, b, h) do { _Pragma("unroll") for (int m = 0; m < 4; ++m) _Pragma("unroll") for (int k = 0; k < 2; ++k) dst[m][k] = *(const LAS bf16x8*)(lds + PG8_SA(b, h) + aoff + m * 2048 + k * 1024); } while (0)
; #define PG8_LDB(dst, b, h) do { _Pragma("unroll") for (int n = 0; n < 2; ++n) _Pragma("unroll") for (int k = 0; k < 2; ++k) dst[n][k] = *(const LAS bf16x8*)(lds + PG8_SB(b, h) + boff + n * 2048 + k * 1024); } while (0)
; #define PG8_MMA(ai, bj, At, Bt) do { __builtin_amdgcn_s_setprio(1); _Pragma("unroll") for (int m = 0; m < 4; ++m) _Pragma("unroll") for (int n = 0; n < 2; ++n) _Pragma("unroll") for (int k = 0; k < 2; ++k) \
;         acc[ai][bj][m][n] = __builtin_amdgcn_mfma_f32_16x16x32_bf16(Bt[n][k], At[m][k], acc[ai][bj][m][n], 0, 0, 0); __builtin_amdgcn_s_setprio(0); } while (0)
; #define PG8_WAIT_V(n) asm volatile("s_waitcnt vmcnt(" #n ")" ::: "memory")
; #define PG8_WAIT_L(n) asm volatile("s_waitcnt lgkmcnt(" #n ")" ::: "memory")
; #define PG8_BAR __builtin_amdgcn_s_barrier()
; #define PG8_SCHED __builtin_amdgcn_sched_barrier(0)
; template <class Epi, bool SP2 = false>
; __device__ __forceinline__ void gemm_phase(LAS unsigned char* lds, const Gemm g, const StaticOrder& S, const Epi& E) {
;     ...
;             PG8_LDB(B0, 0, 0); PG8_SCHED; PG8_LDA(At, 0, 0); PG8_STAGE(PG8_SA(1, 1), a1 + hstepA, voffA);
;             PG8_WAIT_L(8); PG8_BAR; PG8_WAIT_L(0); PG8_MMA(0, 0, At, B0); PG8_BAR; PG8_SCHED;
;             PG8_LDB(B1, 0, 1); PG8_STAGE(PG8_SB(0, 0), b2, voffB);
;             PG8_BAR; PG8_WAIT_L(0); PG8_MMA(0, 1, At, B1); PG8_BAR;
;     ...
;             PG8_BAR; PG8_WAIT_L(0); PG8_MMA(1, 0, At, B0); PG8_BAR; PG8_SCHED;
;             PG8_STAGE(PG8_SB(1, 1), b3 + hstepB, voffB);
;             PG8_WAIT_V(6); PG8_BAR; PG8_MMA(1, 1, At, B1); PG8_BAR;
	s_waitcnt lgkmcnt(0)
	s_waitcnt lgkmcnt(0)
	v_mfma_f32_16x16x32_bf16 v[154:157], v[108:111], v[150:153], v[154:157]
	v_mfma_f32_16x16x32_bf16 v[158:161], v[142:145], v[150:153], v[158:161]
	v_mfma_f32_16x16x32_bf16 v[162:165], v[108:111], v[182:185], v[162:165]
	v_mfma_f32_16x16x32_bf16 v[166:169], v[142:145], v[182:185], v[166:169]
	v_mfma_f32_16x16x32_bf16 v[170:173], v[108:111], v[190:193], v[170:173]
	v_mfma_f32_16x16x32_bf16 v[174:177], v[142:145], v[190:193], v[174:177]
	v_mfma_f32_16x16x32_bf16 v[26:29], v[108:111], v[198:201], v[26:29]
	v_mfma_f32_16x16x32_bf16 v[30:33], v[142:145], v[198:201], v[30:33]
	v_mfma_f32_16x16x32_bf16 v[154:157], v[112:115], v[178:181], v[154:157]
	v_mfma_f32_16x16x32_bf16 v[158:161], v[146:149], v[178:181], v[158:161]
	v_mfma_f32_16x16x32_bf16 v[162:165], v[112:115], v[186:189], v[162:165]
	v_mfma_f32_16x16x32_bf16 v[166:169], v[146:149], v[186:189], v[166:169]
	v_mfma_f32_16x16x32_bf16 v[170:173], v[112:115], v[194:197], v[170:173]
	v_mfma_f32_16x16x32_bf16 v[174:177], v[146:149], v[194:197], v[174:177]
	v_mfma_f32_16x16x32_bf16 v[26:29], v[112:115], v[202:205], v[26:29]
	v_mfma_f32_16x16x32_bf16 v[30:33], v[146:149], v[202:205], v[30:33]
	s_barrier
	s_add_u32 s76, s46, 0x18180
	s_addc_u32 s77, s47, 0
	s_add_i32 s74, s74, s50
	v_lshl_add_u64 v[62:63], s[76:77], 0, v[4:5]
	s_mov_b32 m0, s74
	s_add_i32 s71, s74, 0x2000
	global_load_lds_dwordx4 v[62:63], off
	v_lshl_add_u64 v[62:63], s[76:77], 0, v[0:1]
	s_mov_b32 m0, s71
	s_nop 0
	global_load_lds_dwordx4 v[62:63], off
	s_waitcnt vmcnt(6)
	s_barrier
	v_mfma_f32_16x16x32_bf16 v[34:37], v[206:209], v[150:153], v[34:37]
	v_mfma_f32_16x16x32_bf16 v[62:65], v[214:217], v[150:153], v[64:67]
	v_mfma_f32_16x16x32_bf16 v[108:111], v[206:209], v[182:185], v[124:127]
	v_mfma_f32_16x16x32_bf16 v[112:115], v[214:217], v[182:185], v[130:133]
	v_mfma_f32_16x16x32_bf16 v[124:127], v[206:209], v[190:193], v[134:137]
	v_mfma_f32_16x16x32_bf16 v[130:133], v[214:217], v[190:193], v[138:141]
	v_mfma_f32_16x16x32_bf16 v[100:103], v[206:209], v[198:201], v[100:103]
	v_mfma_f32_16x16x32_bf16 v[104:107], v[214:217], v[198:201], v[104:107]
	v_mfma_f32_16x16x32_bf16 v[34:37], v[210:213], v[178:181], v[34:37]
	v_mfma_f32_16x16x32_bf16 v[62:65], v[218:221], v[178:181], v[62:65]
	v_mfma_f32_16x16x32_bf16 v[108:111], v[210:213], v[186:189], v[108:111]
	v_mfma_f32_16x16x32_bf16 v[112:115], v[218:221], v[186:189], v[112:115]
	v_mfma_f32_16x16x32_bf16 v[124:127], v[210:213], v[194:197], v[124:127]
	v_mfma_f32_16x16x32_bf16 v[130:133], v[218:221], v[194:197], v[130:133]
	v_mfma_f32_16x16x32_bf16 v[100:103], v[210:213], v[202:205], v[100:103]
	v_mfma_f32_16x16x32_bf16 v[104:107], v[218:221], v[202:205], v[104:107]
	s_barrier
	ds_read_b128 v[134:137], v22
	ds_read_b128 v[138:141], v22 offset:1024
	ds_read_b128 v[142:145], v22 offset:2048
	ds_read_b128 v[146:149], v22 offset:3072
	s_add_u32 s76, s44, 0x20180
	s_addc_u32 s77, s45, 0
	s_mov_b32 m0, s72
	v_lshl_add_u64 v[66:67], s[76:77], 0, v[6:7]
	ds_read_b128 v[150:153], v21
	ds_read_b128 v[178:181], v21 offset:1024
	ds_read_b128 v[182:185], v21 offset:2048
	ds_read_b128 v[186:189], v21 offset:3072
	ds_read_b128 v[190:193], v21 offset:4096
	ds_read_b128 v[194:197], v21 offset:5120
	ds_read_b128 v[198:201], v21 offset:6144
	ds_read_b128 v[202:205], v21 offset:7168
	global_load_lds_dwordx4 v[66:67], off
	v_lshl_add_u64 v[66:67], s[76:77], 0, v[2:3]
	s_mov_b32 m0, s39
	s_nop 0
	global_load_lds_dwordx4 v[66:67], off
	s_waitcnt lgkmcnt(8)
	s_barrier
	s_waitcnt lgkmcnt(0)
	s_waitcnt lgkmcnt(0)
	v_mfma_f32_16x16x32_bf16 v[66:69], v[134:137], v[150:153], v[68:71]
	v_mfma_f32_16x16x32_bf16 v[70:73], v[142:145], v[150:153], v[72:75]
	v_mfma_f32_16x16x32_bf16 v[74:77], v[134:137], v[182:185], v[76:79]
	v_mfma_f32_16x16x32_bf16 v[78:81], v[142:145], v[182:185], v[80:83]
	v_mfma_f32_16x16x32_bf16 v[82:85], v[134:137], v[190:193], v[84:87]
	v_mfma_f32_16x16x32_bf16 v[86:89], v[142:145], v[190:193], v[88:91]
	v_mfma_f32_16x16x32_bf16 v[90:93], v[134:137], v[198:201], v[92:95]
	v_mfma_f32_16x16x32_bf16 v[94:97], v[142:145], v[198:201], v[96:99]
	v_mfma_f32_16x16x32_bf16 v[66:69], v[138:141], v[178:181], v[66:69]
	v_mfma_f32_16x16x32_bf16 v[70:73], v[146:149], v[178:181], v[70:73]
	v_mfma_f32_16x16x32_bf16 v[74:77], v[138:141], v[186:189], v[74:77]
	v_mfma_f32_16x16x32_bf16 v[78:81], v[146:149], v[186:189], v[78:81]
	v_mfma_f32_16x16x32_bf16 v[82:85], v[138:141], v[194:197], v[82:85]
	v_mfma_f32_16x16x32_bf16 v[86:89], v[146:149], v[194:197], v[86:89]
	v_mfma_f32_16x16x32_bf16 v[90:93], v[138:141], v[202:205], v[90:93]
	v_mfma_f32_16x16x32_bf16 v[94:97], v[146:149], v[202:205], v[94:97]
	s_barrier
	s_mov_b32 m0, s68
	v_lshl_add_u64 v[98:99], v[12:13], 0, s[28:29]
	ds_read_b128 v[206:209], v23
	ds_read_b128 v[210:213], v23 offset:1024
	ds_read_b128 v[214:217], v23 offset:2048
	ds_read_b128 v[218:221], v23 offset:3072
	global_load_lds_dwordx4 v[98:99], off
	v_lshl_add_u64 v[98:99], v[14:15], 0, s[28:29]
	s_mov_b32 m0, s66
	s_nop 0
	global_load_lds_dwordx4 v[98:99], off
	s_barrier
; #define PG8_STAGE(bufoff, gbase, voff) do { _Pragma("unroll") for (int _i = 0; _i < 2; ++_i) \
;         __builtin_amdgcn_global_load_lds((const unsigned*)((const char*)(gbase) + (voff)[_i]), (LAS unsigned*)(lds + (bufoff) + ldsw + _i * 8192), 16, 0, 0); } while (0)
; #define PG8_LDA(dst, b, h) do { _Pragma("unroll") for (int m = 0; m < 4; ++m) _Pragma("unroll") for (int k = 0; k < 2; ++k) dst[m][k] = *(const LAS bf16x8*)(lds + PG8_SA(b, h) + aoff + m * 2048 + k * 1024); } while (0)
; #define PG8_LDB(dst, b, h) do { _Pragma("unroll") for (int n = 0; n < 2; ++n) _Pragma("unroll") for (int k = 0; k < 2; ++k) dst[n][k] = *(const LAS bf16x8*)(lds + PG8_SB(b, h) + boff + n * 2048 + k * 1024); } while (0)
; #define PG8_MMA(ai, bj, At, Bt) do { __builtin_amdgcn_s_setprio(1); _Pragma("unroll") for (int m = 0; m < 4; ++m) _Pragma("unroll") for (int n = 0; n < 2; ++n) _Pragma("unroll") for (int k = 0; k < 2; ++k) \
;         acc[ai][bj][m][n] = __builtin_amdgcn_mfma_f32_16x16x32_bf16(Bt[n][k], At[m][k], acc[ai][bj][m][n], 0, 0, 0); __builtin_amdgcn_s_setprio(0); } while (0)
; #define PG8_WAIT_V(n) asm volatile("s_waitcnt vmcnt(" #n ")" ::: "memory")
; #define PG8_WAIT_L(n) asm volatile("s_waitcnt lgkmcnt(" #n ")" ::: "memory")
; #define PG8_BAR __builtin_amdgcn_s_barrier()
; #define PG8_SCHED __builtin_amdgcn_sched_barrier(0)
; template <class Epi, bool SP2 = false>
; __device__ __forceinline__ void gemm_phase(LAS unsigned char* lds, const Gemm g, const StaticOrder& S, const Epi& E) {
;     ...
;             PG8_BAR; PG8_WAIT_L(0); PG8_MMA(0, 1, At, B1); PG8_BAR;
;             PG8_LDA(At, 0, 1); PG8_STAGE(PG8_SA(0, 0), a2, voffA);
;             PG8_BAR; PG8_WAIT_L(0); PG8_MMA(1, 0, At, B0); PG8_BAR; PG8_SCHED;
;             PG8_STAGE(PG8_SB(0, 1), b2 + hstepB, voffB);
;             PG8_WAIT_V(6); PG8_BAR; PG8_MMA(1, 1, At, B1); PG8_BAR;
;             PG8_LDB(B0, 1, 0); PG8_SCHED; PG8_LDA(At, 1, 0); PG8_STAGE(PG8_SA(0, 1), a2 + hstepA, voffA);
;             PG8_WAIT_L(8); PG8_BAR; PG8_WAIT_L(0); PG8_MMA(0, 0, At, B0); PG8_BAR; PG8_SCHED;
	s_waitcnt lgkmcnt(0)
	s_waitcnt lgkmcnt(0)
	v_mfma_f32_16x16x32_bf16 v[116:119], v[206:209], v[150:153], v[116:119]
	v_mfma_f32_16x16x32_bf16 v[38:41], v[214:217], v[150:153], v[38:41]
	v_mfma_f32_16x16x32_bf16 v[120:123], v[206:209], v[182:185], v[120:123]
	v_mfma_f32_16x16x32_bf16 v[42:45], v[214:217], v[182:185], v[42:45]
	v_mfma_f32_16x16x32_bf16 v[46:49], v[206:209], v[190:193], v[46:49]
	v_mfma_f32_16x16x32_bf16 v[50:53], v[214:217], v[190:193], v[50:53]
	v_mfma_f32_16x16x32_bf16 v[54:57], v[206:209], v[198:201], v[54:57]
	v_mfma_f32_16x16x32_bf16 v[58:61], v[214:217], v[198:201], v[58:61]
	v_mfma_f32_16x16x32_bf16 v[116:119], v[210:213], v[178:181], v[116:119]
	v_mfma_f32_16x16x32_bf16 v[38:41], v[218:221], v[178:181], v[38:41]
	v_mfma_f32_16x16x32_bf16 v[120:123], v[210:213], v[186:189], v[120:123]
	v_mfma_f32_16x16x32_bf16 v[42:45], v[218:221], v[186:189], v[42:45]
	v_mfma_f32_16x16x32_bf16 v[46:49], v[210:213], v[194:197], v[46:49]
	v_mfma_f32_16x16x32_bf16 v[50:53], v[218:221], v[194:197], v[50:53]
	v_mfma_f32_16x16x32_bf16 v[54:57], v[210:213], v[202:205], v[54:57]
	v_mfma_f32_16x16x32_bf16 v[58:61], v[218:221], v[202:205], v[58:61]
	s_mov_b32 m0, s35
	v_lshl_add_u64 v[98:99], v[16:17], 0, s[28:29]
	s_barrier
	ds_read_b128 v[150:153], v21 offset:16384
	ds_read_b128 v[178:181], v21 offset:17408
	ds_read_b128 v[182:185], v21 offset:18432
	ds_read_b128 v[186:189], v21 offset:19456
	ds_read_b128 v[190:193], v21 offset:20480
	ds_read_b128 v[194:197], v21 offset:21504
	ds_read_b128 v[198:201], v21 offset:22528
	ds_read_b128 v[202:205], v21 offset:23552
	global_load_lds_dwordx4 v[98:99], off
	v_lshl_add_u64 v[98:99], v[18:19], 0, s[28:29]
	s_mov_b32 m0, s52
	s_nop 0
	global_load_lds_dwordx4 v[98:99], off
	s_barrier
	s_waitcnt lgkmcnt(0)
	s_waitcnt lgkmcnt(0)
	v_mfma_f32_16x16x32_bf16 v[154:157], v[134:137], v[150:153], v[154:157]
	v_mfma_f32_16x16x32_bf16 v[158:161], v[142:145], v[150:153], v[158:161]
	v_mfma_f32_16x16x32_bf16 v[162:165], v[134:137], v[182:185], v[162:165]
	v_mfma_f32_16x16x32_bf16 v[166:169], v[142:145], v[182:185], v[166:169]
	v_mfma_f32_16x16x32_bf16 v[170:173], v[134:137], v[190:193], v[170:173]
	v_mfma_f32_16x16x32_bf16 v[174:177], v[142:145], v[190:193], v[174:177]
	v_mfma_f32_16x16x32_bf16 v[26:29], v[134:137], v[198:201], v[26:29]
	v_mfma_f32_16x16x32_bf16 v[30:33], v[142:145], v[198:201], v[30:33]
	v_mfma_f32_16x16x32_bf16 v[154:157], v[138:141], v[178:181], v[154:157]
	v_mfma_f32_16x16x32_bf16 v[158:161], v[146:149], v[178:181], v[158:161]
	v_mfma_f32_16x16x32_bf16 v[162:165], v[138:141], v[186:189], v[162:165]
	v_mfma_f32_16x16x32_bf16 v[166:169], v[146:149], v[186:189], v[166:169]
	v_mfma_f32_16x16x32_bf16 v[170:173], v[138:141], v[194:197], v[170:173]
	v_mfma_f32_16x16x32_bf16 v[174:177], v[146:149], v[194:197], v[174:177]
	v_mfma_f32_16x16x32_bf16 v[26:29], v[138:141], v[202:205], v[26:29]
	v_mfma_f32_16x16x32_bf16 v[30:33], v[146:149], v[202:205], v[30:33]
	s_barrier
	s_add_u32 s76, s46, 0x18200
	s_addc_u32 s77, s47, 0
	s_mov_b32 m0, s69
	v_lshl_add_u64 v[98:99], s[76:77], 0, v[4:5]
	global_load_lds_dwordx4 v[98:99], off
	v_lshl_add_u64 v[98:99], s[76:77], 0, v[0:1]
	s_mov_b32 m0, s67
	s_nop 0
	global_load_lds_dwordx4 v[98:99], off
	s_waitcnt vmcnt(6)
	s_barrier
	v_mfma_f32_16x16x32_bf16 v[34:37], v[206:209], v[150:153], v[34:37]
	v_mfma_f32_16x16x32_bf16 v[62:65], v[214:217], v[150:153], v[62:65]
	v_mfma_f32_16x16x32_bf16 v[108:111], v[206:209], v[182:185], v[108:111]
	v_mfma_f32_16x16x32_bf16 v[112:115], v[214:217], v[182:185], v[112:115]
	v_mfma_f32_16x16x32_bf16 v[124:127], v[206:209], v[190:193], v[124:127]
	v_mfma_f32_16x16x32_bf16 v[130:133], v[214:217], v[190:193], v[130:133]
	v_mfma_f32_16x16x32_bf16 v[98:101], v[206:209], v[198:201], v[100:103]
	v_mfma_f32_16x16x32_bf16 v[102:105], v[214:217], v[198:201], v[104:107]
	v_mfma_f32_16x16x32_bf16 v[34:37], v[210:213], v[178:181], v[34:37]
	v_mfma_f32_16x16x32_bf16 v[62:65], v[218:221], v[178:181], v[62:65]
	v_mfma_f32_16x16x32_bf16 v[108:111], v[210:213], v[186:189], v[108:111]
	v_mfma_f32_16x16x32_bf16 v[112:115], v[218:221], v[186:189], v[112:115]
	v_mfma_f32_16x16x32_bf16 v[124:127], v[210:213], v[194:197], v[124:127]
	v_mfma_f32_16x16x32_bf16 v[130:133], v[218:221], v[194:197], v[130:133]
	v_mfma_f32_16x16x32_bf16 v[98:101], v[210:213], v[202:205], v[98:101]
	v_mfma_f32_16x16x32_bf16 v[102:105], v[218:221], v[202:205], v[102:105]
	s_barrier
	ds_read_b128 v[134:137], v24
	ds_read_b128 v[138:141], v24 offset:1024
	ds_read_b128 v[142:145], v24 offset:2048
	ds_read_b128 v[146:149], v24 offset:3072
	s_add_u32 s76, s44, 0x20200
	s_addc_u32 s77, s45, 0
	s_mov_b32 m0, s53
	v_lshl_add_u64 v[106:107], s[76:77], 0, v[6:7]
	ds_read_b128 v[150:153], v21 offset:32768
	ds_read_b128 v[178:181], v21 offset:33792
	ds_read_b128 v[182:185], v21 offset:34816
	ds_read_b128 v[186:189], v21 offset:35840
	ds_read_b128 v[190:193], v21 offset:36864
	ds_read_b128 v[194:197], v21 offset:37888
	ds_read_b128 v[198:201], v21 offset:38912
	ds_read_b128 v[202:205], v21 offset:39936
	global_load_lds_dwordx4 v[106:107], off
	v_lshl_add_u64 v[106:107], s[76:77], 0, v[2:3]
	s_mov_b32 m0, s54
	s_nop 0
	global_load_lds_dwordx4 v[106:107], off
	s_waitcnt lgkmcnt(8)
	s_barrier
; #define PG8_STAGE(bufoff, gbase, voff) do { _Pragma("unroll") for (int _i = 0; _i < 2; ++_i) \
;         __builtin_amdgcn_global_load_lds((const unsigned*)((const char*)(gbase) + (voff)[_i]), (LAS unsigned*)(lds + (bufoff) + ldsw + _i * 8192), 16, 0, 0); } while (0)
; #define PG8_LDA(dst, b, h) do { _Pragma("unroll") for (int m = 0; m < 4; ++m) _Pragma("unroll") for (int k = 0; k < 2; ++k) dst[m][k] = *(const LAS bf16x8*)(lds + PG8_SA(b, h) + aoff + m * 2048 + k * 1024); } while (0)
; #define PG8_LDB(dst, b, h) do { _Pragma("unroll") for (int n = 0; n < 2; ++n) _Pragma("unroll") for (int k = 0; k < 2; ++k) dst[n][k] = *(const LAS bf16x8*)(lds + PG8_SB(b, h) + boff + n * 2048 + k * 1024); } while (0)
; #define PG8_MMA(ai, bj, At, Bt) do { __builtin_amdgcn_s_setprio(1); _Pragma("unroll") for (int m = 0; m < 4; ++m) _Pragma("unroll") for (int n = 0; n < 2; ++n) _Pragma("unroll") for (int k = 0; k < 2; ++k) \
;         acc[ai][bj][m][n] = __builtin_amdgcn_mfma_f32_16x16x32_bf16(Bt[n][k], At[m][k], acc[ai][bj][m][n], 0, 0, 0); __builtin_amdgcn_s_setprio(0); } while (0)
; #define PG8_WAIT_V(n) asm volatile("s_waitcnt vmcnt(" #n ")" ::: "memory")
; #define PG8_WAIT_L(n) asm volatile("s_waitcnt lgkmcnt(" #n ")" ::: "memory")
; #define PG8_BAR __builtin_amdgcn_s_barrier()
; #define PG8_SCHED __builtin_amdgcn_sched_barrier(0)
; template <class Epi, bool SP2 = false>
; __device__ __forceinline__ void gemm_phase(LAS unsigned char* lds, const Gemm g, const StaticOrder& S, const Epi& E) {
;     ...
;             PG8_WAIT_L(8); PG8_BAR; PG8_WAIT_L(0); PG8_MMA(0, 0, At, B0); PG8_BAR; PG8_SCHED;
;             PG8_LDB(B1, 1, 1); PG8_STAGE(PG8_SB(1, 0), b3, voffB);
;             PG8_BAR; PG8_WAIT_L(0); PG8_MMA(0, 1, At, B1); PG8_BAR;
;             PG8_LDA(At, 1, 1); PG8_STAGE(PG8_SA(1, 0), a3, voffA);
;             PG8_BAR; PG8_WAIT_L(0); PG8_MMA(1, 0, At, B0); PG8_BAR; PG8_SCHED;
;             PG8_STAGE(PG8_SB(1, 1), b3 + hstepB, voffB);
;             PG8_WAIT_V(6); PG8_BAR; PG8_MMA(1, 1, At, B1); PG8_BAR;
	s_waitcnt lgkmcnt(0)
	s_waitcnt lgkmcnt(0)
	v_mfma_f32_16x16x32_bf16 v[66:69], v[134:137], v[150:153], v[66:69]
	v_mfma_f32_16x16x32_bf16 v[70:73], v[142:145], v[150:153], v[70:73]
	v_mfma_f32_16x16x32_bf16 v[74:77], v[134:137], v[182:185], v[74:77]
	v_mfma_f32_16x16x32_bf16 v[78:81], v[142:145], v[182:185], v[78:81]
	v_mfma_f32_16x16x32_bf16 v[82:85], v[134:137], v[190:193], v[82:85]
	v_mfma_f32_16x16x32_bf16 v[86:89], v[142:145], v[190:193], v[86:89]
	v_mfma_f32_16x16x32_bf16 v[90:93], v[134:137], v[198:201], v[90:93]
	v_mfma_f32_16x16x32_bf16 v[94:97], v[142:145], v[198:201], v[94:97]
	v_mfma_f32_16x16x32_bf16 v[66:69], v[138:141], v[178:181], v[66:69]
	v_mfma_f32_16x16x32_bf16 v[70:73], v[146:149], v[178:181], v[70:73]
	v_mfma_f32_16x16x32_bf16 v[74:77], v[138:141], v[186:189], v[74:77]
	v_mfma_f32_16x16x32_bf16 v[78:81], v[146:149], v[186:189], v[78:81]
	v_mfma_f32_16x16x32_bf16 v[82:85], v[138:141], v[194:197], v[82:85]
	v_mfma_f32_16x16x32_bf16 v[86:89], v[146:149], v[194:197], v[86:89]
	v_mfma_f32_16x16x32_bf16 v[90:93], v[138:141], v[202:205], v[90:93]
	v_mfma_f32_16x16x32_bf16 v[94:97], v[146:149], v[202:205], v[94:97]
	s_barrier
	s_mov_b32 m0, s73
	v_lshl_add_u64 v[12:13], v[12:13], 0, s[30:31]
	ds_read_b128 v[206:209], v25
	ds_read_b128 v[210:213], v25 offset:1024
	ds_read_b128 v[214:217], v25 offset:2048
	ds_read_b128 v[218:221], v25 offset:3072
	global_load_lds_dwordx4 v[12:13], off
	v_lshl_add_u64 v[12:13], v[14:15], 0, s[30:31]
	s_mov_b32 m0, s70
	s_nop 0
	global_load_lds_dwordx4 v[12:13], off
	s_barrier
	s_waitcnt lgkmcnt(0)
	s_waitcnt lgkmcnt(0)
	v_mfma_f32_16x16x32_bf16 v[12:15], v[206:209], v[150:153], v[116:119]
	v_mfma_f32_16x16x32_bf16 v[38:41], v[214:217], v[150:153], v[38:41]
	v_mfma_f32_16x16x32_bf16 v[116:119], v[206:209], v[182:185], v[120:123]
	v_mfma_f32_16x16x32_bf16 v[42:45], v[214:217], v[182:185], v[42:45]
	v_mfma_f32_16x16x32_bf16 v[46:49], v[206:209], v[190:193], v[46:49]
	v_mfma_f32_16x16x32_bf16 v[50:53], v[214:217], v[190:193], v[50:53]
	v_mfma_f32_16x16x32_bf16 v[54:57], v[206:209], v[198:201], v[54:57]
	v_mfma_f32_16x16x32_bf16 v[58:61], v[214:217], v[198:201], v[58:61]
	v_mfma_f32_16x16x32_bf16 v[12:15], v[210:213], v[178:181], v[12:15]
	v_mfma_f32_16x16x32_bf16 v[38:41], v[218:221], v[178:181], v[38:41]
	v_mfma_f32_16x16x32_bf16 v[116:119], v[210:213], v[186:189], v[116:119]
	v_mfma_f32_16x16x32_bf16 v[42:45], v[218:221], v[186:189], v[42:45]
	v_mfma_f32_16x16x32_bf16 v[46:49], v[210:213], v[194:197], v[46:49]
	v_mfma_f32_16x16x32_bf16 v[50:53], v[218:221], v[194:197], v[50:53]
	v_mfma_f32_16x16x32_bf16 v[54:57], v[210:213], v[202:205], v[54:57]
	v_mfma_f32_16x16x32_bf16 v[58:61], v[218:221], v[202:205], v[58:61]
	s_mov_b32 m0, s57
	v_lshl_add_u64 v[16:17], v[16:17], 0, s[30:31]
	s_barrier
	ds_read_b128 v[120:123], v21 offset:49152
	ds_read_b128 v[150:153], v21 offset:50176
	ds_read_b128 v[178:181], v21 offset:51200
	ds_read_b128 v[182:185], v21 offset:52224
	ds_read_b128 v[186:189], v21 offset:53248
	ds_read_b128 v[190:193], v21 offset:54272
	ds_read_b128 v[194:197], v21 offset:55296
	ds_read_b128 v[198:201], v21 offset:56320
	global_load_lds_dwordx4 v[16:17], off
	v_lshl_add_u64 v[16:17], v[18:19], 0, s[30:31]
	s_mov_b32 m0, s58
	s_nop 0
	global_load_lds_dwordx4 v[16:17], off
	s_barrier
	s_waitcnt lgkmcnt(0)
	s_waitcnt lgkmcnt(0)
	v_mfma_f32_16x16x32_bf16 v[16:19], v[134:137], v[120:123], v[154:157]
	v_mfma_f32_16x16x32_bf16 v[154:157], v[142:145], v[120:123], v[158:161]
	v_mfma_f32_16x16x32_bf16 v[158:161], v[134:137], v[178:181], v[162:165]
	v_mfma_f32_16x16x32_bf16 v[162:165], v[142:145], v[178:181], v[166:169]
	v_mfma_f32_16x16x32_bf16 v[166:169], v[134:137], v[186:189], v[170:173]
	v_mfma_f32_16x16x32_bf16 v[170:173], v[142:145], v[186:189], v[174:177]
	v_mfma_f32_16x16x32_bf16 v[26:29], v[134:137], v[194:197], v[26:29]
	v_mfma_f32_16x16x32_bf16 v[30:33], v[142:145], v[194:197], v[30:33]
	v_mfma_f32_16x16x32_bf16 v[16:19], v[138:141], v[150:153], v[16:19]
	v_mfma_f32_16x16x32_bf16 v[154:157], v[146:149], v[150:153], v[154:157]
	v_mfma_f32_16x16x32_bf16 v[158:161], v[138:141], v[182:185], v[158:161]
	v_mfma_f32_16x16x32_bf16 v[162:165], v[146:149], v[182:185], v[162:165]
	v_mfma_f32_16x16x32_bf16 v[166:169], v[138:141], v[190:193], v[166:169]
	v_mfma_f32_16x16x32_bf16 v[170:173], v[146:149], v[190:193], v[170:173]
	v_mfma_f32_16x16x32_bf16 v[26:29], v[138:141], v[198:201], v[26:29]
	v_mfma_f32_16x16x32_bf16 v[30:33], v[146:149], v[198:201], v[30:33]
	s_barrier
	s_add_u32 s46, s46, 0x18280
	s_addc_u32 s47, s47, 0
	s_mov_b32 m0, s74
	v_lshl_add_u64 v[106:107], s[46:47], 0, v[4:5]
	global_load_lds_dwordx4 v[106:107], off
	v_lshl_add_u64 v[106:107], s[46:47], 0, v[0:1]
	s_mov_b32 m0, s71
	s_nop 0
	global_load_lds_dwordx4 v[106:107], off
	s_waitcnt vmcnt(6)
	s_barrier
	v_mfma_f32_16x16x32_bf16 v[34:37], v[206:209], v[120:123], v[34:37]
	v_mfma_f32_16x16x32_bf16 v[62:65], v[214:217], v[120:123], v[62:65]
	v_mfma_f32_16x16x32_bf16 v[106:109], v[206:209], v[178:181], v[108:111]
	v_mfma_f32_16x16x32_bf16 v[110:113], v[214:217], v[178:181], v[112:115]
	v_mfma_f32_16x16x32_bf16 v[120:123], v[206:209], v[186:189], v[124:127]
	v_mfma_f32_16x16x32_bf16 v[124:127], v[214:217], v[186:189], v[130:133]
	v_mfma_f32_16x16x32_bf16 v[98:101], v[206:209], v[194:197], v[98:101]
	v_mfma_f32_16x16x32_bf16 v[102:105], v[214:217], v[194:197], v[102:105]
	v_mfma_f32_16x16x32_bf16 v[34:37], v[210:213], v[150:153], v[34:37]
	v_mfma_f32_16x16x32_bf16 v[62:65], v[218:221], v[150:153], v[62:65]
	v_mfma_f32_16x16x32_bf16 v[106:109], v[210:213], v[182:185], v[106:109]
	v_mfma_f32_16x16x32_bf16 v[110:113], v[218:221], v[182:185], v[110:113]
	v_mfma_f32_16x16x32_bf16 v[120:123], v[210:213], v[190:193], v[120:123]
	v_mfma_f32_16x16x32_bf16 v[124:127], v[218:221], v[190:193], v[124:127]
	v_mfma_f32_16x16x32_bf16 v[98:101], v[210:213], v[198:201], v[98:101]
	v_mfma_f32_16x16x32_bf16 v[102:105], v[218:221], v[198:201], v[102:105]
	s_barrier
; #define PG8_STAGE(bufoff, gbase, voff) do { _Pragma("unroll") for (int _i = 0; _i < 2; ++_i) \
;         __builtin_amdgcn_global_load_lds((const unsigned*)((const char*)(gbase) + (voff)[_i]), (LAS unsigned*)(lds + (bufoff) + ldsw + _i * 8192), 16, 0, 0); } while (0)
; #define PG8_LDA(dst, b, h) do { _Pragma("unroll") for (int m = 0; m < 4; ++m) _Pragma("unroll") for (int k = 0; k < 2; ++k) dst[m][k] = *(const LAS bf16x8*)(lds + PG8_SA(b, h) + aoff + m * 2048 + k * 1024); } while (0)
; #define PG8_LDB(dst, b, h) do { _Pragma("unroll") for (int n = 0; n < 2; ++n) _Pragma("unroll") for (int k = 0; k < 2; ++k) dst[n][k] = *(const LAS bf16x8*)(lds + PG8_SB(b, h) + boff + n * 2048 + k * 1024); } while (0)
; #define PG8_MMA(ai, bj, At, Bt) do { __builtin_amdgcn_s_setprio(1); _Pragma("unroll") for (int m = 0; m < 4; ++m) _Pragma("unroll") for (int n = 0; n < 2; ++n) _Pragma("unroll") for (int k = 0; k < 2; ++k) \
;         acc[ai][bj][m][n] = __builtin_amdgcn_mfma_f32_16x16x32_bf16(Bt[n][k], At[m][k], acc[ai][bj][m][n], 0, 0, 0); __builtin_amdgcn_s_setprio(0); } while (0)
; #define PG8_WAIT_V(n) asm volatile("s_waitcnt vmcnt(" #n ")" ::: "memory")
; #define PG8_WAIT_L(n) asm volatile("s_waitcnt lgkmcnt(" #n ")" ::: "memory")
; #define PG8_BAR __builtin_amdgcn_s_barrier()
; #define PG8_SCHED __builtin_amdgcn_sched_barrier(0)
; template <class Epi, bool SP2 = false>
; __device__ __forceinline__ void gemm_phase(LAS unsigned char* lds, const Gemm g, const StaticOrder& S, const Epi& E) {
;     ...
;             PG8_LDB(B0, 0, 0); PG8_SCHED; PG8_LDA(At, 0, 0); PG8_STAGE(PG8_SA(1, 1), a1 + hstepA, voffA);
;             PG8_WAIT_L(8); PG8_BAR; PG8_WAIT_L(0); PG8_MMA(0, 0, At, B0); PG8_BAR; PG8_SCHED;
;             PG8_LDB(B1, 0, 1); PG8_STAGE(PG8_SB(0, 0), b2, voffB);
;             PG8_BAR; PG8_WAIT_L(0); PG8_MMA(0, 1, At, B1); PG8_BAR;
;             PG8_LDA(At, 0, 1); PG8_STAGE(PG8_SA(0, 0), a2, voffA);
;             PG8_BAR; PG8_WAIT_L(0); PG8_MMA(1, 0, At, B0); PG8_BAR; PG8_SCHED;
;             PG8_STAGE(PG8_SB(0, 1), b2 + hstepB, voffB);
;             PG8_WAIT_V(6); PG8_BAR; PG8_MMA(1, 1, At, B1); PG8_BAR;
	ds_read_b128 v[130:133], v22
	ds_read_b128 v[134:137], v22 offset:1024
	ds_read_b128 v[138:141], v22 offset:2048
	ds_read_b128 v[142:145], v22 offset:3072
	s_add_u32 s44, s44, 0x20280
	s_addc_u32 s45, s45, 0
	s_mov_b32 m0, s72
	v_lshl_add_u64 v[114:115], s[44:45], 0, v[6:7]
	ds_read_b128 v[146:149], v21
	ds_read_b128 v[150:153], v21 offset:1024
	ds_read_b128 v[174:177], v21 offset:2048
	ds_read_b128 v[178:181], v21 offset:3072
	ds_read_b128 v[182:185], v21 offset:4096
	ds_read_b128 v[186:189], v21 offset:5120
	ds_read_b128 v[190:193], v21 offset:6144
	ds_read_b128 v[194:197], v21 offset:7168
	global_load_lds_dwordx4 v[114:115], off
	v_lshl_add_u64 v[114:115], s[44:45], 0, v[2:3]
	s_mov_b32 m0, s39
	s_nop 0
	global_load_lds_dwordx4 v[114:115], off
	s_waitcnt lgkmcnt(8)
	s_barrier
	s_waitcnt lgkmcnt(0)
	s_waitcnt lgkmcnt(0)
	v_mfma_f32_16x16x32_bf16 v[66:69], v[130:133], v[146:149], v[66:69]
	v_mfma_f32_16x16x32_bf16 v[70:73], v[138:141], v[146:149], v[70:73]
	v_mfma_f32_16x16x32_bf16 v[74:77], v[130:133], v[174:177], v[74:77]
	v_mfma_f32_16x16x32_bf16 v[78:81], v[138:141], v[174:177], v[78:81]
	v_mfma_f32_16x16x32_bf16 v[82:85], v[130:133], v[182:185], v[82:85]
	v_mfma_f32_16x16x32_bf16 v[86:89], v[138:141], v[182:185], v[86:89]
	v_mfma_f32_16x16x32_bf16 v[90:93], v[130:133], v[190:193], v[90:93]
	v_mfma_f32_16x16x32_bf16 v[94:97], v[138:141], v[190:193], v[94:97]
	v_mfma_f32_16x16x32_bf16 v[66:69], v[134:137], v[150:153], v[66:69]
	v_mfma_f32_16x16x32_bf16 v[70:73], v[142:145], v[150:153], v[70:73]
	v_mfma_f32_16x16x32_bf16 v[74:77], v[134:137], v[178:181], v[74:77]
	v_mfma_f32_16x16x32_bf16 v[78:81], v[142:145], v[178:181], v[78:81]
	v_mfma_f32_16x16x32_bf16 v[82:85], v[134:137], v[186:189], v[82:85]
	v_mfma_f32_16x16x32_bf16 v[86:89], v[142:145], v[186:189], v[86:89]
	v_mfma_f32_16x16x32_bf16 v[90:93], v[134:137], v[194:197], v[90:93]
	v_mfma_f32_16x16x32_bf16 v[94:97], v[142:145], v[194:197], v[94:97]
	s_barrier
	s_mov_b32 m0, s68
	v_lshl_add_u64 v[214:215], s[40:41], 0, v[4:5]
	ds_read_b128 v[198:201], v23
	ds_read_b128 v[202:205], v23 offset:1024
	ds_read_b128 v[206:209], v23 offset:2048
	ds_read_b128 v[210:213], v23 offset:3072
	global_load_lds_dwordx4 v[214:215], off
	v_lshl_add_u64 v[216:217], s[40:41], 0, v[0:1]
	s_mov_b32 m0, s66
	s_nop 0
	global_load_lds_dwordx4 v[216:217], off
	s_barrier
	s_waitcnt lgkmcnt(0)
	s_waitcnt lgkmcnt(0)
	v_mfma_f32_16x16x32_bf16 v[12:15], v[198:201], v[146:149], v[12:15]
	v_mfma_f32_16x16x32_bf16 v[38:41], v[206:209], v[146:149], v[38:41]
	v_mfma_f32_16x16x32_bf16 v[114:117], v[198:201], v[174:177], v[116:119]
	v_mfma_f32_16x16x32_bf16 v[42:45], v[206:209], v[174:177], v[42:45]
	v_mfma_f32_16x16x32_bf16 v[46:49], v[198:201], v[182:185], v[46:49]
	v_mfma_f32_16x16x32_bf16 v[50:53], v[206:209], v[182:185], v[50:53]
	v_mfma_f32_16x16x32_bf16 v[54:57], v[198:201], v[190:193], v[54:57]
	v_mfma_f32_16x16x32_bf16 v[58:61], v[206:209], v[190:193], v[58:61]
	v_mfma_f32_16x16x32_bf16 v[12:15], v[202:205], v[150:153], v[12:15]
	v_mfma_f32_16x16x32_bf16 v[38:41], v[210:213], v[150:153], v[38:41]
	v_mfma_f32_16x16x32_bf16 v[114:117], v[202:205], v[178:181], v[114:117]
	v_mfma_f32_16x16x32_bf16 v[42:45], v[210:213], v[178:181], v[42:45]
	v_mfma_f32_16x16x32_bf16 v[46:49], v[202:205], v[186:189], v[46:49]
	v_mfma_f32_16x16x32_bf16 v[50:53], v[210:213], v[186:189], v[50:53]
	v_mfma_f32_16x16x32_bf16 v[54:57], v[202:205], v[194:197], v[54:57]
	v_mfma_f32_16x16x32_bf16 v[58:61], v[210:213], v[194:197], v[58:61]
	s_mov_b32 m0, s35
	v_lshl_add_u64 v[218:219], s[4:5], 0, v[6:7]
	s_barrier
	ds_read_b128 v[146:149], v21 offset:16384
	ds_read_b128 v[150:153], v21 offset:17408
	ds_read_b128 v[174:177], v21 offset:18432
	ds_read_b128 v[178:181], v21 offset:19456
	ds_read_b128 v[182:185], v21 offset:20480
	ds_read_b128 v[186:189], v21 offset:21504
	ds_read_b128 v[190:193], v21 offset:22528
	ds_read_b128 v[194:197], v21 offset:23552
	global_load_lds_dwordx4 v[218:219], off
	v_lshl_add_u64 v[220:221], s[4:5], 0, v[2:3]
	s_mov_b32 m0, s52
	s_nop 0
	global_load_lds_dwordx4 v[220:221], off
	s_barrier
	s_waitcnt lgkmcnt(0)
	s_waitcnt lgkmcnt(0)
	v_mfma_f32_16x16x32_bf16 v[16:19], v[130:133], v[146:149], v[16:19]
	v_mfma_f32_16x16x32_bf16 v[154:157], v[138:141], v[146:149], v[154:157]
	v_mfma_f32_16x16x32_bf16 v[158:161], v[130:133], v[174:177], v[158:161]
	v_mfma_f32_16x16x32_bf16 v[162:165], v[138:141], v[174:177], v[162:165]
	v_mfma_f32_16x16x32_bf16 v[166:169], v[130:133], v[182:185], v[166:169]
	v_mfma_f32_16x16x32_bf16 v[170:173], v[138:141], v[182:185], v[170:173]
	v_mfma_f32_16x16x32_bf16 v[26:29], v[130:133], v[190:193], v[26:29]
	v_mfma_f32_16x16x32_bf16 v[30:33], v[138:141], v[190:193], v[30:33]
	v_mfma_f32_16x16x32_bf16 v[16:19], v[134:137], v[150:153], v[16:19]
	v_mfma_f32_16x16x32_bf16 v[154:157], v[142:145], v[150:153], v[154:157]
	v_mfma_f32_16x16x32_bf16 v[158:161], v[134:137], v[178:181], v[158:161]
	v_mfma_f32_16x16x32_bf16 v[162:165], v[142:145], v[178:181], v[162:165]
	v_mfma_f32_16x16x32_bf16 v[166:169], v[134:137], v[186:189], v[166:169]
	v_mfma_f32_16x16x32_bf16 v[170:173], v[142:145], v[186:189], v[170:173]
	v_mfma_f32_16x16x32_bf16 v[26:29], v[134:137], v[194:197], v[26:29]
	v_mfma_f32_16x16x32_bf16 v[30:33], v[142:145], v[194:197], v[30:33]
	s_barrier
	s_add_u32 s44, s40, 0x18000
	s_addc_u32 s45, s41, 0
	s_mov_b32 m0, s69
	v_lshl_add_u64 v[118:119], s[44:45], 0, v[4:5]
	global_load_lds_dwordx4 v[118:119], off
	v_lshl_add_u64 v[118:119], s[44:45], 0, v[0:1]
	s_mov_b32 m0, s67
	s_nop 0
	global_load_lds_dwordx4 v[118:119], off
	s_waitcnt vmcnt(6)
	s_barrier
; #define PG8_STAGE(bufoff, gbase, voff) do { _Pragma("unroll") for (int _i = 0; _i < 2; ++_i) \
;         __builtin_amdgcn_global_load_lds((const unsigned*)((const char*)(gbase) + (voff)[_i]), (LAS unsigned*)(lds + (bufoff) + ldsw + _i * 8192), 16, 0, 0); } while (0)
; #define PG8_LDA(dst, b, h) do { _Pragma("unroll") for (int m = 0; m < 4; ++m) _Pragma("unroll") for (int k = 0; k < 2; ++k) dst[m][k] = *(const LAS bf16x8*)(lds + PG8_SA(b, h) + aoff + m * 2048 + k * 1024); } while (0)
; #define PG8_LDB(dst, b, h) do { _Pragma("unroll") for (int n = 0; n < 2; ++n) _Pragma("unroll") for (int k = 0; k < 2; ++k) dst[n][k] = *(const LAS bf16x8*)(lds + PG8_SB(b, h) + boff + n * 2048 + k * 1024); } while (0)
; #define PG8_MMA(ai, bj, At, Bt) do { __builtin_amdgcn_s_setprio(1); _Pragma("unroll") for (int m = 0; m < 4; ++m) _Pragma("unroll") for (int n = 0; n < 2; ++n) _Pragma("unroll") for (int k = 0; k < 2; ++k) \
;         acc[ai][bj][m][n] = __builtin_amdgcn_mfma_f32_16x16x32_bf16(Bt[n][k], At[m][k], acc[ai][bj][m][n], 0, 0, 0); __builtin_amdgcn_s_setprio(0); } while (0)
; #define PG8_WAIT_V(n) asm volatile("s_waitcnt vmcnt(" #n ")" ::: "memory")
; #define PG8_WAIT_L(n) asm volatile("s_waitcnt lgkmcnt(" #n ")" ::: "memory")
; #define PG8_BAR __builtin_amdgcn_s_barrier()
; #define PG8_SCHED __builtin_amdgcn_sched_barrier(0)
; template <class Epi, bool SP2 = false>
; __device__ __forceinline__ void gemm_phase(LAS unsigned char* lds, const Gemm g, const StaticOrder& S, const Epi& E) {
;     ...
;             PG8_WAIT_V(6); PG8_BAR; PG8_MMA(1, 1, At, B1); PG8_BAR;
;             PG8_LDB(B0, 1, 0); PG8_SCHED; PG8_LDA(At, 1, 0); PG8_STAGE(PG8_SA(0, 1), a2 + hstepA, voffA);
;             PG8_WAIT_L(8); PG8_BAR; PG8_WAIT_L(0); PG8_MMA(0, 0, At, B0); PG8_BAR; PG8_SCHED;
;             PG8_LDB(B1, 1, 1); PG8_STAGE(PG8_SB(1, 0), b3, voffB);
;             PG8_BAR; PG8_WAIT_L(0); PG8_MMA(0, 1, At, B1); PG8_BAR;
;             PG8_LDA(At, 1, 1); PG8_STAGE(PG8_SA(1, 0), a3, voffA);
;             PG8_BAR; PG8_WAIT_L(0); PG8_MMA(1, 0, At, B0); PG8_BAR; PG8_SCHED;
	v_mfma_f32_16x16x32_bf16 v[34:37], v[198:201], v[146:149], v[34:37]
	v_mfma_f32_16x16x32_bf16 v[62:65], v[206:209], v[146:149], v[62:65]
	v_mfma_f32_16x16x32_bf16 v[106:109], v[198:201], v[174:177], v[106:109]
	v_mfma_f32_16x16x32_bf16 v[110:113], v[206:209], v[174:177], v[110:113]
	v_mfma_f32_16x16x32_bf16 v[118:121], v[198:201], v[182:185], v[120:123]
	v_mfma_f32_16x16x32_bf16 v[122:125], v[206:209], v[182:185], v[124:127]
	v_mfma_f32_16x16x32_bf16 v[98:101], v[198:201], v[190:193], v[98:101]
	v_mfma_f32_16x16x32_bf16 v[102:105], v[206:209], v[190:193], v[102:105]
	v_mfma_f32_16x16x32_bf16 v[34:37], v[202:205], v[150:153], v[34:37]
	v_mfma_f32_16x16x32_bf16 v[62:65], v[210:213], v[150:153], v[62:65]
	v_mfma_f32_16x16x32_bf16 v[106:109], v[202:205], v[178:181], v[106:109]
	v_mfma_f32_16x16x32_bf16 v[110:113], v[210:213], v[178:181], v[110:113]
	v_mfma_f32_16x16x32_bf16 v[118:121], v[202:205], v[186:189], v[118:121]
	v_mfma_f32_16x16x32_bf16 v[122:125], v[210:213], v[186:189], v[122:125]
	v_mfma_f32_16x16x32_bf16 v[98:101], v[202:205], v[194:197], v[98:101]
	v_mfma_f32_16x16x32_bf16 v[102:105], v[210:213], v[194:197], v[102:105]
	s_barrier
	ds_read_b128 v[130:133], v24
	ds_read_b128 v[134:137], v24 offset:1024
	ds_read_b128 v[138:141], v24 offset:2048
	ds_read_b128 v[142:145], v24 offset:3072
	s_add_u32 s4, s4, 0x20000
	s_addc_u32 s5, s5, 0
	s_mov_b32 m0, s53
	v_lshl_add_u64 v[126:127], s[4:5], 0, v[6:7]
	ds_read_b128 v[146:149], v21 offset:32768
	ds_read_b128 v[150:153], v21 offset:33792
	ds_read_b128 v[174:177], v21 offset:34816
	ds_read_b128 v[178:181], v21 offset:35840
	ds_read_b128 v[182:185], v21 offset:36864
	ds_read_b128 v[186:189], v21 offset:37888
	ds_read_b128 v[190:193], v21 offset:38912
	ds_read_b128 v[194:197], v21 offset:39936
	global_load_lds_dwordx4 v[126:127], off
	v_lshl_add_u64 v[126:127], s[4:5], 0, v[2:3]
	s_mov_b32 m0, s54
	s_nop 0
	global_load_lds_dwordx4 v[126:127], off
	s_waitcnt lgkmcnt(8)
	s_barrier
	s_waitcnt lgkmcnt(0)
	s_waitcnt lgkmcnt(0)
	v_mfma_f32_16x16x32_bf16 v[66:69], v[130:133], v[146:149], v[66:69]
	v_mfma_f32_16x16x32_bf16 v[70:73], v[138:141], v[146:149], v[70:73]
	v_mfma_f32_16x16x32_bf16 v[74:77], v[130:133], v[174:177], v[74:77]
	v_mfma_f32_16x16x32_bf16 v[78:81], v[138:141], v[174:177], v[78:81]
	v_mfma_f32_16x16x32_bf16 v[82:85], v[130:133], v[182:185], v[82:85]
	v_mfma_f32_16x16x32_bf16 v[86:89], v[138:141], v[182:185], v[86:89]
	v_mfma_f32_16x16x32_bf16 v[90:93], v[130:133], v[190:193], v[90:93]
	v_mfma_f32_16x16x32_bf16 v[94:97], v[138:141], v[190:193], v[94:97]
	v_mfma_f32_16x16x32_bf16 v[66:69], v[134:137], v[150:153], v[66:69]
	v_mfma_f32_16x16x32_bf16 v[70:73], v[142:145], v[150:153], v[70:73]
	v_mfma_f32_16x16x32_bf16 v[74:77], v[134:137], v[178:181], v[74:77]
	v_mfma_f32_16x16x32_bf16 v[78:81], v[142:145], v[178:181], v[78:81]
	v_mfma_f32_16x16x32_bf16 v[82:85], v[134:137], v[186:189], v[82:85]
	v_mfma_f32_16x16x32_bf16 v[86:89], v[142:145], v[186:189], v[86:89]
	v_mfma_f32_16x16x32_bf16 v[90:93], v[134:137], v[194:197], v[90:93]
	v_mfma_f32_16x16x32_bf16 v[94:97], v[142:145], v[194:197], v[94:97]
	s_barrier
	s_mov_b32 m0, s73
	ds_read_b128 v[198:201], v25
	ds_read_b128 v[202:205], v25 offset:1024
	ds_read_b128 v[206:209], v25 offset:2048
	ds_read_b128 v[210:213], v25 offset:3072
	v_lshl_add_u64 v[24:25], v[214:215], 0, s[8:9]
	global_load_lds_dwordx4 v[24:25], off
	v_lshl_add_u64 v[24:25], v[216:217], 0, s[8:9]
	s_mov_b32 m0, s70
	s_nop 0
	global_load_lds_dwordx4 v[24:25], off
	s_barrier
	s_waitcnt lgkmcnt(0)
	s_waitcnt lgkmcnt(0)
	v_mfma_f32_16x16x32_bf16 v[12:15], v[198:201], v[146:149], v[12:15]
	v_mfma_f32_16x16x32_bf16 v[38:41], v[206:209], v[146:149], v[38:41]
	v_mfma_f32_16x16x32_bf16 v[114:117], v[198:201], v[174:177], v[114:117]
	v_mfma_f32_16x16x32_bf16 v[42:45], v[206:209], v[174:177], v[42:45]
	v_mfma_f32_16x16x32_bf16 v[46:49], v[198:201], v[182:185], v[46:49]
	v_mfma_f32_16x16x32_bf16 v[50:53], v[206:209], v[182:185], v[50:53]
	v_mfma_f32_16x16x32_bf16 v[54:57], v[198:201], v[190:193], v[54:57]
	v_mfma_f32_16x16x32_bf16 v[58:61], v[206:209], v[190:193], v[58:61]
	v_mfma_f32_16x16x32_bf16 v[12:15], v[202:205], v[150:153], v[12:15]
	v_mfma_f32_16x16x32_bf16 v[38:41], v[210:213], v[150:153], v[38:41]
	v_mfma_f32_16x16x32_bf16 v[114:117], v[202:205], v[178:181], v[114:117]
	v_mfma_f32_16x16x32_bf16 v[42:45], v[210:213], v[178:181], v[42:45]
	v_mfma_f32_16x16x32_bf16 v[46:49], v[202:205], v[186:189], v[46:49]
	v_mfma_f32_16x16x32_bf16 v[50:53], v[210:213], v[186:189], v[50:53]
	v_mfma_f32_16x16x32_bf16 v[54:57], v[202:205], v[194:197], v[54:57]
	v_mfma_f32_16x16x32_bf16 v[58:61], v[210:213], v[194:197], v[58:61]
	s_mov_b32 m0, s57
	v_lshl_add_u64 v[24:25], v[218:219], 0, s[8:9]
	s_barrier
	ds_read_b128 v[146:149], v21 offset:49152
	ds_read_b128 v[150:153], v21 offset:50176
	ds_read_b128 v[174:177], v21 offset:51200
	ds_read_b128 v[178:181], v21 offset:52224
	ds_read_b128 v[182:185], v21 offset:53248
	ds_read_b128 v[186:189], v21 offset:54272
	ds_read_b128 v[190:193], v21 offset:55296
	ds_read_b128 v[194:197], v21 offset:56320
	global_load_lds_dwordx4 v[24:25], off
	v_lshl_add_u64 v[24:25], v[220:221], 0, s[8:9]
	s_mov_b32 m0, s58
	s_nop 0
	global_load_lds_dwordx4 v[24:25], off
	s_barrier
; #define PG8_STAGE(bufoff, gbase, voff) do { _Pragma("unroll") for (int _i = 0; _i < 2; ++_i) \
;         __builtin_amdgcn_global_load_lds((const unsigned*)((const char*)(gbase) + (voff)[_i]), (LAS unsigned*)(lds + (bufoff) + ldsw + _i * 8192), 16, 0, 0); } while (0)
; #define PG8_MMA(ai, bj, At, Bt) do { __builtin_amdgcn_s_setprio(1); _Pragma("unroll") for (int m = 0; m < 4; ++m) _Pragma("unroll") for (int n = 0; n < 2; ++n) _Pragma("unroll") for (int k = 0; k < 2; ++k) \
;         acc[ai][bj][m][n] = __builtin_amdgcn_mfma_f32_16x16x32_bf16(Bt[n][k], At[m][k], acc[ai][bj][m][n], 0, 0, 0); __builtin_amdgcn_s_setprio(0); } while (0)
; #define PG8_WAIT_V(n) asm volatile("s_waitcnt vmcnt(" #n ")" ::: "memory")
; #define PG8_WAIT_L(n) asm volatile("s_waitcnt lgkmcnt(" #n ")" ::: "memory")
; #define PG8_BAR __builtin_amdgcn_s_barrier()
; #define PG8_SCHED __builtin_amdgcn_sched_barrier(0)
; template <class Epi, bool SP2 = false>
; __device__ __forceinline__ void gemm_phase(LAS unsigned char* lds, const Gemm g, const StaticOrder& S, const Epi& E) {
;     ...
;             PG8_BAR; PG8_WAIT_L(0); PG8_MMA(1, 0, At, B0); PG8_BAR; PG8_SCHED;
;             PG8_STAGE(PG8_SB(1, 1), b3 + hstepB, voffB);
;             PG8_WAIT_V(6); PG8_BAR; PG8_MMA(1, 1, At, B1); PG8_BAR;
;     __device__ __forceinline__ void operator()(const f32x4 (&acc)[2][2][4][2], const Unit& u, int wr, int wc, int fr, int fq) const {
;         size_t boff = 0; if (u.pn >= 3) boff += (size_t)((const char*)Kn - (const char*)Q); if (u.pn >= 5) boff += (size_t)T * NKV * 2;
;         bf16_t* dst = (bf16_t*)((char*)Q + boff);
;         int ld = NQ, ctile = u.pn * BM; if (u.pn >= 3) { ld = NKV; ctile = ((u.pn - 3) & 1) * BM; }
;         store_tile_bf16(acc, dst, ld, u.pm * BM + wr * 64 + fr, ctile + wc * 32 + 8 * fq, 0);
	s_waitcnt lgkmcnt(0)
	s_waitcnt lgkmcnt(0)
	v_mfma_f32_16x16x32_bf16 v[16:19], v[130:133], v[146:149], v[16:19]
	v_mfma_f32_16x16x32_bf16 v[154:157], v[138:141], v[146:149], v[154:157]
	v_mfma_f32_16x16x32_bf16 v[158:161], v[130:133], v[174:177], v[158:161]
	v_mfma_f32_16x16x32_bf16 v[162:165], v[138:141], v[174:177], v[162:165]
	v_mfma_f32_16x16x32_bf16 v[166:169], v[130:133], v[182:185], v[166:169]
	v_mfma_f32_16x16x32_bf16 v[170:173], v[138:141], v[182:185], v[170:173]
	v_mfma_f32_16x16x32_bf16 v[24:27], v[130:133], v[190:193], v[26:29]
	v_mfma_f32_16x16x32_bf16 v[28:31], v[138:141], v[190:193], v[30:33]
	v_mfma_f32_16x16x32_bf16 v[16:19], v[134:137], v[150:153], v[16:19]
	v_mfma_f32_16x16x32_bf16 v[154:157], v[142:145], v[150:153], v[154:157]
	v_mfma_f32_16x16x32_bf16 v[158:161], v[134:137], v[178:181], v[158:161]
	v_mfma_f32_16x16x32_bf16 v[162:165], v[142:145], v[178:181], v[162:165]
	v_mfma_f32_16x16x32_bf16 v[166:169], v[134:137], v[186:189], v[166:169]
	v_mfma_f32_16x16x32_bf16 v[170:173], v[142:145], v[186:189], v[170:173]
	v_mfma_f32_16x16x32_bf16 v[24:27], v[134:137], v[194:197], v[24:27]
	v_mfma_f32_16x16x32_bf16 v[28:31], v[142:145], v[194:197], v[28:31]
	s_barrier
	s_add_u32 s4, s40, 0x18080
	s_addc_u32 s5, s41, 0
	s_mov_b32 m0, s74
	v_lshl_add_u64 v[32:33], s[4:5], 0, v[4:5]
	global_load_lds_dwordx4 v[32:33], off
	v_lshl_add_u64 v[32:33], s[4:5], 0, v[0:1]
	s_mov_b32 m0, s71
	s_nop 0
	global_load_lds_dwordx4 v[32:33], off
	s_waitcnt vmcnt(6)
	s_barrier
	v_mfma_f32_16x16x32_bf16 v[32:35], v[198:201], v[146:149], v[34:37]
	v_mfma_f32_16x16x32_bf16 v[62:65], v[206:209], v[146:149], v[62:65]
	v_mfma_f32_16x16x32_bf16 v[106:109], v[198:201], v[174:177], v[106:109]
	v_mfma_f32_16x16x32_bf16 v[110:113], v[206:209], v[174:177], v[110:113]
	v_mfma_f32_16x16x32_bf16 v[118:121], v[198:201], v[182:185], v[118:121]
	v_mfma_f32_16x16x32_bf16 v[122:125], v[206:209], v[182:185], v[122:125]
	v_mfma_f32_16x16x32_bf16 v[98:101], v[198:201], v[190:193], v[98:101]
	v_mfma_f32_16x16x32_bf16 v[102:105], v[206:209], v[190:193], v[102:105]
	v_mfma_f32_16x16x32_bf16 v[32:35], v[202:205], v[150:153], v[32:35]
	v_mfma_f32_16x16x32_bf16 v[62:65], v[210:213], v[150:153], v[62:65]
	v_mfma_f32_16x16x32_bf16 v[106:109], v[202:205], v[178:181], v[106:109]
	v_mfma_f32_16x16x32_bf16 v[110:113], v[210:213], v[178:181], v[110:113]
	v_mfma_f32_16x16x32_bf16 v[118:121], v[202:205], v[186:189], v[118:121]
	v_mfma_f32_16x16x32_bf16 v[122:125], v[210:213], v[186:189], v[122:125]
	v_mfma_f32_16x16x32_bf16 v[98:101], v[202:205], v[194:197], v[98:101]
	v_mfma_f32_16x16x32_bf16 v[102:105], v[210:213], v[194:197], v[102:105]
	s_lshl_b32 s4, s65, 8
	s_andn2_b32 s5, 0x100, s4
	s_cmp_gt_i32 s65, 2
	s_cselect_b32 s39, 0x12000000, 0
	s_cselect_b32 s44, s64, 0x300
	s_cselect_b32 s45, s5, s4
	s_add_i32 s4, s39, 0x6000000
	s_cmp_gt_i32 s65, 4
	s_cselect_b32 s4, s4, s39
	s_cselect_b32 s5, 0, 0
	s_add_u32 s4, s18, s4
	s_addc_u32 s5, s19, s5
	s_lshl_b32 s34, s34, 8
	s_barrier
; __device__ __forceinline__ unsigned pk_bf16(float lo, float hi) { const f32x2 v = {lo, hi}; const bf16x2_t b = __builtin_convertvector(v, bf16x2_t); return __builtin_bit_cast(unsigned, b); }
; __device__ __forceinline__ float fsigmoid(float x) { return __builtin_amdgcn_rcpf(1.0f + fexp(-x)); }
; __device__ __forceinline__ float fgelu(float x) { return x * fsigmoid(1.5957691216057308f * (x + 0.044715f * x * x * x)); }
; __device__ __forceinline__ void store_tile_bf16(const f32x4 (&acc)[2][2][4][2], bf16_t* base, int ld, int row0, int col0, int act) {
; #pragma unroll
;     for (int ai = 0; ai < 2; ++ai)
; #pragma unroll
;         for (int m = 0; m < 4; ++m) {
;             bf16_t* rowp = base + (size_t)(row0 + ai * HALF + m * 16) * ld + col0;
; #pragma unroll
;             for (int bj = 0; bj < 2; ++bj) {
;                 f32x4 v0 = acc[ai][bj][m][0], v1 = acc[ai][bj][m][1];
;                 if (act == 1) {
; #pragma unroll
;                     for (int j = 0; j < 4; ++j) { v0[j] = fgelu(v0[j]); v1[j] = fgelu(v1[j]); }
;                 } else if (act == 2) {
; #pragma unroll
;                     for (int j = 0; j < 4; ++j) { v0[j] = fsigmoid(v0[j]); v1[j] = fsigmoid(v1[j]); }
;                 }
;                 u32x4 w; w.x = pk_bf16(v0[0], v0[1]); w.y = pk_bf16(v0[2], v0[3]); w.z = pk_bf16(v1[0], v1[1]); w.w = pk_bf16(v1[2], v1[3]);
;                 *(u32x4*)(rowp + bj * HALF) = w;
;             }
;             asm volatile("" ::: "memory");
;     __device__ __forceinline__ void operator()(const f32x4 (&acc)[2][2][4][2], const Unit& u, int wr, int wc, int fr, int fq) const {
;     ...
;         store_tile_bf16(acc, dst, ld, u.pm * BM + wr * 64 + fr, ctile + wc * 32 + 8 * fq, 0);
	v_mbcnt_lo_u32_b32 v36, -1, 0
	v_mbcnt_hi_u32_b32 v36, -1, v36
	s_add_i32 s34, s34, s55
	v_and_or_b32 v130, v36, 15, s34
	v_ashrrev_i32_e32 v36, 1, v36
	s_or_b32 s34, s45, s56
	v_and_b32_e32 v36, -8, v36
	v_add_u32_e32 v36, s34, v36
	v_ashrrev_i32_e32 v37, 31, v36
	v_lshl_add_u64 v[36:37], v[36:37], 1, s[4:5]
	v_mad_i64_i32 v[126:127], s[4:5], s44, v130, 0
	v_lshl_add_u64 v[126:127], v[126:127], 1, v[36:37]
	v_cvt_pk_bf16_f32 v12, v12, v13
	v_cvt_pk_bf16_f32 v13, v14, v15
	v_cvt_pk_bf16_f32 v14, v38, v39
	v_cvt_pk_bf16_f32 v15, v40, v41
	global_store_dwordx4 v[126:127], v[12:15], off offset:256
	v_cvt_pk_bf16_f32 v66, v66, v67
	v_cvt_pk_bf16_f32 v67, v68, v69
	v_or_b32_e32 v12, 16, v130
	v_cvt_pk_bf16_f32 v68, v70, v71
	v_cvt_pk_bf16_f32 v69, v72, v73
	v_mad_i64_i32 v[12:13], s[4:5], s44, v12, 0
	global_store_dwordx4 v[126:127], v[66:69], off
	v_lshl_add_u64 v[38:39], v[12:13], 1, v[36:37]
	v_cvt_pk_bf16_f32 v12, v74, v75
	v_cvt_pk_bf16_f32 v13, v76, v77
	v_cvt_pk_bf16_f32 v14, v78, v79
	v_cvt_pk_bf16_f32 v15, v80, v81
	global_store_dwordx4 v[38:39], v[12:15], off
	s_add_i32 s61, s61, s90
	s_andn2_b64 vcc, exec, s[0:1]
	v_cvt_pk_bf16_f32 v12, v114, v115
	v_cvt_pk_bf16_f32 v13, v116, v117
	v_cvt_pk_bf16_f32 v14, v42, v43
	v_cvt_pk_bf16_f32 v15, v44, v45
	global_store_dwordx4 v[38:39], v[12:15], off offset:256
	s_mov_b32 s65, s3
	s_mov_b32 s34, s38
	v_or_b32_e32 v12, 32, v130
	v_mad_i64_i32 v[12:13], s[4:5], s44, v12, 0
	v_lshl_add_u64 v[38:39], v[12:13], 1, v[36:37]
	v_cvt_pk_bf16_f32 v12, v82, v83
	v_cvt_pk_bf16_f32 v13, v84, v85
	v_cvt_pk_bf16_f32 v14, v86, v87
	v_cvt_pk_bf16_f32 v15, v88, v89
	global_store_dwordx4 v[38:39], v[12:15], off
	s_mov_b64 s[46:47], s[40:41]
	s_nop 0
	v_cvt_pk_bf16_f32 v12, v46, v47
	v_cvt_pk_bf16_f32 v13, v48, v49
	v_cvt_pk_bf16_f32 v14, v50, v51
	v_cvt_pk_bf16_f32 v15, v52, v53
	global_store_dwordx4 v[38:39], v[12:15], off offset:256
	s_nop 1
	v_or_b32_e32 v12, 48, v130
	v_mad_i64_i32 v[12:13], s[4:5], s44, v12, 0
	v_lshl_add_u64 v[38:39], v[12:13], 1, v[36:37]
	v_cvt_pk_bf16_f32 v12, v90, v91
	v_cvt_pk_bf16_f32 v13, v92, v93
	v_cvt_pk_bf16_f32 v14, v94, v95
	v_cvt_pk_bf16_f32 v15, v96, v97
	global_store_dwordx4 v[38:39], v[12:15], off
	s_nop 1
	v_cvt_pk_bf16_f32 v12, v54, v55
	v_cvt_pk_bf16_f32 v13, v56, v57
	v_cvt_pk_bf16_f32 v14, v58, v59
	v_cvt_pk_bf16_f32 v15, v60, v61
	global_store_dwordx4 v[38:39], v[12:15], off offset:256
	s_nop 1
	v_add_u32_e32 v12, 0x80, v130
	v_mad_i64_i32 v[12:13], s[4:5], s44, v12, 0
	v_lshl_add_u64 v[38:39], v[12:13], 1, v[36:37]
	v_cvt_pk_bf16_f32 v12, v16, v17
	v_cvt_pk_bf16_f32 v13, v18, v19
	v_cvt_pk_bf16_f32 v14, v154, v155
	v_cvt_pk_bf16_f32 v15, v156, v157
	global_store_dwordx4 v[38:39], v[12:15], off
	s_nop 1
	v_cvt_pk_bf16_f32 v12, v32, v33
	v_cvt_pk_bf16_f32 v13, v34, v35
	v_cvt_pk_bf16_f32 v14, v62, v63
	v_cvt_pk_bf16_f32 v15, v64, v65
	global_store_dwordx4 v[38:39], v[12:15], off offset:256
	s_nop 1
	v_add_u32_e32 v12, 0x90, v130
	v_mad_i64_i32 v[12:13], s[4:5], s44, v12, 0
	v_lshl_add_u64 v[16:17], v[12:13], 1, v[36:37]
	v_cvt_pk_bf16_f32 v12, v158, v159
	v_cvt_pk_bf16_f32 v13, v160, v161
	v_cvt_pk_bf16_f32 v14, v162, v163
	v_cvt_pk_bf16_f32 v15, v164, v165
	global_store_dwordx4 v[16:17], v[12:15], off
	s_nop 1
	v_cvt_pk_bf16_f32 v12, v106, v107
	v_cvt_pk_bf16_f32 v13, v108, v109
	v_cvt_pk_bf16_f32 v14, v110, v111
	v_cvt_pk_bf16_f32 v15, v112, v113
	global_store_dwordx4 v[16:17], v[12:15], off offset:256
	s_nop 1
	v_add_u32_e32 v12, 0xa0, v130
	v_mad_i64_i32 v[12:13], s[4:5], s44, v12, 0
	v_lshl_add_u64 v[16:17], v[12:13], 1, v[36:37]
	v_cvt_pk_bf16_f32 v12, v166, v167
	v_cvt_pk_bf16_f32 v13, v168, v169
	v_cvt_pk_bf16_f32 v14, v170, v171
	v_cvt_pk_bf16_f32 v15, v172, v173
	global_store_dwordx4 v[16:17], v[12:15], off
	s_nop 1
	v_cvt_pk_bf16_f32 v12, v118, v119
	v_cvt_pk_bf16_f32 v13, v120, v121
	v_cvt_pk_bf16_f32 v14, v122, v123
	v_cvt_pk_bf16_f32 v15, v124, v125
	global_store_dwordx4 v[16:17], v[12:15], off offset:256
	s_nop 1
	v_add_u32_e32 v12, 0xb0, v130
	v_mad_i64_i32 v[12:13], s[4:5], s44, v12, 0
	v_lshl_add_u64 v[16:17], v[12:13], 1, v[36:37]
	v_cvt_pk_bf16_f32 v12, v24, v25
	v_cvt_pk_bf16_f32 v13, v26, v27
	v_cvt_pk_bf16_f32 v14, v28, v29
	v_cvt_pk_bf16_f32 v15, v30, v31
	global_store_dwordx4 v[16:17], v[12:15], off
	s_mov_b64 s[44:45], s[42:43]
	s_nop 0
	v_cvt_pk_bf16_f32 v12, v98, v99
	v_cvt_pk_bf16_f32 v13, v100, v101
	v_cvt_pk_bf16_f32 v14, v102, v103
	v_cvt_pk_bf16_f32 v15, v104, v105
	global_store_dwordx4 v[16:17], v[12:15], off offset:256
	s_cbranch_vccz .LBB0_669

; #define PG8_STAGE(bufoff, gbase, voff) do { _Pragma("unroll") for (int _i = 0; _i < 2; ++_i) \
;         __builtin_amdgcn_global_load_lds((const unsigned*)((const char*)(gbase) + (voff)[_i]), (LAS unsigned*)(lds + (bufoff) + ldsw + _i * 8192), 16, 0, 0); } while (0)
; #define PG8_LDA(dst, b, h) do { _Pragma("unroll") for (int m = 0; m < 4; ++m) _Pragma("unroll") for (int k = 0; k < 2; ++k) dst[m][k] = *(const LAS bf16x8*)(lds + PG8_SA(b, h) + aoff + m * 2048 + k * 1024); } while (0)
; #define PG8_LDB(dst, b, h) do { _Pragma("unroll") for (int n = 0; n < 2; ++n) _Pragma("unroll") for (int k = 0; k < 2; ++k) dst[n][k] = *(const LAS bf16x8*)(lds + PG8_SB(b, h) + boff + n * 2048 + k * 1024); } while (0)
; #define PG8_MMA(ai, bj, At, Bt) do { __builtin_amdgcn_s_setprio(1); _Pragma("unroll") for (int m = 0; m < 4; ++m) _Pragma("unroll") for (int n = 0; n < 2; ++n) _Pragma("unroll") for (int k = 0; k < 2; ++k) \
;         acc[ai][bj][m][n] = __builtin_amdgcn_mfma_f32_16x16x32_bf16(Bt[n][k], At[m][k], acc[ai][bj][m][n], 0, 0, 0); __builtin_amdgcn_s_setprio(0); } while (0)
; #define PG8_WAIT_V(n) asm volatile("s_waitcnt vmcnt(" #n ")" ::: "memory")
; #define PG8_WAIT_L(n) asm volatile("s_waitcnt lgkmcnt(" #n ")" ::: "memory")
; #define PG8_BAR __builtin_amdgcn_s_barrier()
; template <class Epi, bool SP2 = false>
; __device__ __forceinline__ void gemm_phase(LAS unsigned char* lds, const Gemm g, const StaticOrder& S, const Epi& E) {
;     ...
;         for (int t = 0; t < nt; t += 2) {
;             const bool last = (t == nt - 2);
;             const char* a1 = cA + (size_t)(t + 1) * kstep;
;             const char* a2 = last ? nA : cA + (size_t)(t + 2) * kstep; const char* b2 = last ? nB : cB + (size_t)(t + 2) * kstep;
;             const char* a3 = a2 + kstep; const char* b3 = b2 + kstep;
;             if constexpr (SP2) {
;             PG8_LDB(B0, 0, 0); PG8_LDB(B1, 0, 1); PG8_SCHED; PG8_LDA(At, 0, 0); PG8_STAGE(PG8_SA(1, 1), a1 + hstepA, voffA);
;             PG8_WAIT_V(8); PG8_WAIT_L(0); PG8_BAR; PG8_MMA(0, 0, At, B0); PG8_MMA(0, 1, At, B1); PG8_BAR; PG8_SCHED;
;             PG8_LDA(At, 0, 1); PG8_STAGE(PG8_SB(0, 0), b2, voffB); PG8_STAGE(PG8_SB(0, 1), b2 + hstepB, voffB); PG8_STAGE(PG8_SA(0, 0), a2, voffA);
;             PG8_WAIT_V(8); PG8_WAIT_L(0); PG8_BAR; PG8_MMA(1, 0, At, B0); PG8_MMA(1, 1, At, B1); PG8_BAR; PG8_SCHED;
.LBB0_805:
	ds_read_b128 v[146:149], v153
	ds_read_b128 v[156:159], v153 offset:1024
	ds_read_b128 v[160:163], v153 offset:2048
	ds_read_b128 v[164:167], v153 offset:3072
	ds_read_b128 v[168:171], v154
	ds_read_b128 v[172:175], v154 offset:1024
	ds_read_b128 v[176:179], v154 offset:2048
	ds_read_b128 v[180:183], v154 offset:3072
	s_add_u32 s48, s34, 0xfffc0080
	s_addc_u32 s49, s35, -1
	s_cmp_eq_u32 s80, 12
	s_cselect_b32 s51, s43, s49
	s_cselect_b32 s50, s76, s48
	s_cselect_b32 s49, s41, s79
	s_cselect_b32 s48, s77, s78
	v_lshl_add_u64 v[150:151], s[34:35], 0, v[138:139]
	s_add_i32 m0, s31, 0xc000
	ds_read_b128 v[184:187], v155
	ds_read_b128 v[188:191], v155 offset:1024
	ds_read_b128 v[192:195], v155 offset:2048
	ds_read_b128 v[196:199], v155 offset:3072
	ds_read_b128 v[200:203], v155 offset:4096
	ds_read_b128 v[204:207], v155 offset:5120
	ds_read_b128 v[208:211], v155 offset:6144
	ds_read_b128 v[212:215], v155 offset:7168
	global_load_lds_dwordx4 v[150:151], off
	v_lshl_add_u64 v[150:151], s[34:35], 0, v[140:141]
	s_add_i32 m0, s31, 0xe000
	s_nop 0
	global_load_lds_dwordx4 v[150:151], off
	s_waitcnt vmcnt(8)
	s_waitcnt lgkmcnt(0)
	s_barrier
	v_mfma_f32_16x16x32_bf16 v[124:127], v[146:149], v[184:187], v[124:127]
	v_mfma_f32_16x16x32_bf16 v[120:123], v[160:163], v[184:187], v[120:123]
	v_mfma_f32_16x16x32_bf16 v[108:111], v[146:149], v[192:195], v[108:111]
	v_mfma_f32_16x16x32_bf16 v[104:107], v[160:163], v[192:195], v[104:107]
	v_mfma_f32_16x16x32_bf16 v[92:95], v[146:149], v[200:203], v[92:95]
	v_mfma_f32_16x16x32_bf16 v[88:91], v[160:163], v[200:203], v[88:91]
	v_mfma_f32_16x16x32_bf16 v[76:79], v[146:149], v[208:211], v[76:79]
	v_mfma_f32_16x16x32_bf16 v[72:75], v[160:163], v[208:211], v[72:75]
	v_mfma_f32_16x16x32_bf16 v[124:127], v[156:159], v[188:191], v[124:127]
	v_mfma_f32_16x16x32_bf16 v[120:123], v[164:167], v[188:191], v[120:123]
	v_mfma_f32_16x16x32_bf16 v[108:111], v[156:159], v[196:199], v[108:111]
	v_mfma_f32_16x16x32_bf16 v[104:107], v[164:167], v[196:199], v[104:107]
	v_mfma_f32_16x16x32_bf16 v[92:95], v[156:159], v[204:207], v[92:95]
	v_mfma_f32_16x16x32_bf16 v[88:91], v[164:167], v[204:207], v[88:91]
	v_mfma_f32_16x16x32_bf16 v[76:79], v[156:159], v[212:215], v[76:79]
	v_mfma_f32_16x16x32_bf16 v[72:75], v[164:167], v[212:215], v[72:75]
	v_mfma_f32_16x16x32_bf16 v[116:119], v[168:171], v[184:187], v[116:119]
	v_mfma_f32_16x16x32_bf16 v[112:115], v[176:179], v[184:187], v[112:115]
	v_mfma_f32_16x16x32_bf16 v[100:103], v[168:171], v[192:195], v[100:103]
	v_mfma_f32_16x16x32_bf16 v[96:99], v[176:179], v[192:195], v[96:99]
	v_mfma_f32_16x16x32_bf16 v[84:87], v[168:171], v[200:203], v[84:87]
	v_mfma_f32_16x16x32_bf16 v[80:83], v[176:179], v[200:203], v[80:83]
	v_mfma_f32_16x16x32_bf16 v[68:71], v[168:171], v[208:211], v[68:71]
	v_mfma_f32_16x16x32_bf16 v[64:67], v[176:179], v[208:211], v[64:67]
	v_mfma_f32_16x16x32_bf16 v[116:119], v[172:175], v[188:191], v[116:119]
	v_mfma_f32_16x16x32_bf16 v[112:115], v[180:183], v[188:191], v[112:115]
	v_mfma_f32_16x16x32_bf16 v[100:103], v[172:175], v[196:199], v[100:103]
	v_mfma_f32_16x16x32_bf16 v[96:99], v[180:183], v[196:199], v[96:99]
	v_mfma_f32_16x16x32_bf16 v[84:87], v[172:175], v[204:207], v[84:87]
	v_mfma_f32_16x16x32_bf16 v[80:83], v[180:183], v[204:207], v[80:83]
	v_mfma_f32_16x16x32_bf16 v[68:71], v[172:175], v[212:215], v[68:71]
	v_mfma_f32_16x16x32_bf16 v[64:67], v[180:183], v[212:215], v[64:67]
	s_barrier
	s_add_i32 s68, s66, s53
	v_lshl_add_u64 v[150:151], s[48:49], 0, v[134:135]
	s_mov_b32 m0, s68
	ds_read_b128 v[184:187], v155 offset:16384
	ds_read_b128 v[188:191], v155 offset:17408
	ds_read_b128 v[192:195], v155 offset:18432
	ds_read_b128 v[196:199], v155 offset:19456
	ds_read_b128 v[200:203], v155 offset:20480
	ds_read_b128 v[204:207], v155 offset:21504
	ds_read_b128 v[208:211], v155 offset:22528
	ds_read_b128 v[212:215], v155 offset:23552
	global_load_lds_dwordx4 v[150:151], off
	s_add_i32 m0, s68, 0x2000
	s_add_u32 s68, s48, 0x40000
	v_lshl_add_u64 v[216:217], s[48:49], 0, v[130:131]
	s_addc_u32 s69, s49, 0
	s_add_i32 s70, s67, s53
	global_load_lds_dwordx4 v[216:217], off
	v_lshl_add_u64 v[218:219], s[68:69], 0, v[134:135]
	s_mov_b32 m0, s70
	v_lshl_add_u64 v[220:221], s[50:51], 0, v[132:133]
	global_load_lds_dwordx4 v[218:219], off
	v_lshl_add_u64 v[218:219], s[68:69], 0, v[130:131]
	s_add_i32 m0, s70, 0x2000
	s_nop 0
	global_load_lds_dwordx4 v[218:219], off
	v_lshl_add_u64 v[218:219], s[50:51], 0, v[136:137]
	s_mov_b32 m0, s31
	s_nop 0
	global_load_lds_dwordx4 v[218:219], off
	s_mov_b32 m0, s56
	s_nop 0
	global_load_lds_dwordx4 v[220:221], off
	s_waitcnt vmcnt(8)
	s_waitcnt lgkmcnt(0)
	s_barrier
; #define PG8_STAGE(bufoff, gbase, voff) do { _Pragma("unroll") for (int _i = 0; _i < 2; ++_i) \
;         __builtin_amdgcn_global_load_lds((const unsigned*)((const char*)(gbase) + (voff)[_i]), (LAS unsigned*)(lds + (bufoff) + ldsw + _i * 8192), 16, 0, 0); } while (0)
; #define PG8_LDA(dst, b, h) do { _Pragma("unroll") for (int m = 0; m < 4; ++m) _Pragma("unroll") for (int k = 0; k < 2; ++k) dst[m][k] = *(const LAS bf16x8*)(lds + PG8_SA(b, h) + aoff + m * 2048 + k * 1024); } while (0)
; #define PG8_LDB(dst, b, h) do { _Pragma("unroll") for (int n = 0; n < 2; ++n) _Pragma("unroll") for (int k = 0; k < 2; ++k) dst[n][k] = *(const LAS bf16x8*)(lds + PG8_SB(b, h) + boff + n * 2048 + k * 1024); } while (0)
; #define PG8_MMA(ai, bj, At, Bt) do { __builtin_amdgcn_s_setprio(1); _Pragma("unroll") for (int m = 0; m < 4; ++m) _Pragma("unroll") for (int n = 0; n < 2; ++n) _Pragma("unroll") for (int k = 0; k < 2; ++k) \
;         acc[ai][bj][m][n] = __builtin_amdgcn_mfma_f32_16x16x32_bf16(Bt[n][k], At[m][k], acc[ai][bj][m][n], 0, 0, 0); __builtin_amdgcn_s_setprio(0); } while (0)
; #define PG8_WAIT_V(n) asm volatile("s_waitcnt vmcnt(" #n ")" ::: "memory")
; #define PG8_WAIT_L(n) asm volatile("s_waitcnt lgkmcnt(" #n ")" ::: "memory")
; #define PG8_BAR __builtin_amdgcn_s_barrier()
; #define PG8_SCHED __builtin_amdgcn_sched_barrier(0)
; template <class Epi, bool SP2 = false>
; __device__ __forceinline__ void gemm_phase(LAS unsigned char* lds, const Gemm g, const StaticOrder& S, const Epi& E) {
;     ...
;             PG8_WAIT_V(8); PG8_WAIT_L(0); PG8_BAR; PG8_MMA(1, 0, At, B0); PG8_MMA(1, 1, At, B1); PG8_BAR; PG8_SCHED;
;             PG8_LDB(B0, 1, 0); PG8_LDB(B1, 1, 1); PG8_SCHED; PG8_LDA(At, 1, 0); PG8_STAGE(PG8_SA(0, 1), a2 + hstepA, voffA);
;             PG8_WAIT_V(8); PG8_WAIT_L(0); PG8_BAR; PG8_MMA(0, 0, At, B0); PG8_MMA(0, 1, At, B1); PG8_BAR; PG8_SCHED;
	v_mfma_f32_16x16x32_bf16 v[60:63], v[146:149], v[184:187], v[60:63]
	v_mfma_f32_16x16x32_bf16 v[56:59], v[160:163], v[184:187], v[56:59]
	v_mfma_f32_16x16x32_bf16 v[44:47], v[146:149], v[192:195], v[44:47]
	v_mfma_f32_16x16x32_bf16 v[40:43], v[160:163], v[192:195], v[40:43]
	v_mfma_f32_16x16x32_bf16 v[28:31], v[146:149], v[200:203], v[28:31]
	v_mfma_f32_16x16x32_bf16 v[24:27], v[160:163], v[200:203], v[24:27]
	v_mfma_f32_16x16x32_bf16 v[12:15], v[146:149], v[208:211], v[12:15]
	v_mfma_f32_16x16x32_bf16 v[8:11], v[160:163], v[208:211], v[8:11]
	v_mfma_f32_16x16x32_bf16 v[60:63], v[156:159], v[188:191], v[60:63]
	v_mfma_f32_16x16x32_bf16 v[56:59], v[164:167], v[188:191], v[56:59]
	v_mfma_f32_16x16x32_bf16 v[44:47], v[156:159], v[196:199], v[44:47]
	v_mfma_f32_16x16x32_bf16 v[40:43], v[164:167], v[196:199], v[40:43]
	v_mfma_f32_16x16x32_bf16 v[28:31], v[156:159], v[204:207], v[28:31]
	v_mfma_f32_16x16x32_bf16 v[24:27], v[164:167], v[204:207], v[24:27]
	v_mfma_f32_16x16x32_bf16 v[12:15], v[156:159], v[212:215], v[12:15]
	v_mfma_f32_16x16x32_bf16 v[8:11], v[164:167], v[212:215], v[8:11]
	v_mfma_f32_16x16x32_bf16 v[52:55], v[168:171], v[184:187], v[52:55]
	v_mfma_f32_16x16x32_bf16 v[48:51], v[176:179], v[184:187], v[48:51]
	v_mfma_f32_16x16x32_bf16 v[36:39], v[168:171], v[192:195], v[36:39]
	v_mfma_f32_16x16x32_bf16 v[32:35], v[176:179], v[192:195], v[32:35]
	v_mfma_f32_16x16x32_bf16 v[20:23], v[168:171], v[200:203], v[20:23]
	v_mfma_f32_16x16x32_bf16 v[16:19], v[176:179], v[200:203], v[16:19]
	v_mfma_f32_16x16x32_bf16 v[4:7], v[168:171], v[208:211], v[4:7]
	v_mfma_f32_16x16x32_bf16 v[0:3], v[176:179], v[208:211], v[0:3]
	v_mfma_f32_16x16x32_bf16 v[52:55], v[172:175], v[188:191], v[52:55]
	v_mfma_f32_16x16x32_bf16 v[48:51], v[180:183], v[188:191], v[48:51]
	v_mfma_f32_16x16x32_bf16 v[36:39], v[172:175], v[196:199], v[36:39]
	v_mfma_f32_16x16x32_bf16 v[32:35], v[180:183], v[196:199], v[32:35]
	v_mfma_f32_16x16x32_bf16 v[20:23], v[172:175], v[204:207], v[20:23]
	v_mfma_f32_16x16x32_bf16 v[16:19], v[180:183], v[204:207], v[16:19]
	v_mfma_f32_16x16x32_bf16 v[4:7], v[172:175], v[212:215], v[4:7]
	v_mfma_f32_16x16x32_bf16 v[0:3], v[180:183], v[212:215], v[0:3]
	s_barrier
	s_add_i32 s68, 0, 0x18000
	s_add_i32 s69, 0, 0x1c000
	v_add_u32_e32 v164, s68, v152
	v_add_u32_e32 v180, s69, v152
	ds_read_b128 v[146:149], v164
	ds_read_b128 v[156:159], v164 offset:1024
	ds_read_b128 v[160:163], v164 offset:2048
	ds_read_b128 v[164:167], v164 offset:3072
	ds_read_b128 v[168:171], v180
	ds_read_b128 v[172:175], v180 offset:1024
	ds_read_b128 v[176:179], v180 offset:2048
	ds_read_b128 v[180:183], v180 offset:3072
	s_add_u32 s50, s50, 0x40000
	s_addc_u32 s51, s51, 0
	s_mov_b32 m0, s57
	v_lshl_add_u64 v[222:223], s[50:51], 0, v[136:137]
	ds_read_b128 v[184:187], v155 offset:32768
	ds_read_b128 v[188:191], v155 offset:33792
	ds_read_b128 v[192:195], v155 offset:34816
	ds_read_b128 v[196:199], v155 offset:35840
	ds_read_b128 v[200:203], v155 offset:36864
	ds_read_b128 v[204:207], v155 offset:37888
	ds_read_b128 v[208:211], v155 offset:38912
	ds_read_b128 v[212:215], v155 offset:39936
	global_load_lds_dwordx4 v[222:223], off
	v_lshl_add_u64 v[222:223], s[50:51], 0, v[132:133]
	s_mov_b32 m0, s58
	s_nop 0
	global_load_lds_dwordx4 v[222:223], off
	s_waitcnt vmcnt(8)
	s_waitcnt lgkmcnt(0)
	s_barrier
	v_mfma_f32_16x16x32_bf16 v[124:127], v[146:149], v[184:187], v[124:127]
	v_mfma_f32_16x16x32_bf16 v[120:123], v[160:163], v[184:187], v[120:123]
	v_mfma_f32_16x16x32_bf16 v[108:111], v[146:149], v[192:195], v[108:111]
	v_mfma_f32_16x16x32_bf16 v[104:107], v[160:163], v[192:195], v[104:107]
	v_mfma_f32_16x16x32_bf16 v[92:95], v[146:149], v[200:203], v[92:95]
	v_mfma_f32_16x16x32_bf16 v[88:91], v[160:163], v[200:203], v[88:91]
	v_mfma_f32_16x16x32_bf16 v[76:79], v[146:149], v[208:211], v[76:79]
	v_mfma_f32_16x16x32_bf16 v[72:75], v[160:163], v[208:211], v[72:75]
	v_mfma_f32_16x16x32_bf16 v[124:127], v[156:159], v[188:191], v[124:127]
	v_mfma_f32_16x16x32_bf16 v[120:123], v[164:167], v[188:191], v[120:123]
	v_mfma_f32_16x16x32_bf16 v[108:111], v[156:159], v[196:199], v[108:111]
	v_mfma_f32_16x16x32_bf16 v[104:107], v[164:167], v[196:199], v[104:107]
	v_mfma_f32_16x16x32_bf16 v[92:95], v[156:159], v[204:207], v[92:95]
	v_mfma_f32_16x16x32_bf16 v[88:91], v[164:167], v[204:207], v[88:91]
	v_mfma_f32_16x16x32_bf16 v[76:79], v[156:159], v[212:215], v[76:79]
	v_mfma_f32_16x16x32_bf16 v[72:75], v[164:167], v[212:215], v[72:75]
	v_mfma_f32_16x16x32_bf16 v[116:119], v[168:171], v[184:187], v[116:119]
	v_mfma_f32_16x16x32_bf16 v[112:115], v[176:179], v[184:187], v[112:115]
	v_mfma_f32_16x16x32_bf16 v[100:103], v[168:171], v[192:195], v[100:103]
	v_mfma_f32_16x16x32_bf16 v[96:99], v[176:179], v[192:195], v[96:99]
	v_mfma_f32_16x16x32_bf16 v[84:87], v[168:171], v[200:203], v[84:87]
	v_mfma_f32_16x16x32_bf16 v[80:83], v[176:179], v[200:203], v[80:83]
	v_mfma_f32_16x16x32_bf16 v[68:71], v[168:171], v[208:211], v[68:71]
	v_mfma_f32_16x16x32_bf16 v[64:67], v[176:179], v[208:211], v[64:67]
	v_mfma_f32_16x16x32_bf16 v[116:119], v[172:175], v[188:191], v[116:119]
	v_mfma_f32_16x16x32_bf16 v[112:115], v[180:183], v[188:191], v[112:115]
	v_mfma_f32_16x16x32_bf16 v[100:103], v[172:175], v[196:199], v[100:103]
	v_mfma_f32_16x16x32_bf16 v[96:99], v[180:183], v[196:199], v[96:99]
	v_mfma_f32_16x16x32_bf16 v[84:87], v[172:175], v[204:207], v[84:87]
	v_mfma_f32_16x16x32_bf16 v[80:83], v[180:183], v[204:207], v[80:83]
	v_mfma_f32_16x16x32_bf16 v[68:71], v[172:175], v[212:215], v[68:71]
	v_mfma_f32_16x16x32_bf16 v[64:67], v[180:183], v[212:215], v[64:67]
	s_barrier
; #define PG8_STAGE(bufoff, gbase, voff) do { _Pragma("unroll") for (int _i = 0; _i < 2; ++_i) \
;         __builtin_amdgcn_global_load_lds((const unsigned*)((const char*)(gbase) + (voff)[_i]), (LAS unsigned*)(lds + (bufoff) + ldsw + _i * 8192), 16, 0, 0); } while (0)
; #define PG8_LDA(dst, b, h) do { _Pragma("unroll") for (int m = 0; m < 4; ++m) _Pragma("unroll") for (int k = 0; k < 2; ++k) dst[m][k] = *(const LAS bf16x8*)(lds + PG8_SA(b, h) + aoff + m * 2048 + k * 1024); } while (0)
; #define PG8_LDB(dst, b, h) do { _Pragma("unroll") for (int n = 0; n < 2; ++n) _Pragma("unroll") for (int k = 0; k < 2; ++k) dst[n][k] = *(const LAS bf16x8*)(lds + PG8_SB(b, h) + boff + n * 2048 + k * 1024); } while (0)
; #define PG8_WAIT_V(n) asm volatile("s_waitcnt vmcnt(" #n ")" ::: "memory")
; template <class Epi, bool SP2 = false>
; __device__ __forceinline__ void gemm_phase(LAS unsigned char* lds, const Gemm g, const StaticOrder& S, const Epi& E) {
;     ...
;         for (int t = 0; t < nt; t += 2) {
;             const bool last = (t == nt - 2);
;             const char* a1 = cA + (size_t)(t + 1) * kstep;
;             const char* a2 = last ? nA : cA + (size_t)(t + 2) * kstep; const char* b2 = last ? nB : cB + (size_t)(t + 2) * kstep;
;             const char* a3 = a2 + kstep; const char* b3 = b2 + kstep;
;             if constexpr (SP2) {
;             PG8_LDB(B0, 0, 0); PG8_LDB(B1, 0, 1); PG8_SCHED; PG8_LDA(At, 0, 0); PG8_STAGE(PG8_SA(1, 1), a1 + hstepA, voffA);
;             PG8_WAIT_V(8); PG8_WAIT_L(0); PG8_BAR; PG8_MMA(0, 0, At, B0); PG8_MMA(0, 1, At, B1); PG8_BAR; PG8_SCHED;
;             PG8_LDA(At, 0, 1); PG8_STAGE(PG8_SB(0, 0), b2, voffB); PG8_STAGE(PG8_SB(0, 1), b2 + hstepB, voffB); PG8_STAGE(PG8_SA(0, 0), a2, voffA);
;             PG8_WAIT_V(8); PG8_WAIT_L(0); PG8_BAR; PG8_MMA(1, 0, At, B0); PG8_MMA(1, 1, At, B1); PG8_BAR; PG8_SCHED;
;             PG8_LDB(B0, 1, 0); PG8_LDB(B1, 1, 1); PG8_SCHED; PG8_LDA(At, 1, 0); PG8_STAGE(PG8_SA(0, 1), a2 + hstepA, voffA);
;             PG8_WAIT_V(8); PG8_WAIT_L(0); PG8_BAR; PG8_MMA(0, 0, At, B0); PG8_MMA(0, 1, At, B1); PG8_BAR; PG8_SCHED;
;             PG8_LDA(At, 1, 1); PG8_STAGE(PG8_SB(1, 0), b3, voffB); PG8_STAGE(PG8_SB(1, 1), b3 + hstepB, voffB); PG8_STAGE(PG8_SA(1, 0), a3, voffA);
;             PG8_WAIT_V(8); PG8_WAIT_L(0); PG8_BAR; PG8_MMA(1, 0, At, B0); PG8_MMA(1, 1, At, B1); PG8_BAR; PG8_SCHED;
	s_add_i32 s50, s68, s53
	v_lshl_add_u64 v[150:151], v[150:151], 0, s[10:11]
	s_mov_b32 m0, s50
	ds_read_b128 v[184:187], v155 offset:49152
	ds_read_b128 v[188:191], v155 offset:50176
	ds_read_b128 v[192:195], v155 offset:51200
	ds_read_b128 v[196:199], v155 offset:52224
	ds_read_b128 v[200:203], v155 offset:53248
	ds_read_b128 v[204:207], v155 offset:54272
	ds_read_b128 v[208:211], v155 offset:55296
	ds_read_b128 v[212:215], v155 offset:56320
	global_load_lds_dwordx4 v[150:151], off
	s_add_i32 m0, s50, 0x2000
	s_add_u32 s48, s48, 0x40080
	v_lshl_add_u64 v[150:151], v[216:217], 0, s[10:11]
	s_addc_u32 s49, s49, 0
	s_add_i32 s50, s69, s53
	global_load_lds_dwordx4 v[150:151], off
	v_lshl_add_u64 v[150:151], s[48:49], 0, v[134:135]
	s_mov_b32 m0, s50
	s_nop 0
	global_load_lds_dwordx4 v[150:151], off
	v_lshl_add_u64 v[150:151], s[48:49], 0, v[130:131]
	s_add_i32 m0, s50, 0x2000
	s_nop 0
	global_load_lds_dwordx4 v[150:151], off
	v_lshl_add_u64 v[150:151], v[218:219], 0, s[10:11]
	s_mov_b32 m0, s62
	s_nop 0
	global_load_lds_dwordx4 v[150:151], off
	v_lshl_add_u64 v[150:151], v[220:221], 0, s[10:11]
	s_mov_b32 m0, s63
	s_nop 0
	global_load_lds_dwordx4 v[150:151], off
	s_waitcnt vmcnt(8)
	s_waitcnt lgkmcnt(0)
	s_barrier
	v_mfma_f32_16x16x32_bf16 v[60:63], v[146:149], v[184:187], v[60:63]
	v_mfma_f32_16x16x32_bf16 v[56:59], v[160:163], v[184:187], v[56:59]
	v_mfma_f32_16x16x32_bf16 v[44:47], v[146:149], v[192:195], v[44:47]
	v_mfma_f32_16x16x32_bf16 v[40:43], v[160:163], v[192:195], v[40:43]
	v_mfma_f32_16x16x32_bf16 v[28:31], v[146:149], v[200:203], v[28:31]
	v_mfma_f32_16x16x32_bf16 v[24:27], v[160:163], v[200:203], v[24:27]
	v_mfma_f32_16x16x32_bf16 v[12:15], v[146:149], v[208:211], v[12:15]
	v_mfma_f32_16x16x32_bf16 v[8:11], v[160:163], v[208:211], v[8:11]
	v_mfma_f32_16x16x32_bf16 v[60:63], v[156:159], v[188:191], v[60:63]
	v_mfma_f32_16x16x32_bf16 v[56:59], v[164:167], v[188:191], v[56:59]
	v_mfma_f32_16x16x32_bf16 v[44:47], v[156:159], v[196:199], v[44:47]
	v_mfma_f32_16x16x32_bf16 v[40:43], v[164:167], v[196:199], v[40:43]
	v_mfma_f32_16x16x32_bf16 v[28:31], v[156:159], v[204:207], v[28:31]
	v_mfma_f32_16x16x32_bf16 v[24:27], v[164:167], v[204:207], v[24:27]
	v_mfma_f32_16x16x32_bf16 v[12:15], v[156:159], v[212:215], v[12:15]
	v_mfma_f32_16x16x32_bf16 v[8:11], v[164:167], v[212:215], v[8:11]
	v_mfma_f32_16x16x32_bf16 v[52:55], v[168:171], v[184:187], v[52:55]
	v_mfma_f32_16x16x32_bf16 v[48:51], v[176:179], v[184:187], v[48:51]
	v_mfma_f32_16x16x32_bf16 v[36:39], v[168:171], v[192:195], v[36:39]
	v_mfma_f32_16x16x32_bf16 v[32:35], v[176:179], v[192:195], v[32:35]
	v_mfma_f32_16x16x32_bf16 v[20:23], v[168:171], v[200:203], v[20:23]
	v_mfma_f32_16x16x32_bf16 v[16:19], v[176:179], v[200:203], v[16:19]
	v_mfma_f32_16x16x32_bf16 v[4:7], v[168:171], v[208:211], v[4:7]
	v_mfma_f32_16x16x32_bf16 v[0:3], v[176:179], v[208:211], v[0:3]
	v_mfma_f32_16x16x32_bf16 v[52:55], v[172:175], v[188:191], v[52:55]
	v_mfma_f32_16x16x32_bf16 v[48:51], v[180:183], v[188:191], v[48:51]
	v_mfma_f32_16x16x32_bf16 v[36:39], v[172:175], v[196:199], v[36:39]
	v_mfma_f32_16x16x32_bf16 v[32:35], v[180:183], v[196:199], v[32:35]
	v_mfma_f32_16x16x32_bf16 v[20:23], v[172:175], v[204:207], v[20:23]
	v_mfma_f32_16x16x32_bf16 v[16:19], v[180:183], v[204:207], v[16:19]
	v_mfma_f32_16x16x32_bf16 v[4:7], v[172:175], v[212:215], v[4:7]
	v_mfma_f32_16x16x32_bf16 v[0:3], v[180:183], v[212:215], v[0:3]
	s_barrier
	s_add_i32 s80, s80, 2
	s_add_u32 s34, s34, 0x100
	s_addc_u32 s35, s35, 0
	s_add_u32 s78, s78, 0x100
	s_addc_u32 s79, s79, 0
	s_cmp_gt_u32 s80, 13
	s_cbranch_scc0 .LBB0_805
	s_and_b64 vcc, exec, s[12:13]
	s_cbranch_vccz .LBB0_808
	s_barrier

; #define PG8_STAGE(bufoff, gbase, voff) do { _Pragma("unroll") for (int _i = 0; _i < 2; ++_i) \
;         __builtin_amdgcn_global_load_lds((const unsigned*)((const char*)(gbase) + (voff)[_i]), (LAS unsigned*)(lds + (bufoff) + ldsw + _i * 8192), 16, 0, 0); } while (0)
; #define PG8_LDA(dst, b, h) do { _Pragma("unroll") for (int m = 0; m < 4; ++m) _Pragma("unroll") for (int k = 0; k < 2; ++k) dst[m][k] = *(const LAS bf16x8*)(lds + PG8_SA(b, h) + aoff + m * 2048 + k * 1024); } while (0)
; #define PG8_LDB(dst, b, h) do { _Pragma("unroll") for (int n = 0; n < 2; ++n) _Pragma("unroll") for (int k = 0; k < 2; ++k) dst[n][k] = *(const LAS bf16x8*)(lds + PG8_SB(b, h) + boff + n * 2048 + k * 1024); } while (0)
; #define PG8_MMA(ai, bj, At, Bt) do { __builtin_amdgcn_s_setprio(1); _Pragma("unroll") for (int m = 0; m < 4; ++m) _Pragma("unroll") for (int n = 0; n < 2; ++n) _Pragma("unroll") for (int k = 0; k < 2; ++k) \
;         acc[ai][bj][m][n] = __builtin_amdgcn_mfma_f32_16x16x32_bf16(Bt[n][k], At[m][k], acc[ai][bj][m][n], 0, 0, 0); __builtin_amdgcn_s_setprio(0); } while (0)
; #define PG8_WAIT_V(n) asm volatile("s_waitcnt vmcnt(" #n ")" ::: "memory")
; #define PG8_WAIT_L(n) asm volatile("s_waitcnt lgkmcnt(" #n ")" ::: "memory")
; #define PG8_BAR __builtin_amdgcn_s_barrier()
; template <class Epi, bool SP2 = false>
; __device__ __forceinline__ void gemm_phase(LAS unsigned char* lds, const Gemm g, const StaticOrder& S, const Epi& E) {
;     ...
;         for (int t = 0; t < nt; t += 2) {
;             const bool last = (t == nt - 2);
;             const char* a1 = cA + (size_t)(t + 1) * kstep;
;             const char* a2 = last ? nA : cA + (size_t)(t + 2) * kstep; const char* b2 = last ? nB : cB + (size_t)(t + 2) * kstep;
;             const char* a3 = a2 + kstep; const char* b3 = b2 + kstep;
;             if constexpr (SP2) {
;             PG8_LDB(B0, 0, 0); PG8_LDB(B1, 0, 1); PG8_SCHED; PG8_LDA(At, 0, 0); PG8_STAGE(PG8_SA(1, 1), a1 + hstepA, voffA);
;             PG8_WAIT_V(8); PG8_WAIT_L(0); PG8_BAR; PG8_MMA(0, 0, At, B0); PG8_MMA(0, 1, At, B1); PG8_BAR; PG8_SCHED;
;             PG8_LDA(At, 0, 1); PG8_STAGE(PG8_SB(0, 0), b2, voffB); PG8_STAGE(PG8_SB(0, 1), b2 + hstepB, voffB); PG8_STAGE(PG8_SA(0, 0), a2, voffA);
;             PG8_WAIT_V(8); PG8_WAIT_L(0); PG8_BAR; PG8_MMA(1, 0, At, B0); PG8_MMA(1, 1, At, B1); PG8_BAR; PG8_SCHED;
.LBB0_872:
	ds_read_b128 v[146:149], v166
	ds_read_b128 v[170:173], v166 offset:1024
	ds_read_b128 v[174:177], v166 offset:2048
	ds_read_b128 v[178:181], v166 offset:3072
	ds_read_b128 v[182:185], v167
	ds_read_b128 v[186:189], v167 offset:1024
	ds_read_b128 v[190:193], v167 offset:2048
	ds_read_b128 v[194:197], v167 offset:3072
	s_add_u32 s50, s34, 0xfffe0080
	s_addc_u32 s51, s35, -1
	s_cmp_eq_u32 s82, 4
	s_cselect_b32 s53, s45, s51
	s_cselect_b32 s52, s78, s50
	s_cselect_b32 s51, s43, s81
	s_cselect_b32 s50, s79, s80
	v_lshl_add_u64 v[150:151], s[34:35], 0, v[138:139]
	s_add_i32 m0, s31, 0xc000
	ds_read_b128 v[198:201], v168
	ds_read_b128 v[202:205], v168 offset:1024
	ds_read_b128 v[206:209], v168 offset:2048
	ds_read_b128 v[210:213], v168 offset:3072
	ds_read_b128 v[214:217], v168 offset:4096
	ds_read_b128 v[218:221], v168 offset:5120
	ds_read_b128 v[222:225], v168 offset:6144
	ds_read_b128 v[226:229], v168 offset:7168
	global_load_lds_dwordx4 v[150:151], off
	v_lshl_add_u64 v[150:151], s[34:35], 0, v[140:141]
	s_add_i32 m0, s31, 0xe000
	s_nop 0
	global_load_lds_dwordx4 v[150:151], off
	s_waitcnt vmcnt(8)
	s_waitcnt lgkmcnt(0)
	s_barrier
	v_mfma_f32_16x16x32_bf16 v[124:127], v[146:149], v[198:201], v[124:127]
	v_mfma_f32_16x16x32_bf16 v[120:123], v[174:177], v[198:201], v[120:123]
	v_mfma_f32_16x16x32_bf16 v[108:111], v[146:149], v[206:209], v[108:111]
	v_mfma_f32_16x16x32_bf16 v[104:107], v[174:177], v[206:209], v[104:107]
	v_mfma_f32_16x16x32_bf16 v[92:95], v[146:149], v[214:217], v[92:95]
	v_mfma_f32_16x16x32_bf16 v[88:91], v[174:177], v[214:217], v[88:91]
	v_mfma_f32_16x16x32_bf16 v[76:79], v[146:149], v[222:225], v[76:79]
	v_mfma_f32_16x16x32_bf16 v[72:75], v[174:177], v[222:225], v[72:75]
	v_mfma_f32_16x16x32_bf16 v[124:127], v[170:173], v[202:205], v[124:127]
	v_mfma_f32_16x16x32_bf16 v[120:123], v[178:181], v[202:205], v[120:123]
	v_mfma_f32_16x16x32_bf16 v[108:111], v[170:173], v[210:213], v[108:111]
	v_mfma_f32_16x16x32_bf16 v[104:107], v[178:181], v[210:213], v[104:107]
	v_mfma_f32_16x16x32_bf16 v[92:95], v[170:173], v[218:221], v[92:95]
	v_mfma_f32_16x16x32_bf16 v[88:91], v[178:181], v[218:221], v[88:91]
	v_mfma_f32_16x16x32_bf16 v[76:79], v[170:173], v[226:229], v[76:79]
	v_mfma_f32_16x16x32_bf16 v[72:75], v[178:181], v[226:229], v[72:75]
	v_mfma_f32_16x16x32_bf16 v[116:119], v[182:185], v[198:201], v[116:119]
	v_mfma_f32_16x16x32_bf16 v[112:115], v[190:193], v[198:201], v[112:115]
	v_mfma_f32_16x16x32_bf16 v[100:103], v[182:185], v[206:209], v[100:103]
	v_mfma_f32_16x16x32_bf16 v[96:99], v[190:193], v[206:209], v[96:99]
	v_mfma_f32_16x16x32_bf16 v[84:87], v[182:185], v[214:217], v[84:87]
	v_mfma_f32_16x16x32_bf16 v[80:83], v[190:193], v[214:217], v[80:83]
	v_mfma_f32_16x16x32_bf16 v[68:71], v[182:185], v[222:225], v[68:71]
	v_mfma_f32_16x16x32_bf16 v[64:67], v[190:193], v[222:225], v[64:67]
	v_mfma_f32_16x16x32_bf16 v[116:119], v[186:189], v[202:205], v[116:119]
	v_mfma_f32_16x16x32_bf16 v[112:115], v[194:197], v[202:205], v[112:115]
	v_mfma_f32_16x16x32_bf16 v[100:103], v[186:189], v[210:213], v[100:103]
	v_mfma_f32_16x16x32_bf16 v[96:99], v[194:197], v[210:213], v[96:99]
	v_mfma_f32_16x16x32_bf16 v[84:87], v[186:189], v[218:221], v[84:87]
	v_mfma_f32_16x16x32_bf16 v[80:83], v[194:197], v[218:221], v[80:83]
	v_mfma_f32_16x16x32_bf16 v[68:71], v[186:189], v[226:229], v[68:71]
	v_mfma_f32_16x16x32_bf16 v[64:67], v[194:197], v[226:229], v[64:67]
	s_barrier
	s_add_i32 s68, s72, s55
	v_lshl_add_u64 v[150:151], s[50:51], 0, v[134:135]
	s_mov_b32 m0, s68
	ds_read_b128 v[198:201], v168 offset:16384
	ds_read_b128 v[202:205], v168 offset:17408
	ds_read_b128 v[206:209], v168 offset:18432
	ds_read_b128 v[210:213], v168 offset:19456
	ds_read_b128 v[214:217], v168 offset:20480
	ds_read_b128 v[218:221], v168 offset:21504
	ds_read_b128 v[222:225], v168 offset:22528
	ds_read_b128 v[226:229], v168 offset:23552
	global_load_lds_dwordx4 v[150:151], off
	s_add_i32 m0, s68, 0x2000
	s_add_u32 s68, s50, 0x20000
	v_lshl_add_u64 v[230:231], s[50:51], 0, v[130:131]
	s_addc_u32 s69, s51, 0
	s_add_i32 s70, s73, s55
	global_load_lds_dwordx4 v[230:231], off
	v_lshl_add_u64 v[232:233], s[68:69], 0, v[134:135]
	s_mov_b32 m0, s70
	v_lshl_add_u64 v[234:235], s[52:53], 0, v[132:133]
	global_load_lds_dwordx4 v[232:233], off
	v_lshl_add_u64 v[232:233], s[68:69], 0, v[130:131]
	s_add_i32 m0, s70, 0x2000
	s_nop 0
	global_load_lds_dwordx4 v[232:233], off
	v_lshl_add_u64 v[232:233], s[52:53], 0, v[136:137]
	s_mov_b32 m0, s31
	s_nop 0
	global_load_lds_dwordx4 v[232:233], off
	s_mov_b32 m0, s58
	s_nop 0
	global_load_lds_dwordx4 v[234:235], off
	s_waitcnt vmcnt(8)
	s_waitcnt lgkmcnt(0)
	s_barrier
; #define PG8_STAGE(bufoff, gbase, voff) do { _Pragma("unroll") for (int _i = 0; _i < 2; ++_i) \
;         __builtin_amdgcn_global_load_lds((const unsigned*)((const char*)(gbase) + (voff)[_i]), (LAS unsigned*)(lds + (bufoff) + ldsw + _i * 8192), 16, 0, 0); } while (0)
; #define PG8_LDA(dst, b, h) do { _Pragma("unroll") for (int m = 0; m < 4; ++m) _Pragma("unroll") for (int k = 0; k < 2; ++k) dst[m][k] = *(const LAS bf16x8*)(lds + PG8_SA(b, h) + aoff + m * 2048 + k * 1024); } while (0)
; #define PG8_LDB(dst, b, h) do { _Pragma("unroll") for (int n = 0; n < 2; ++n) _Pragma("unroll") for (int k = 0; k < 2; ++k) dst[n][k] = *(const LAS bf16x8*)(lds + PG8_SB(b, h) + boff + n * 2048 + k * 1024); } while (0)
; #define PG8_MMA(ai, bj, At, Bt) do { __builtin_amdgcn_s_setprio(1); _Pragma("unroll") for (int m = 0; m < 4; ++m) _Pragma("unroll") for (int n = 0; n < 2; ++n) _Pragma("unroll") for (int k = 0; k < 2; ++k) \
;         acc[ai][bj][m][n] = __builtin_amdgcn_mfma_f32_16x16x32_bf16(Bt[n][k], At[m][k], acc[ai][bj][m][n], 0, 0, 0); __builtin_amdgcn_s_setprio(0); } while (0)
; #define PG8_WAIT_V(n) asm volatile("s_waitcnt vmcnt(" #n ")" ::: "memory")
; #define PG8_WAIT_L(n) asm volatile("s_waitcnt lgkmcnt(" #n ")" ::: "memory")
; #define PG8_BAR __builtin_amdgcn_s_barrier()
; #define PG8_SCHED __builtin_amdgcn_sched_barrier(0)
; template <class Epi, bool SP2 = false>
; __device__ __forceinline__ void gemm_phase(LAS unsigned char* lds, const Gemm g, const StaticOrder& S, const Epi& E) {
;     ...
;             PG8_WAIT_V(8); PG8_WAIT_L(0); PG8_BAR; PG8_MMA(1, 0, At, B0); PG8_MMA(1, 1, At, B1); PG8_BAR; PG8_SCHED;
;             PG8_LDB(B0, 1, 0); PG8_LDB(B1, 1, 1); PG8_SCHED; PG8_LDA(At, 1, 0); PG8_STAGE(PG8_SA(0, 1), a2 + hstepA, voffA);
;             PG8_WAIT_V(8); PG8_WAIT_L(0); PG8_BAR; PG8_MMA(0, 0, At, B0); PG8_MMA(0, 1, At, B1); PG8_BAR; PG8_SCHED;
	v_mfma_f32_16x16x32_bf16 v[60:63], v[146:149], v[198:201], v[60:63]
	v_mfma_f32_16x16x32_bf16 v[56:59], v[174:177], v[198:201], v[56:59]
	v_mfma_f32_16x16x32_bf16 v[44:47], v[146:149], v[206:209], v[44:47]
	v_mfma_f32_16x16x32_bf16 v[40:43], v[174:177], v[206:209], v[40:43]
	v_mfma_f32_16x16x32_bf16 v[28:31], v[146:149], v[214:217], v[28:31]
	v_mfma_f32_16x16x32_bf16 v[24:27], v[174:177], v[214:217], v[24:27]
	v_mfma_f32_16x16x32_bf16 v[12:15], v[146:149], v[222:225], v[12:15]
	v_mfma_f32_16x16x32_bf16 v[8:11], v[174:177], v[222:225], v[8:11]
	v_mfma_f32_16x16x32_bf16 v[60:63], v[170:173], v[202:205], v[60:63]
	v_mfma_f32_16x16x32_bf16 v[56:59], v[178:181], v[202:205], v[56:59]
	v_mfma_f32_16x16x32_bf16 v[44:47], v[170:173], v[210:213], v[44:47]
	v_mfma_f32_16x16x32_bf16 v[40:43], v[178:181], v[210:213], v[40:43]
	v_mfma_f32_16x16x32_bf16 v[28:31], v[170:173], v[218:221], v[28:31]
	v_mfma_f32_16x16x32_bf16 v[24:27], v[178:181], v[218:221], v[24:27]
	v_mfma_f32_16x16x32_bf16 v[12:15], v[170:173], v[226:229], v[12:15]
	v_mfma_f32_16x16x32_bf16 v[8:11], v[178:181], v[226:229], v[8:11]
	v_mfma_f32_16x16x32_bf16 v[52:55], v[182:185], v[198:201], v[52:55]
	v_mfma_f32_16x16x32_bf16 v[48:51], v[190:193], v[198:201], v[48:51]
	v_mfma_f32_16x16x32_bf16 v[36:39], v[182:185], v[206:209], v[36:39]
	v_mfma_f32_16x16x32_bf16 v[32:35], v[190:193], v[206:209], v[32:35]
	v_mfma_f32_16x16x32_bf16 v[20:23], v[182:185], v[214:217], v[20:23]
	v_mfma_f32_16x16x32_bf16 v[16:19], v[190:193], v[214:217], v[16:19]
	v_mfma_f32_16x16x32_bf16 v[4:7], v[182:185], v[222:225], v[4:7]
	v_mfma_f32_16x16x32_bf16 v[0:3], v[190:193], v[222:225], v[0:3]
	v_mfma_f32_16x16x32_bf16 v[52:55], v[186:189], v[202:205], v[52:55]
	v_mfma_f32_16x16x32_bf16 v[48:51], v[194:197], v[202:205], v[48:51]
	v_mfma_f32_16x16x32_bf16 v[36:39], v[186:189], v[210:213], v[36:39]
	v_mfma_f32_16x16x32_bf16 v[32:35], v[194:197], v[210:213], v[32:35]
	v_mfma_f32_16x16x32_bf16 v[20:23], v[186:189], v[218:221], v[20:23]
	v_mfma_f32_16x16x32_bf16 v[16:19], v[194:197], v[218:221], v[16:19]
	v_mfma_f32_16x16x32_bf16 v[4:7], v[186:189], v[226:229], v[4:7]
	v_mfma_f32_16x16x32_bf16 v[0:3], v[194:197], v[226:229], v[0:3]
	s_barrier
	s_add_i32 s68, 0, 0x18000
	v_add_u32_e32 v169, s68, v165
	s_add_i32 s69, 0, 0x1c000
	ds_read_b128 v[146:149], v169
	ds_read_b128 v[170:173], v169 offset:1024
	ds_read_b128 v[174:177], v169 offset:2048
	ds_read_b128 v[178:181], v169 offset:3072
	v_add_u32_e32 v169, s69, v165
	ds_read_b128 v[182:185], v169
	ds_read_b128 v[186:189], v169 offset:1024
	ds_read_b128 v[190:193], v169 offset:2048
	ds_read_b128 v[194:197], v169 offset:3072
	s_add_u32 s52, s52, 0x20000
	s_addc_u32 s53, s53, 0
	s_mov_b32 m0, s59
	v_lshl_add_u64 v[236:237], s[52:53], 0, v[136:137]
	ds_read_b128 v[198:201], v168 offset:32768
	ds_read_b128 v[202:205], v168 offset:33792
	ds_read_b128 v[206:209], v168 offset:34816
	ds_read_b128 v[210:213], v168 offset:35840
	ds_read_b128 v[214:217], v168 offset:36864
	ds_read_b128 v[218:221], v168 offset:37888
	ds_read_b128 v[222:225], v168 offset:38912
	ds_read_b128 v[226:229], v168 offset:39936
	global_load_lds_dwordx4 v[236:237], off
	v_lshl_add_u64 v[236:237], s[52:53], 0, v[132:133]
	s_mov_b32 m0, s60
	s_nop 0
	global_load_lds_dwordx4 v[236:237], off
	s_waitcnt vmcnt(8)
	s_waitcnt lgkmcnt(0)
	s_barrier
	v_mfma_f32_16x16x32_bf16 v[124:127], v[146:149], v[198:201], v[124:127]
	v_mfma_f32_16x16x32_bf16 v[120:123], v[174:177], v[198:201], v[120:123]
	v_mfma_f32_16x16x32_bf16 v[108:111], v[146:149], v[206:209], v[108:111]
	v_mfma_f32_16x16x32_bf16 v[104:107], v[174:177], v[206:209], v[104:107]
	v_mfma_f32_16x16x32_bf16 v[92:95], v[146:149], v[214:217], v[92:95]
	v_mfma_f32_16x16x32_bf16 v[88:91], v[174:177], v[214:217], v[88:91]
	v_mfma_f32_16x16x32_bf16 v[76:79], v[146:149], v[222:225], v[76:79]
	v_mfma_f32_16x16x32_bf16 v[72:75], v[174:177], v[222:225], v[72:75]
	v_mfma_f32_16x16x32_bf16 v[124:127], v[170:173], v[202:205], v[124:127]
	v_mfma_f32_16x16x32_bf16 v[120:123], v[178:181], v[202:205], v[120:123]
	v_mfma_f32_16x16x32_bf16 v[108:111], v[170:173], v[210:213], v[108:111]
	v_mfma_f32_16x16x32_bf16 v[104:107], v[178:181], v[210:213], v[104:107]
	v_mfma_f32_16x16x32_bf16 v[92:95], v[170:173], v[218:221], v[92:95]
	v_mfma_f32_16x16x32_bf16 v[88:91], v[178:181], v[218:221], v[88:91]
	v_mfma_f32_16x16x32_bf16 v[76:79], v[170:173], v[226:229], v[76:79]
	v_mfma_f32_16x16x32_bf16 v[72:75], v[178:181], v[226:229], v[72:75]
	v_mfma_f32_16x16x32_bf16 v[116:119], v[182:185], v[198:201], v[116:119]
	v_mfma_f32_16x16x32_bf16 v[112:115], v[190:193], v[198:201], v[112:115]
	v_mfma_f32_16x16x32_bf16 v[100:103], v[182:185], v[206:209], v[100:103]
	v_mfma_f32_16x16x32_bf16 v[96:99], v[190:193], v[206:209], v[96:99]
	v_mfma_f32_16x16x32_bf16 v[84:87], v[182:185], v[214:217], v[84:87]
	v_mfma_f32_16x16x32_bf16 v[80:83], v[190:193], v[214:217], v[80:83]
	v_mfma_f32_16x16x32_bf16 v[68:71], v[182:185], v[222:225], v[68:71]
	v_mfma_f32_16x16x32_bf16 v[64:67], v[190:193], v[222:225], v[64:67]
	v_mfma_f32_16x16x32_bf16 v[116:119], v[186:189], v[202:205], v[116:119]
	v_mfma_f32_16x16x32_bf16 v[112:115], v[194:197], v[202:205], v[112:115]
	v_mfma_f32_16x16x32_bf16 v[100:103], v[186:189], v[210:213], v[100:103]
	v_mfma_f32_16x16x32_bf16 v[96:99], v[194:197], v[210:213], v[96:99]
	v_mfma_f32_16x16x32_bf16 v[84:87], v[186:189], v[218:221], v[84:87]
	v_mfma_f32_16x16x32_bf16 v[80:83], v[194:197], v[218:221], v[80:83]
	v_mfma_f32_16x16x32_bf16 v[68:71], v[186:189], v[226:229], v[68:71]
	v_mfma_f32_16x16x32_bf16 v[64:67], v[194:197], v[226:229], v[64:67]
	s_barrier
; #define PG8_STAGE(bufoff, gbase, voff) do { _Pragma("unroll") for (int _i = 0; _i < 2; ++_i) \
;         __builtin_amdgcn_global_load_lds((const unsigned*)((const char*)(gbase) + (voff)[_i]), (LAS unsigned*)(lds + (bufoff) + ldsw + _i * 8192), 16, 0, 0); } while (0)
; #define PG8_LDA(dst, b, h) do { _Pragma("unroll") for (int m = 0; m < 4; ++m) _Pragma("unroll") for (int k = 0; k < 2; ++k) dst[m][k] = *(const LAS bf16x8*)(lds + PG8_SA(b, h) + aoff + m * 2048 + k * 1024); } while (0)
; #define PG8_MMA(ai, bj, At, Bt) do { __builtin_amdgcn_s_setprio(1); _Pragma("unroll") for (int m = 0; m < 4; ++m) _Pragma("unroll") for (int n = 0; n < 2; ++n) _Pragma("unroll") for (int k = 0; k < 2; ++k) \
;         acc[ai][bj][m][n] = __builtin_amdgcn_mfma_f32_16x16x32_bf16(Bt[n][k], At[m][k], acc[ai][bj][m][n], 0, 0, 0); __builtin_amdgcn_s_setprio(0); } while (0)
; #define PG8_WAIT_V(n) asm volatile("s_waitcnt vmcnt(" #n ")" ::: "memory")
; #define PG8_WAIT_L(n) asm volatile("s_waitcnt lgkmcnt(" #n ")" ::: "memory")
; #define PG8_BAR __builtin_amdgcn_s_barrier()
; #define PG8_SCHED __builtin_amdgcn_sched_barrier(0)
; template <class Epi, bool SP2 = false>
; __device__ __forceinline__ void gemm_phase(LAS unsigned char* lds, const Gemm g, const StaticOrder& S, const Epi& E) {
;     ...
;             PG8_LDA(At, 1, 1); PG8_STAGE(PG8_SB(1, 0), b3, voffB); PG8_STAGE(PG8_SB(1, 1), b3 + hstepB, voffB); PG8_STAGE(PG8_SA(1, 0), a3, voffA);
;             PG8_WAIT_V(8); PG8_WAIT_L(0); PG8_BAR; PG8_MMA(1, 0, At, B0); PG8_MMA(1, 1, At, B1); PG8_BAR; PG8_SCHED;
;     ...
;         if constexpr (SP2) { if (wr == 0) PG8_BAR; }
	s_add_i32 s52, s68, s55
	v_lshl_add_u64 v[150:151], v[150:151], 0, s[10:11]
	s_mov_b32 m0, s52
	ds_read_b128 v[198:201], v168 offset:49152
	ds_read_b128 v[202:205], v168 offset:50176
	ds_read_b128 v[206:209], v168 offset:51200
	ds_read_b128 v[210:213], v168 offset:52224
	ds_read_b128 v[214:217], v168 offset:53248
	ds_read_b128 v[218:221], v168 offset:54272
	ds_read_b128 v[222:225], v168 offset:55296
	ds_read_b128 v[226:229], v168 offset:56320
	global_load_lds_dwordx4 v[150:151], off
	s_add_i32 m0, s52, 0x2000
	s_add_u32 s50, s50, 0x20080
	v_lshl_add_u64 v[150:151], v[230:231], 0, s[10:11]
	s_addc_u32 s51, s51, 0
	s_add_i32 s52, s69, s55
	global_load_lds_dwordx4 v[150:151], off
	v_lshl_add_u64 v[150:151], s[50:51], 0, v[134:135]
	s_mov_b32 m0, s52
	s_nop 0
	global_load_lds_dwordx4 v[150:151], off
	v_lshl_add_u64 v[150:151], s[50:51], 0, v[130:131]
	s_add_i32 m0, s52, 0x2000
	s_nop 0
	global_load_lds_dwordx4 v[150:151], off
	v_lshl_add_u64 v[150:151], v[232:233], 0, s[10:11]
	s_mov_b32 m0, s64
	s_nop 0
	global_load_lds_dwordx4 v[150:151], off
	v_lshl_add_u64 v[150:151], v[234:235], 0, s[10:11]
	s_mov_b32 m0, s65
	s_nop 0
	global_load_lds_dwordx4 v[150:151], off
	s_waitcnt vmcnt(8)
	s_waitcnt lgkmcnt(0)
	s_barrier
	v_mfma_f32_16x16x32_bf16 v[60:63], v[146:149], v[198:201], v[60:63]
	v_mfma_f32_16x16x32_bf16 v[56:59], v[174:177], v[198:201], v[56:59]
	v_mfma_f32_16x16x32_bf16 v[44:47], v[146:149], v[206:209], v[44:47]
	v_mfma_f32_16x16x32_bf16 v[40:43], v[174:177], v[206:209], v[40:43]
	v_mfma_f32_16x16x32_bf16 v[28:31], v[146:149], v[214:217], v[28:31]
	v_mfma_f32_16x16x32_bf16 v[24:27], v[174:177], v[214:217], v[24:27]
	v_mfma_f32_16x16x32_bf16 v[12:15], v[146:149], v[222:225], v[12:15]
	v_mfma_f32_16x16x32_bf16 v[8:11], v[174:177], v[222:225], v[8:11]
	v_mfma_f32_16x16x32_bf16 v[60:63], v[170:173], v[202:205], v[60:63]
	v_mfma_f32_16x16x32_bf16 v[56:59], v[178:181], v[202:205], v[56:59]
	v_mfma_f32_16x16x32_bf16 v[44:47], v[170:173], v[210:213], v[44:47]
	v_mfma_f32_16x16x32_bf16 v[40:43], v[178:181], v[210:213], v[40:43]
	v_mfma_f32_16x16x32_bf16 v[28:31], v[170:173], v[218:221], v[28:31]
	v_mfma_f32_16x16x32_bf16 v[24:27], v[178:181], v[218:221], v[24:27]
	v_mfma_f32_16x16x32_bf16 v[12:15], v[170:173], v[226:229], v[12:15]
	v_mfma_f32_16x16x32_bf16 v[8:11], v[178:181], v[226:229], v[8:11]
	v_mfma_f32_16x16x32_bf16 v[52:55], v[182:185], v[198:201], v[52:55]
	v_mfma_f32_16x16x32_bf16 v[48:51], v[190:193], v[198:201], v[48:51]
	v_mfma_f32_16x16x32_bf16 v[36:39], v[182:185], v[206:209], v[36:39]
	v_mfma_f32_16x16x32_bf16 v[32:35], v[190:193], v[206:209], v[32:35]
	v_mfma_f32_16x16x32_bf16 v[20:23], v[182:185], v[214:217], v[20:23]
	v_mfma_f32_16x16x32_bf16 v[16:19], v[190:193], v[214:217], v[16:19]
	v_mfma_f32_16x16x32_bf16 v[4:7], v[182:185], v[222:225], v[4:7]
	v_mfma_f32_16x16x32_bf16 v[0:3], v[190:193], v[222:225], v[0:3]
	v_mfma_f32_16x16x32_bf16 v[52:55], v[186:189], v[202:205], v[52:55]
	v_mfma_f32_16x16x32_bf16 v[48:51], v[194:197], v[202:205], v[48:51]
	v_mfma_f32_16x16x32_bf16 v[36:39], v[186:189], v[210:213], v[36:39]
	v_mfma_f32_16x16x32_bf16 v[32:35], v[194:197], v[210:213], v[32:35]
	v_mfma_f32_16x16x32_bf16 v[20:23], v[186:189], v[218:221], v[20:23]
	v_mfma_f32_16x16x32_bf16 v[16:19], v[194:197], v[218:221], v[16:19]
	v_mfma_f32_16x16x32_bf16 v[4:7], v[186:189], v[226:229], v[4:7]
	v_mfma_f32_16x16x32_bf16 v[0:3], v[194:197], v[226:229], v[0:3]
	s_barrier
	s_add_i32 s82, s82, 2
	s_add_u32 s34, s34, 0x100
	s_addc_u32 s35, s35, 0
	s_add_u32 s80, s80, 0x100
	s_addc_u32 s81, s81, 0
	s_cmp_gt_u32 s82, 5
	s_cbranch_scc0 .LBB0_872
	s_and_b64 vcc, exec, s[12:13]
	s_cbranch_vccz .LBB0_875
	s_barrier

; #define PG8_STAGE(bufoff, gbase, voff) do { _Pragma("unroll") for (int _i = 0; _i < 2; ++_i) \
;         __builtin_amdgcn_global_load_lds((const unsigned*)((const char*)(gbase) + (voff)[_i]), (LAS unsigned*)(lds + (bufoff) + ldsw + _i * 8192), 16, 0, 0); } while (0)
; #define PG8_LDA(dst, b, h) do { _Pragma("unroll") for (int m = 0; m < 4; ++m) _Pragma("unroll") for (int k = 0; k < 2; ++k) dst[m][k] = *(const LAS bf16x8*)(lds + PG8_SA(b, h) + aoff + m * 2048 + k * 1024); } while (0)
; #define PG8_LDB(dst, b, h) do { _Pragma("unroll") for (int n = 0; n < 2; ++n) _Pragma("unroll") for (int k = 0; k < 2; ++k) dst[n][k] = *(const LAS bf16x8*)(lds + PG8_SB(b, h) + boff + n * 2048 + k * 1024); } while (0)
; #define PG8_MMA(ai, bj, At, Bt) do { __builtin_amdgcn_s_setprio(1); _Pragma("unroll") for (int m = 0; m < 4; ++m) _Pragma("unroll") for (int n = 0; n < 2; ++n) _Pragma("unroll") for (int k = 0; k < 2; ++k) \
;         acc[ai][bj][m][n] = __builtin_amdgcn_mfma_f32_16x16x32_bf16(Bt[n][k], At[m][k], acc[ai][bj][m][n], 0, 0, 0); __builtin_amdgcn_s_setprio(0); } while (0)
; #define PG8_WAIT_V(n) asm volatile("s_waitcnt vmcnt(" #n ")" ::: "memory")
; #define PG8_WAIT_L(n) asm volatile("s_waitcnt lgkmcnt(" #n ")" ::: "memory")
; #define PG8_BAR __builtin_amdgcn_s_barrier()
; #define PG8_SCHED __builtin_amdgcn_sched_barrier(0)
; template <class Epi, bool SP2 = false>
; __device__ __forceinline__ void gemm_phase(LAS unsigned char* lds, const Gemm g, const StaticOrder& S, const Epi& E) {
;     ...
;             const bool last = (t == nt - 2);
;             const char* a1 = cA + (size_t)(t + 1) * kstep;
;             const char* a2 = last ? nA : cA + (size_t)(t + 2) * kstep; const char* b2 = last ? nB : cB + (size_t)(t + 2) * kstep;
;             const char* a3 = a2 + kstep; const char* b3 = b2 + kstep;
;             if constexpr (SP2) {
;             PG8_LDB(B0, 0, 0); PG8_LDB(B1, 0, 1); PG8_SCHED; PG8_LDA(At, 0, 0); PG8_STAGE(PG8_SA(1, 1), a1 + hstepA, voffA);
;             PG8_WAIT_V(8); PG8_WAIT_L(0); PG8_BAR; PG8_MMA(0, 0, At, B0); PG8_MMA(0, 1, At, B1); PG8_BAR; PG8_SCHED;
;             PG8_LDA(At, 0, 1); PG8_STAGE(PG8_SB(0, 0), b2, voffB); PG8_STAGE(PG8_SB(0, 1), b2 + hstepB, voffB); PG8_STAGE(PG8_SA(0, 0), a2, voffA);
;             PG8_WAIT_V(8); PG8_WAIT_L(0); PG8_BAR; PG8_MMA(1, 0, At, B0); PG8_MMA(1, 1, At, B1); PG8_BAR; PG8_SCHED;
.LBB0_888:
	ds_read_b128 v[146:149], v152
	ds_read_b128 v[156:159], v152 offset:1024
	ds_read_b128 v[160:163], v152 offset:2048
	ds_read_b128 v[164:167], v152 offset:3072
	ds_read_b128 v[168:171], v153
	ds_read_b128 v[172:175], v153 offset:1024
	ds_read_b128 v[176:179], v153 offset:2048
	ds_read_b128 v[180:183], v153 offset:3072
	s_add_u32 s48, s34, 0xfffc0080
	s_addc_u32 s49, s35, -1
	s_cmp_eq_u32 s76, 12
	s_cselect_b32 s51, s43, s49
	s_cselect_b32 s50, s72, s48
	s_cselect_b32 s49, s41, s75
	s_cselect_b32 s48, s73, s74
	v_lshl_add_u64 v[150:151], s[34:35], 0, v[138:139]
	s_add_i32 m0, s31, 0xc000
	ds_read_b128 v[184:187], v155
	ds_read_b128 v[188:191], v155 offset:1024
	ds_read_b128 v[192:195], v155 offset:2048
	ds_read_b128 v[196:199], v155 offset:3072
	ds_read_b128 v[200:203], v155 offset:4096
	ds_read_b128 v[204:207], v155 offset:5120
	ds_read_b128 v[208:211], v155 offset:6144
	ds_read_b128 v[212:215], v155 offset:7168
	global_load_lds_dwordx4 v[150:151], off
	v_lshl_add_u64 v[150:151], s[34:35], 0, v[140:141]
	s_add_i32 m0, s31, 0xe000
	s_nop 0
	global_load_lds_dwordx4 v[150:151], off
	s_waitcnt vmcnt(8)
	s_waitcnt lgkmcnt(0)
	s_barrier
	v_mfma_f32_16x16x32_bf16 v[124:127], v[146:149], v[184:187], v[124:127]
	v_mfma_f32_16x16x32_bf16 v[120:123], v[160:163], v[184:187], v[120:123]
	v_mfma_f32_16x16x32_bf16 v[108:111], v[146:149], v[192:195], v[108:111]
	v_mfma_f32_16x16x32_bf16 v[104:107], v[160:163], v[192:195], v[104:107]
	v_mfma_f32_16x16x32_bf16 v[92:95], v[146:149], v[200:203], v[92:95]
	v_mfma_f32_16x16x32_bf16 v[88:91], v[160:163], v[200:203], v[88:91]
	v_mfma_f32_16x16x32_bf16 v[76:79], v[146:149], v[208:211], v[76:79]
	v_mfma_f32_16x16x32_bf16 v[72:75], v[160:163], v[208:211], v[72:75]
	v_mfma_f32_16x16x32_bf16 v[124:127], v[156:159], v[188:191], v[124:127]
	v_mfma_f32_16x16x32_bf16 v[120:123], v[164:167], v[188:191], v[120:123]
	v_mfma_f32_16x16x32_bf16 v[108:111], v[156:159], v[196:199], v[108:111]
	v_mfma_f32_16x16x32_bf16 v[104:107], v[164:167], v[196:199], v[104:107]
	v_mfma_f32_16x16x32_bf16 v[92:95], v[156:159], v[204:207], v[92:95]
	v_mfma_f32_16x16x32_bf16 v[88:91], v[164:167], v[204:207], v[88:91]
	v_mfma_f32_16x16x32_bf16 v[76:79], v[156:159], v[212:215], v[76:79]
	v_mfma_f32_16x16x32_bf16 v[72:75], v[164:167], v[212:215], v[72:75]
	v_mfma_f32_16x16x32_bf16 v[116:119], v[168:171], v[184:187], v[116:119]
	v_mfma_f32_16x16x32_bf16 v[112:115], v[176:179], v[184:187], v[112:115]
	v_mfma_f32_16x16x32_bf16 v[100:103], v[168:171], v[192:195], v[100:103]
	v_mfma_f32_16x16x32_bf16 v[96:99], v[176:179], v[192:195], v[96:99]
	v_mfma_f32_16x16x32_bf16 v[84:87], v[168:171], v[200:203], v[84:87]
	v_mfma_f32_16x16x32_bf16 v[80:83], v[176:179], v[200:203], v[80:83]
	v_mfma_f32_16x16x32_bf16 v[68:71], v[168:171], v[208:211], v[68:71]
	v_mfma_f32_16x16x32_bf16 v[64:67], v[176:179], v[208:211], v[64:67]
	v_mfma_f32_16x16x32_bf16 v[116:119], v[172:175], v[188:191], v[116:119]
	v_mfma_f32_16x16x32_bf16 v[112:115], v[180:183], v[188:191], v[112:115]
	v_mfma_f32_16x16x32_bf16 v[100:103], v[172:175], v[196:199], v[100:103]
	v_mfma_f32_16x16x32_bf16 v[96:99], v[180:183], v[196:199], v[96:99]
	v_mfma_f32_16x16x32_bf16 v[84:87], v[172:175], v[204:207], v[84:87]
	v_mfma_f32_16x16x32_bf16 v[80:83], v[180:183], v[204:207], v[80:83]
	v_mfma_f32_16x16x32_bf16 v[68:71], v[172:175], v[212:215], v[68:71]
	v_mfma_f32_16x16x32_bf16 v[64:67], v[180:183], v[212:215], v[64:67]
	s_barrier
	s_add_i32 s68, s66, s53
	v_lshl_add_u64 v[150:151], s[48:49], 0, v[134:135]
	s_mov_b32 m0, s68
	ds_read_b128 v[184:187], v155 offset:16384
	ds_read_b128 v[188:191], v155 offset:17408
	ds_read_b128 v[192:195], v155 offset:18432
	ds_read_b128 v[196:199], v155 offset:19456
	ds_read_b128 v[200:203], v155 offset:20480
	ds_read_b128 v[204:207], v155 offset:21504
	ds_read_b128 v[208:211], v155 offset:22528
	ds_read_b128 v[212:215], v155 offset:23552
	global_load_lds_dwordx4 v[150:151], off
	s_add_i32 m0, s68, 0x2000
	s_add_u32 s68, s48, 0x40000
	v_lshl_add_u64 v[216:217], s[48:49], 0, v[130:131]
	s_addc_u32 s69, s49, 0
	s_add_i32 s70, s67, s53
	global_load_lds_dwordx4 v[216:217], off
	v_lshl_add_u64 v[218:219], s[68:69], 0, v[134:135]
	s_mov_b32 m0, s70
	v_lshl_add_u64 v[220:221], s[50:51], 0, v[132:133]
	global_load_lds_dwordx4 v[218:219], off
	v_lshl_add_u64 v[218:219], s[68:69], 0, v[130:131]
	s_add_i32 m0, s70, 0x2000
	s_nop 0
	global_load_lds_dwordx4 v[218:219], off
	v_lshl_add_u64 v[218:219], s[50:51], 0, v[136:137]
	s_mov_b32 m0, s31
	s_nop 0
	global_load_lds_dwordx4 v[218:219], off
	s_mov_b32 m0, s56
	s_nop 0
	global_load_lds_dwordx4 v[220:221], off
	s_waitcnt vmcnt(8)
	s_waitcnt lgkmcnt(0)
	s_barrier
; #define PG8_STAGE(bufoff, gbase, voff) do { _Pragma("unroll") for (int _i = 0; _i < 2; ++_i) \
;         __builtin_amdgcn_global_load_lds((const unsigned*)((const char*)(gbase) + (voff)[_i]), (LAS unsigned*)(lds + (bufoff) + ldsw + _i * 8192), 16, 0, 0); } while (0)
; #define PG8_LDA(dst, b, h) do { _Pragma("unroll") for (int m = 0; m < 4; ++m) _Pragma("unroll") for (int k = 0; k < 2; ++k) dst[m][k] = *(const LAS bf16x8*)(lds + PG8_SA(b, h) + aoff + m * 2048 + k * 1024); } while (0)
; #define PG8_LDB(dst, b, h) do { _Pragma("unroll") for (int n = 0; n < 2; ++n) _Pragma("unroll") for (int k = 0; k < 2; ++k) dst[n][k] = *(const LAS bf16x8*)(lds + PG8_SB(b, h) + boff + n * 2048 + k * 1024); } while (0)
; #define PG8_MMA(ai, bj, At, Bt) do { __builtin_amdgcn_s_setprio(1); _Pragma("unroll") for (int m = 0; m < 4; ++m) _Pragma("unroll") for (int n = 0; n < 2; ++n) _Pragma("unroll") for (int k = 0; k < 2; ++k) \
;         acc[ai][bj][m][n] = __builtin_amdgcn_mfma_f32_16x16x32_bf16(Bt[n][k], At[m][k], acc[ai][bj][m][n], 0, 0, 0); __builtin_amdgcn_s_setprio(0); } while (0)
; #define PG8_WAIT_V(n) asm volatile("s_waitcnt vmcnt(" #n ")" ::: "memory")
; #define PG8_WAIT_L(n) asm volatile("s_waitcnt lgkmcnt(" #n ")" ::: "memory")
; #define PG8_BAR __builtin_amdgcn_s_barrier()
; #define PG8_SCHED __builtin_amdgcn_sched_barrier(0)
; template <class Epi, bool SP2 = false>
; __device__ __forceinline__ void gemm_phase(LAS unsigned char* lds, const Gemm g, const StaticOrder& S, const Epi& E) {
;     ...
;             PG8_WAIT_V(8); PG8_WAIT_L(0); PG8_BAR; PG8_MMA(1, 0, At, B0); PG8_MMA(1, 1, At, B1); PG8_BAR; PG8_SCHED;
;             PG8_LDB(B0, 1, 0); PG8_LDB(B1, 1, 1); PG8_SCHED; PG8_LDA(At, 1, 0); PG8_STAGE(PG8_SA(0, 1), a2 + hstepA, voffA);
;             PG8_WAIT_V(8); PG8_WAIT_L(0); PG8_BAR; PG8_MMA(0, 0, At, B0); PG8_MMA(0, 1, At, B1); PG8_BAR; PG8_SCHED;
	v_mfma_f32_16x16x32_bf16 v[60:63], v[146:149], v[184:187], v[60:63]
	v_mfma_f32_16x16x32_bf16 v[56:59], v[160:163], v[184:187], v[56:59]
	v_mfma_f32_16x16x32_bf16 v[44:47], v[146:149], v[192:195], v[44:47]
	v_mfma_f32_16x16x32_bf16 v[40:43], v[160:163], v[192:195], v[40:43]
	v_mfma_f32_16x16x32_bf16 v[28:31], v[146:149], v[200:203], v[28:31]
	v_mfma_f32_16x16x32_bf16 v[24:27], v[160:163], v[200:203], v[24:27]
	v_mfma_f32_16x16x32_bf16 v[12:15], v[146:149], v[208:211], v[12:15]
	v_mfma_f32_16x16x32_bf16 v[8:11], v[160:163], v[208:211], v[8:11]
	v_mfma_f32_16x16x32_bf16 v[60:63], v[156:159], v[188:191], v[60:63]
	v_mfma_f32_16x16x32_bf16 v[56:59], v[164:167], v[188:191], v[56:59]
	v_mfma_f32_16x16x32_bf16 v[44:47], v[156:159], v[196:199], v[44:47]
	v_mfma_f32_16x16x32_bf16 v[40:43], v[164:167], v[196:199], v[40:43]
	v_mfma_f32_16x16x32_bf16 v[28:31], v[156:159], v[204:207], v[28:31]
	v_mfma_f32_16x16x32_bf16 v[24:27], v[164:167], v[204:207], v[24:27]
	v_mfma_f32_16x16x32_bf16 v[12:15], v[156:159], v[212:215], v[12:15]
	v_mfma_f32_16x16x32_bf16 v[8:11], v[164:167], v[212:215], v[8:11]
	v_mfma_f32_16x16x32_bf16 v[52:55], v[168:171], v[184:187], v[52:55]
	v_mfma_f32_16x16x32_bf16 v[48:51], v[176:179], v[184:187], v[48:51]
	v_mfma_f32_16x16x32_bf16 v[36:39], v[168:171], v[192:195], v[36:39]
	v_mfma_f32_16x16x32_bf16 v[32:35], v[176:179], v[192:195], v[32:35]
	v_mfma_f32_16x16x32_bf16 v[20:23], v[168:171], v[200:203], v[20:23]
	v_mfma_f32_16x16x32_bf16 v[16:19], v[176:179], v[200:203], v[16:19]
	v_mfma_f32_16x16x32_bf16 v[4:7], v[168:171], v[208:211], v[4:7]
	v_mfma_f32_16x16x32_bf16 v[0:3], v[176:179], v[208:211], v[0:3]
	v_mfma_f32_16x16x32_bf16 v[52:55], v[172:175], v[188:191], v[52:55]
	v_mfma_f32_16x16x32_bf16 v[48:51], v[180:183], v[188:191], v[48:51]
	v_mfma_f32_16x16x32_bf16 v[36:39], v[172:175], v[196:199], v[36:39]
	v_mfma_f32_16x16x32_bf16 v[32:35], v[180:183], v[196:199], v[32:35]
	v_mfma_f32_16x16x32_bf16 v[20:23], v[172:175], v[204:207], v[20:23]
	v_mfma_f32_16x16x32_bf16 v[16:19], v[180:183], v[204:207], v[16:19]
	v_mfma_f32_16x16x32_bf16 v[4:7], v[172:175], v[212:215], v[4:7]
	v_mfma_f32_16x16x32_bf16 v[0:3], v[180:183], v[212:215], v[0:3]
	s_barrier
	s_add_i32 s68, 0, 0x18000
	s_add_i32 s69, 0, 0x1c000
	v_add_u32_e32 v164, s68, v154
	v_add_u32_e32 v180, s69, v154
	ds_read_b128 v[146:149], v164
	ds_read_b128 v[156:159], v164 offset:1024
	ds_read_b128 v[160:163], v164 offset:2048
	ds_read_b128 v[164:167], v164 offset:3072
	ds_read_b128 v[168:171], v180
	ds_read_b128 v[172:175], v180 offset:1024
	ds_read_b128 v[176:179], v180 offset:2048
	ds_read_b128 v[180:183], v180 offset:3072
	s_add_u32 s50, s50, 0x40000
	s_addc_u32 s51, s51, 0
	s_mov_b32 m0, s57
	v_lshl_add_u64 v[222:223], s[50:51], 0, v[136:137]
	ds_read_b128 v[184:187], v155 offset:32768
	ds_read_b128 v[188:191], v155 offset:33792
	ds_read_b128 v[192:195], v155 offset:34816
	ds_read_b128 v[196:199], v155 offset:35840
	ds_read_b128 v[200:203], v155 offset:36864
	ds_read_b128 v[204:207], v155 offset:37888
	ds_read_b128 v[208:211], v155 offset:38912
	ds_read_b128 v[212:215], v155 offset:39936
	global_load_lds_dwordx4 v[222:223], off
	v_lshl_add_u64 v[222:223], s[50:51], 0, v[132:133]
	s_mov_b32 m0, s58
	s_nop 0
	global_load_lds_dwordx4 v[222:223], off
	s_waitcnt vmcnt(8)
	s_waitcnt lgkmcnt(0)
	s_barrier
	v_mfma_f32_16x16x32_bf16 v[124:127], v[146:149], v[184:187], v[124:127]
	v_mfma_f32_16x16x32_bf16 v[120:123], v[160:163], v[184:187], v[120:123]
	v_mfma_f32_16x16x32_bf16 v[108:111], v[146:149], v[192:195], v[108:111]
	v_mfma_f32_16x16x32_bf16 v[104:107], v[160:163], v[192:195], v[104:107]
	v_mfma_f32_16x16x32_bf16 v[92:95], v[146:149], v[200:203], v[92:95]
	v_mfma_f32_16x16x32_bf16 v[88:91], v[160:163], v[200:203], v[88:91]
	v_mfma_f32_16x16x32_bf16 v[76:79], v[146:149], v[208:211], v[76:79]
	v_mfma_f32_16x16x32_bf16 v[72:75], v[160:163], v[208:211], v[72:75]
	v_mfma_f32_16x16x32_bf16 v[124:127], v[156:159], v[188:191], v[124:127]
	v_mfma_f32_16x16x32_bf16 v[120:123], v[164:167], v[188:191], v[120:123]
	v_mfma_f32_16x16x32_bf16 v[108:111], v[156:159], v[196:199], v[108:111]
	v_mfma_f32_16x16x32_bf16 v[104:107], v[164:167], v[196:199], v[104:107]
	v_mfma_f32_16x16x32_bf16 v[92:95], v[156:159], v[204:207], v[92:95]
	v_mfma_f32_16x16x32_bf16 v[88:91], v[164:167], v[204:207], v[88:91]
	v_mfma_f32_16x16x32_bf16 v[76:79], v[156:159], v[212:215], v[76:79]
	v_mfma_f32_16x16x32_bf16 v[72:75], v[164:167], v[212:215], v[72:75]
	v_mfma_f32_16x16x32_bf16 v[116:119], v[168:171], v[184:187], v[116:119]
	v_mfma_f32_16x16x32_bf16 v[112:115], v[176:179], v[184:187], v[112:115]
	v_mfma_f32_16x16x32_bf16 v[100:103], v[168:171], v[192:195], v[100:103]
	v_mfma_f32_16x16x32_bf16 v[96:99], v[176:179], v[192:195], v[96:99]
	v_mfma_f32_16x16x32_bf16 v[84:87], v[168:171], v[200:203], v[84:87]
	v_mfma_f32_16x16x32_bf16 v[80:83], v[176:179], v[200:203], v[80:83]
	v_mfma_f32_16x16x32_bf16 v[68:71], v[168:171], v[208:211], v[68:71]
	v_mfma_f32_16x16x32_bf16 v[64:67], v[176:179], v[208:211], v[64:67]
	v_mfma_f32_16x16x32_bf16 v[116:119], v[172:175], v[188:191], v[116:119]
	v_mfma_f32_16x16x32_bf16 v[112:115], v[180:183], v[188:191], v[112:115]
	v_mfma_f32_16x16x32_bf16 v[100:103], v[172:175], v[196:199], v[100:103]
	v_mfma_f32_16x16x32_bf16 v[96:99], v[180:183], v[196:199], v[96:99]
	v_mfma_f32_16x16x32_bf16 v[84:87], v[172:175], v[204:207], v[84:87]
	v_mfma_f32_16x16x32_bf16 v[80:83], v[180:183], v[204:207], v[80:83]
	v_mfma_f32_16x16x32_bf16 v[68:71], v[172:175], v[212:215], v[68:71]
	v_mfma_f32_16x16x32_bf16 v[64:67], v[180:183], v[212:215], v[64:67]
	s_barrier
; #define PG8_STAGE(bufoff, gbase, voff) do { _Pragma("unroll") for (int _i = 0; _i < 2; ++_i) \
;         __builtin_amdgcn_global_load_lds((const unsigned*)((const char*)(gbase) + (voff)[_i]), (LAS unsigned*)(lds + (bufoff) + ldsw + _i * 8192), 16, 0, 0); } while (0)
; #define PG8_LDA(dst, b, h) do { _Pragma("unroll") for (int m = 0; m < 4; ++m) _Pragma("unroll") for (int k = 0; k < 2; ++k) dst[m][k] = *(const LAS bf16x8*)(lds + PG8_SA(b, h) + aoff + m * 2048 + k * 1024); } while (0)
; #define PG8_MMA(ai, bj, At, Bt) do { __builtin_amdgcn_s_setprio(1); _Pragma("unroll") for (int m = 0; m < 4; ++m) _Pragma("unroll") for (int n = 0; n < 2; ++n) _Pragma("unroll") for (int k = 0; k < 2; ++k) \
;         acc[ai][bj][m][n] = __builtin_amdgcn_mfma_f32_16x16x32_bf16(Bt[n][k], At[m][k], acc[ai][bj][m][n], 0, 0, 0); __builtin_amdgcn_s_setprio(0); } while (0)
; #define PG8_WAIT_V(n) asm volatile("s_waitcnt vmcnt(" #n ")" ::: "memory")
; #define PG8_WAIT_L(n) asm volatile("s_waitcnt lgkmcnt(" #n ")" ::: "memory")
; #define PG8_BAR __builtin_amdgcn_s_barrier()
; #define PG8_SCHED __builtin_amdgcn_sched_barrier(0)
; template <class Epi, bool SP2 = false>
; __device__ __forceinline__ void gemm_phase(LAS unsigned char* lds, const Gemm g, const StaticOrder& S, const Epi& E) {
;     ...
;             PG8_LDA(At, 1, 1); PG8_STAGE(PG8_SB(1, 0), b3, voffB); PG8_STAGE(PG8_SB(1, 1), b3 + hstepB, voffB); PG8_STAGE(PG8_SA(1, 0), a3, voffA);
;             PG8_WAIT_V(8); PG8_WAIT_L(0); PG8_BAR; PG8_MMA(1, 0, At, B0); PG8_MMA(1, 1, At, B1); PG8_BAR; PG8_SCHED;
;     ...
;         if constexpr (SP2) { if (wr == 0) PG8_BAR; }
	s_add_i32 s50, s68, s53
	v_lshl_add_u64 v[150:151], v[150:151], 0, s[10:11]
	s_mov_b32 m0, s50
	ds_read_b128 v[184:187], v155 offset:49152
	ds_read_b128 v[188:191], v155 offset:50176
	ds_read_b128 v[192:195], v155 offset:51200
	ds_read_b128 v[196:199], v155 offset:52224
	ds_read_b128 v[200:203], v155 offset:53248
	ds_read_b128 v[204:207], v155 offset:54272
	ds_read_b128 v[208:211], v155 offset:55296
	ds_read_b128 v[212:215], v155 offset:56320
	global_load_lds_dwordx4 v[150:151], off
	s_add_i32 m0, s50, 0x2000
	s_add_u32 s48, s48, 0x40080
	v_lshl_add_u64 v[150:151], v[216:217], 0, s[10:11]
	s_addc_u32 s49, s49, 0
	s_add_i32 s50, s69, s53
	global_load_lds_dwordx4 v[150:151], off
	v_lshl_add_u64 v[150:151], s[48:49], 0, v[134:135]
	s_mov_b32 m0, s50
	s_nop 0
	global_load_lds_dwordx4 v[150:151], off
	v_lshl_add_u64 v[150:151], s[48:49], 0, v[130:131]
	s_add_i32 m0, s50, 0x2000
	s_nop 0
	global_load_lds_dwordx4 v[150:151], off
	v_lshl_add_u64 v[150:151], v[218:219], 0, s[10:11]
	s_mov_b32 m0, s62
	s_nop 0
	global_load_lds_dwordx4 v[150:151], off
	v_lshl_add_u64 v[150:151], v[220:221], 0, s[10:11]
	s_mov_b32 m0, s63
	s_nop 0
	global_load_lds_dwordx4 v[150:151], off
	s_waitcnt vmcnt(8)
	s_waitcnt lgkmcnt(0)
	s_barrier
	v_mfma_f32_16x16x32_bf16 v[60:63], v[146:149], v[184:187], v[60:63]
	v_mfma_f32_16x16x32_bf16 v[56:59], v[160:163], v[184:187], v[56:59]
	v_mfma_f32_16x16x32_bf16 v[44:47], v[146:149], v[192:195], v[44:47]
	v_mfma_f32_16x16x32_bf16 v[40:43], v[160:163], v[192:195], v[40:43]
	v_mfma_f32_16x16x32_bf16 v[28:31], v[146:149], v[200:203], v[28:31]
	v_mfma_f32_16x16x32_bf16 v[24:27], v[160:163], v[200:203], v[24:27]
	v_mfma_f32_16x16x32_bf16 v[12:15], v[146:149], v[208:211], v[12:15]
	v_mfma_f32_16x16x32_bf16 v[8:11], v[160:163], v[208:211], v[8:11]
	v_mfma_f32_16x16x32_bf16 v[60:63], v[156:159], v[188:191], v[60:63]
	v_mfma_f32_16x16x32_bf16 v[56:59], v[164:167], v[188:191], v[56:59]
	v_mfma_f32_16x16x32_bf16 v[44:47], v[156:159], v[196:199], v[44:47]
	v_mfma_f32_16x16x32_bf16 v[40:43], v[164:167], v[196:199], v[40:43]
	v_mfma_f32_16x16x32_bf16 v[28:31], v[156:159], v[204:207], v[28:31]
	v_mfma_f32_16x16x32_bf16 v[24:27], v[164:167], v[204:207], v[24:27]
	v_mfma_f32_16x16x32_bf16 v[12:15], v[156:159], v[212:215], v[12:15]
	v_mfma_f32_16x16x32_bf16 v[8:11], v[164:167], v[212:215], v[8:11]
	v_mfma_f32_16x16x32_bf16 v[52:55], v[168:171], v[184:187], v[52:55]
	v_mfma_f32_16x16x32_bf16 v[48:51], v[176:179], v[184:187], v[48:51]
	v_mfma_f32_16x16x32_bf16 v[36:39], v[168:171], v[192:195], v[36:39]
	v_mfma_f32_16x16x32_bf16 v[32:35], v[176:179], v[192:195], v[32:35]
	v_mfma_f32_16x16x32_bf16 v[20:23], v[168:171], v[200:203], v[20:23]
	v_mfma_f32_16x16x32_bf16 v[16:19], v[176:179], v[200:203], v[16:19]
	v_mfma_f32_16x16x32_bf16 v[4:7], v[168:171], v[208:211], v[4:7]
	v_mfma_f32_16x16x32_bf16 v[0:3], v[176:179], v[208:211], v[0:3]
	v_mfma_f32_16x16x32_bf16 v[52:55], v[172:175], v[188:191], v[52:55]
	v_mfma_f32_16x16x32_bf16 v[48:51], v[180:183], v[188:191], v[48:51]
	v_mfma_f32_16x16x32_bf16 v[36:39], v[172:175], v[196:199], v[36:39]
	v_mfma_f32_16x16x32_bf16 v[32:35], v[180:183], v[196:199], v[32:35]
	v_mfma_f32_16x16x32_bf16 v[20:23], v[172:175], v[204:207], v[20:23]
	v_mfma_f32_16x16x32_bf16 v[16:19], v[180:183], v[204:207], v[16:19]
	v_mfma_f32_16x16x32_bf16 v[4:7], v[172:175], v[212:215], v[4:7]
	v_mfma_f32_16x16x32_bf16 v[0:3], v[180:183], v[212:215], v[0:3]
	s_barrier
	s_add_i32 s76, s76, 2
	s_add_u32 s34, s34, 0x100
	s_addc_u32 s35, s35, 0
	s_add_u32 s74, s74, 0x100
	s_addc_u32 s75, s75, 0
	s_cmp_gt_u32 s76, 13
	s_cbranch_scc0 .LBB0_888
	s_and_b64 vcc, exec, s[12:13]
	s_cbranch_vccz .LBB0_891
	s_barrier

; #define PG8_STAGE(bufoff, gbase, voff) do { _Pragma("unroll") for (int _i = 0; _i < 2; ++_i) \
;         __builtin_amdgcn_global_load_lds((const unsigned*)((const char*)(gbase) + (voff)[_i]), (LAS unsigned*)(lds + (bufoff) + ldsw + _i * 8192), 16, 0, 0); } while (0)
; #define PG8_LDA(dst, b, h) do { _Pragma("unroll") for (int m = 0; m < 4; ++m) _Pragma("unroll") for (int k = 0; k < 2; ++k) dst[m][k] = *(const LAS bf16x8*)(lds + PG8_SA(b, h) + aoff + m * 2048 + k * 1024); } while (0)
; #define PG8_LDB(dst, b, h) do { _Pragma("unroll") for (int n = 0; n < 2; ++n) _Pragma("unroll") for (int k = 0; k < 2; ++k) dst[n][k] = *(const LAS bf16x8*)(lds + PG8_SB(b, h) + boff + n * 2048 + k * 1024); } while (0)
; #define PG8_MMA(ai, bj, At, Bt) do { __builtin_amdgcn_s_setprio(1); _Pragma("unroll") for (int m = 0; m < 4; ++m) _Pragma("unroll") for (int n = 0; n < 2; ++n) _Pragma("unroll") for (int k = 0; k < 2; ++k) \
;         acc[ai][bj][m][n] = __builtin_amdgcn_mfma_f32_16x16x32_bf16(Bt[n][k], At[m][k], acc[ai][bj][m][n], 0, 0, 0); __builtin_amdgcn_s_setprio(0); } while (0)
; #define PG8_WAIT_V(n) asm volatile("s_waitcnt vmcnt(" #n ")" ::: "memory")
; #define PG8_WAIT_L(n) asm volatile("s_waitcnt lgkmcnt(" #n ")" ::: "memory")
; #define PG8_BAR __builtin_amdgcn_s_barrier()
; #define PG8_SCHED __builtin_amdgcn_sched_barrier(0)
; template <class Epi, bool SP2 = false>
; __device__ __forceinline__ void gemm_phase(LAS unsigned char* lds, const Gemm g, const StaticOrder& S, const Epi& E) {
;     ...
;             const bool last = (t == nt - 2);
;             const char* a1 = cA + (size_t)(t + 1) * kstep;
;             const char* a2 = last ? nA : cA + (size_t)(t + 2) * kstep; const char* b2 = last ? nB : cB + (size_t)(t + 2) * kstep;
;             const char* a3 = a2 + kstep; const char* b3 = b2 + kstep;
;             if constexpr (SP2) {
;             PG8_LDB(B0, 0, 0); PG8_LDB(B1, 0, 1); PG8_SCHED; PG8_LDA(At, 0, 0); PG8_STAGE(PG8_SA(1, 1), a1 + hstepA, voffA);
;             PG8_WAIT_V(8); PG8_WAIT_L(0); PG8_BAR; PG8_MMA(0, 0, At, B0); PG8_MMA(0, 1, At, B1); PG8_BAR; PG8_SCHED;
;             PG8_LDA(At, 0, 1); PG8_STAGE(PG8_SB(0, 0), b2, voffB); PG8_STAGE(PG8_SB(0, 1), b2 + hstepB, voffB); PG8_STAGE(PG8_SA(0, 0), a2, voffA);
;             PG8_WAIT_V(8); PG8_WAIT_L(0); PG8_BAR; PG8_MMA(1, 0, At, B0); PG8_MMA(1, 1, At, B1); PG8_BAR; PG8_SCHED;
.LBB0_955:
	ds_read_b128 v[150:153], v147
	ds_read_b128 v[154:157], v147 offset:1024
	ds_read_b128 v[158:161], v147 offset:2048
	ds_read_b128 v[162:165], v147 offset:3072
	ds_read_b128 v[166:169], v148
	ds_read_b128 v[170:173], v148 offset:1024
	ds_read_b128 v[174:177], v148 offset:2048
	ds_read_b128 v[178:181], v148 offset:3072
	s_add_u32 s46, s34, 0xfffc0080
	s_addc_u32 s47, s35, -1
	s_cmp_eq_u32 s78, 12
	s_cselect_b32 s49, s41, s47
	s_cselect_b32 s48, s74, s46
	s_cselect_b32 s47, s39, s77
	s_cselect_b32 s46, s75, s76
	v_lshl_add_u64 v[214:215], s[34:35], 0, v[138:139]
	s_add_i32 m0, s53, 0xc000
	ds_read_b128 v[182:185], v149
	ds_read_b128 v[186:189], v149 offset:1024
	ds_read_b128 v[190:193], v149 offset:2048
	ds_read_b128 v[194:197], v149 offset:3072
	ds_read_b128 v[198:201], v149 offset:4096
	ds_read_b128 v[202:205], v149 offset:5120
	ds_read_b128 v[206:209], v149 offset:6144
	ds_read_b128 v[210:213], v149 offset:7168
	global_load_lds_dwordx4 v[214:215], off
	v_lshl_add_u64 v[214:215], s[34:35], 0, v[140:141]
	s_add_i32 m0, s53, 0xe000
	s_nop 0
	global_load_lds_dwordx4 v[214:215], off
	s_waitcnt vmcnt(8)
	s_waitcnt lgkmcnt(0)
	s_barrier
	v_mfma_f32_16x16x32_bf16 v[124:127], v[150:153], v[182:185], v[124:127]
	v_mfma_f32_16x16x32_bf16 v[120:123], v[158:161], v[182:185], v[120:123]
	v_mfma_f32_16x16x32_bf16 v[116:119], v[150:153], v[190:193], v[116:119]
	v_mfma_f32_16x16x32_bf16 v[112:115], v[158:161], v[190:193], v[112:115]
	v_mfma_f32_16x16x32_bf16 v[100:103], v[150:153], v[198:201], v[100:103]
	v_mfma_f32_16x16x32_bf16 v[96:99], v[158:161], v[198:201], v[96:99]
	v_mfma_f32_16x16x32_bf16 v[84:87], v[150:153], v[206:209], v[84:87]
	v_mfma_f32_16x16x32_bf16 v[80:83], v[158:161], v[206:209], v[80:83]
	v_mfma_f32_16x16x32_bf16 v[124:127], v[154:157], v[186:189], v[124:127]
	v_mfma_f32_16x16x32_bf16 v[120:123], v[162:165], v[186:189], v[120:123]
	v_mfma_f32_16x16x32_bf16 v[116:119], v[154:157], v[194:197], v[116:119]
	v_mfma_f32_16x16x32_bf16 v[112:115], v[162:165], v[194:197], v[112:115]
	v_mfma_f32_16x16x32_bf16 v[100:103], v[154:157], v[202:205], v[100:103]
	v_mfma_f32_16x16x32_bf16 v[96:99], v[162:165], v[202:205], v[96:99]
	v_mfma_f32_16x16x32_bf16 v[84:87], v[154:157], v[210:213], v[84:87]
	v_mfma_f32_16x16x32_bf16 v[80:83], v[162:165], v[210:213], v[80:83]
	v_mfma_f32_16x16x32_bf16 v[108:111], v[166:169], v[182:185], v[108:111]
	v_mfma_f32_16x16x32_bf16 v[104:107], v[174:177], v[182:185], v[104:107]
	v_mfma_f32_16x16x32_bf16 v[92:95], v[166:169], v[190:193], v[92:95]
	v_mfma_f32_16x16x32_bf16 v[88:91], v[174:177], v[190:193], v[88:91]
	v_mfma_f32_16x16x32_bf16 v[76:79], v[166:169], v[198:201], v[76:79]
	v_mfma_f32_16x16x32_bf16 v[72:75], v[174:177], v[198:201], v[72:75]
	v_mfma_f32_16x16x32_bf16 v[68:71], v[166:169], v[206:209], v[68:71]
	v_mfma_f32_16x16x32_bf16 v[64:67], v[174:177], v[206:209], v[64:67]
	v_mfma_f32_16x16x32_bf16 v[108:111], v[170:173], v[186:189], v[108:111]
	v_mfma_f32_16x16x32_bf16 v[104:107], v[178:181], v[186:189], v[104:107]
	v_mfma_f32_16x16x32_bf16 v[92:95], v[170:173], v[194:197], v[92:95]
	v_mfma_f32_16x16x32_bf16 v[88:91], v[178:181], v[194:197], v[88:91]
	v_mfma_f32_16x16x32_bf16 v[76:79], v[170:173], v[202:205], v[76:79]
	v_mfma_f32_16x16x32_bf16 v[72:75], v[178:181], v[202:205], v[72:75]
	v_mfma_f32_16x16x32_bf16 v[68:71], v[170:173], v[210:213], v[68:71]
	v_mfma_f32_16x16x32_bf16 v[64:67], v[178:181], v[210:213], v[64:67]
	s_barrier
	s_add_i32 s68, s63, s50
	v_lshl_add_u64 v[214:215], s[46:47], 0, v[134:135]
	s_mov_b32 m0, s68
	ds_read_b128 v[182:185], v149 offset:16384
	ds_read_b128 v[186:189], v149 offset:17408
	ds_read_b128 v[190:193], v149 offset:18432
	ds_read_b128 v[194:197], v149 offset:19456
	ds_read_b128 v[198:201], v149 offset:20480
	ds_read_b128 v[202:205], v149 offset:21504
	ds_read_b128 v[206:209], v149 offset:22528
	ds_read_b128 v[210:213], v149 offset:23552
	global_load_lds_dwordx4 v[214:215], off
	s_add_i32 m0, s68, 0x2000
	s_add_u32 s68, s46, 0x40000
	v_lshl_add_u64 v[216:217], s[46:47], 0, v[130:131]
	s_addc_u32 s69, s47, 0
	s_add_i32 s70, s64, s50
	global_load_lds_dwordx4 v[216:217], off
	v_lshl_add_u64 v[218:219], s[68:69], 0, v[134:135]
	s_mov_b32 m0, s70
	v_lshl_add_u64 v[220:221], s[48:49], 0, v[132:133]
	global_load_lds_dwordx4 v[218:219], off
	v_lshl_add_u64 v[218:219], s[68:69], 0, v[130:131]
	s_add_i32 m0, s70, 0x2000
	s_nop 0
	global_load_lds_dwordx4 v[218:219], off
	v_lshl_add_u64 v[218:219], s[48:49], 0, v[136:137]
	s_mov_b32 m0, s53
	s_nop 0
	global_load_lds_dwordx4 v[218:219], off
	s_mov_b32 m0, s54
	s_nop 0
	global_load_lds_dwordx4 v[220:221], off
	s_waitcnt vmcnt(8)
	s_waitcnt lgkmcnt(0)
	s_barrier
; #define PG8_STAGE(bufoff, gbase, voff) do { _Pragma("unroll") for (int _i = 0; _i < 2; ++_i) \
;         __builtin_amdgcn_global_load_lds((const unsigned*)((const char*)(gbase) + (voff)[_i]), (LAS unsigned*)(lds + (bufoff) + ldsw + _i * 8192), 16, 0, 0); } while (0)
; #define PG8_LDA(dst, b, h) do { _Pragma("unroll") for (int m = 0; m < 4; ++m) _Pragma("unroll") for (int k = 0; k < 2; ++k) dst[m][k] = *(const LAS bf16x8*)(lds + PG8_SA(b, h) + aoff + m * 2048 + k * 1024); } while (0)
; #define PG8_LDB(dst, b, h) do { _Pragma("unroll") for (int n = 0; n < 2; ++n) _Pragma("unroll") for (int k = 0; k < 2; ++k) dst[n][k] = *(const LAS bf16x8*)(lds + PG8_SB(b, h) + boff + n * 2048 + k * 1024); } while (0)
; #define PG8_MMA(ai, bj, At, Bt) do { __builtin_amdgcn_s_setprio(1); _Pragma("unroll") for (int m = 0; m < 4; ++m) _Pragma("unroll") for (int n = 0; n < 2; ++n) _Pragma("unroll") for (int k = 0; k < 2; ++k) \
;         acc[ai][bj][m][n] = __builtin_amdgcn_mfma_f32_16x16x32_bf16(Bt[n][k], At[m][k], acc[ai][bj][m][n], 0, 0, 0); __builtin_amdgcn_s_setprio(0); } while (0)
; #define PG8_WAIT_V(n) asm volatile("s_waitcnt vmcnt(" #n ")" ::: "memory")
; #define PG8_WAIT_L(n) asm volatile("s_waitcnt lgkmcnt(" #n ")" ::: "memory")
; #define PG8_BAR __builtin_amdgcn_s_barrier()
; #define PG8_SCHED __builtin_amdgcn_sched_barrier(0)
; template <class Epi, bool SP2 = false>
; __device__ __forceinline__ void gemm_phase(LAS unsigned char* lds, const Gemm g, const StaticOrder& S, const Epi& E) {
;     ...
;             PG8_WAIT_V(8); PG8_WAIT_L(0); PG8_BAR; PG8_MMA(1, 0, At, B0); PG8_MMA(1, 1, At, B1); PG8_BAR; PG8_SCHED;
;             PG8_LDB(B0, 1, 0); PG8_LDB(B1, 1, 1); PG8_SCHED; PG8_LDA(At, 1, 0); PG8_STAGE(PG8_SA(0, 1), a2 + hstepA, voffA);
;             PG8_WAIT_V(8); PG8_WAIT_L(0); PG8_BAR; PG8_MMA(0, 0, At, B0); PG8_MMA(0, 1, At, B1); PG8_BAR; PG8_SCHED;
	v_mfma_f32_16x16x32_bf16 v[60:63], v[150:153], v[182:185], v[60:63]
	v_mfma_f32_16x16x32_bf16 v[56:59], v[158:161], v[182:185], v[56:59]
	v_mfma_f32_16x16x32_bf16 v[52:55], v[150:153], v[190:193], v[52:55]
	v_mfma_f32_16x16x32_bf16 v[48:51], v[158:161], v[190:193], v[48:51]
	v_mfma_f32_16x16x32_bf16 v[36:39], v[150:153], v[198:201], v[36:39]
	v_mfma_f32_16x16x32_bf16 v[32:35], v[158:161], v[198:201], v[32:35]
	v_mfma_f32_16x16x32_bf16 v[20:23], v[150:153], v[206:209], v[20:23]
	v_mfma_f32_16x16x32_bf16 v[16:19], v[158:161], v[206:209], v[16:19]
	v_mfma_f32_16x16x32_bf16 v[60:63], v[154:157], v[186:189], v[60:63]
	v_mfma_f32_16x16x32_bf16 v[56:59], v[162:165], v[186:189], v[56:59]
	v_mfma_f32_16x16x32_bf16 v[52:55], v[154:157], v[194:197], v[52:55]
	v_mfma_f32_16x16x32_bf16 v[48:51], v[162:165], v[194:197], v[48:51]
	v_mfma_f32_16x16x32_bf16 v[36:39], v[154:157], v[202:205], v[36:39]
	v_mfma_f32_16x16x32_bf16 v[32:35], v[162:165], v[202:205], v[32:35]
	v_mfma_f32_16x16x32_bf16 v[20:23], v[154:157], v[210:213], v[20:23]
	v_mfma_f32_16x16x32_bf16 v[16:19], v[162:165], v[210:213], v[16:19]
	v_mfma_f32_16x16x32_bf16 v[44:47], v[166:169], v[182:185], v[44:47]
	v_mfma_f32_16x16x32_bf16 v[40:43], v[174:177], v[182:185], v[40:43]
	v_mfma_f32_16x16x32_bf16 v[28:31], v[166:169], v[190:193], v[28:31]
	v_mfma_f32_16x16x32_bf16 v[24:27], v[174:177], v[190:193], v[24:27]
	v_mfma_f32_16x16x32_bf16 v[12:15], v[166:169], v[198:201], v[12:15]
	v_mfma_f32_16x16x32_bf16 v[8:11], v[174:177], v[198:201], v[8:11]
	v_mfma_f32_16x16x32_bf16 v[4:7], v[166:169], v[206:209], v[4:7]
	v_mfma_f32_16x16x32_bf16 v[0:3], v[174:177], v[206:209], v[0:3]
	v_mfma_f32_16x16x32_bf16 v[44:47], v[170:173], v[186:189], v[44:47]
	v_mfma_f32_16x16x32_bf16 v[40:43], v[178:181], v[186:189], v[40:43]
	v_mfma_f32_16x16x32_bf16 v[28:31], v[170:173], v[194:197], v[28:31]
	v_mfma_f32_16x16x32_bf16 v[24:27], v[178:181], v[194:197], v[24:27]
	v_mfma_f32_16x16x32_bf16 v[12:15], v[170:173], v[202:205], v[12:15]
	v_mfma_f32_16x16x32_bf16 v[8:11], v[178:181], v[202:205], v[8:11]
	v_mfma_f32_16x16x32_bf16 v[4:7], v[170:173], v[210:213], v[4:7]
	v_mfma_f32_16x16x32_bf16 v[0:3], v[178:181], v[210:213], v[0:3]
	s_barrier
	s_add_i32 s68, 0, 0x18000
	s_add_i32 s69, 0, 0x1c000
	v_add_u32_e32 v162, s68, v146
	v_add_u32_e32 v178, s69, v146
	ds_read_b128 v[150:153], v162
	ds_read_b128 v[154:157], v162 offset:1024
	ds_read_b128 v[158:161], v162 offset:2048
	ds_read_b128 v[162:165], v162 offset:3072
	ds_read_b128 v[166:169], v178
	ds_read_b128 v[170:173], v178 offset:1024
	ds_read_b128 v[174:177], v178 offset:2048
	ds_read_b128 v[178:181], v178 offset:3072
	s_add_u32 s48, s48, 0x40000
	s_addc_u32 s49, s49, 0
	s_mov_b32 m0, s55
	v_lshl_add_u64 v[222:223], s[48:49], 0, v[136:137]
	ds_read_b128 v[182:185], v149 offset:32768
	ds_read_b128 v[186:189], v149 offset:33792
	ds_read_b128 v[190:193], v149 offset:34816
	ds_read_b128 v[194:197], v149 offset:35840
	ds_read_b128 v[198:201], v149 offset:36864
	ds_read_b128 v[202:205], v149 offset:37888
	ds_read_b128 v[206:209], v149 offset:38912
	ds_read_b128 v[210:213], v149 offset:39936
	global_load_lds_dwordx4 v[222:223], off
	v_lshl_add_u64 v[222:223], s[48:49], 0, v[132:133]
	s_mov_b32 m0, s56
	s_nop 0
	global_load_lds_dwordx4 v[222:223], off
	s_waitcnt vmcnt(8)
	s_waitcnt lgkmcnt(0)
	s_barrier
	v_mfma_f32_16x16x32_bf16 v[124:127], v[150:153], v[182:185], v[124:127]
	v_mfma_f32_16x16x32_bf16 v[120:123], v[158:161], v[182:185], v[120:123]
	v_mfma_f32_16x16x32_bf16 v[116:119], v[150:153], v[190:193], v[116:119]
	v_mfma_f32_16x16x32_bf16 v[112:115], v[158:161], v[190:193], v[112:115]
	v_mfma_f32_16x16x32_bf16 v[100:103], v[150:153], v[198:201], v[100:103]
	v_mfma_f32_16x16x32_bf16 v[96:99], v[158:161], v[198:201], v[96:99]
	v_mfma_f32_16x16x32_bf16 v[84:87], v[150:153], v[206:209], v[84:87]
	v_mfma_f32_16x16x32_bf16 v[80:83], v[158:161], v[206:209], v[80:83]
	v_mfma_f32_16x16x32_bf16 v[124:127], v[154:157], v[186:189], v[124:127]
	v_mfma_f32_16x16x32_bf16 v[120:123], v[162:165], v[186:189], v[120:123]
	v_mfma_f32_16x16x32_bf16 v[116:119], v[154:157], v[194:197], v[116:119]
	v_mfma_f32_16x16x32_bf16 v[112:115], v[162:165], v[194:197], v[112:115]
	v_mfma_f32_16x16x32_bf16 v[100:103], v[154:157], v[202:205], v[100:103]
	v_mfma_f32_16x16x32_bf16 v[96:99], v[162:165], v[202:205], v[96:99]
	v_mfma_f32_16x16x32_bf16 v[84:87], v[154:157], v[210:213], v[84:87]
	v_mfma_f32_16x16x32_bf16 v[80:83], v[162:165], v[210:213], v[80:83]
	v_mfma_f32_16x16x32_bf16 v[108:111], v[166:169], v[182:185], v[108:111]
	v_mfma_f32_16x16x32_bf16 v[104:107], v[174:177], v[182:185], v[104:107]
	v_mfma_f32_16x16x32_bf16 v[92:95], v[166:169], v[190:193], v[92:95]
	v_mfma_f32_16x16x32_bf16 v[88:91], v[174:177], v[190:193], v[88:91]
	v_mfma_f32_16x16x32_bf16 v[76:79], v[166:169], v[198:201], v[76:79]
	v_mfma_f32_16x16x32_bf16 v[72:75], v[174:177], v[198:201], v[72:75]
	v_mfma_f32_16x16x32_bf16 v[68:71], v[166:169], v[206:209], v[68:71]
	v_mfma_f32_16x16x32_bf16 v[64:67], v[174:177], v[206:209], v[64:67]
	v_mfma_f32_16x16x32_bf16 v[108:111], v[170:173], v[186:189], v[108:111]
	v_mfma_f32_16x16x32_bf16 v[104:107], v[178:181], v[186:189], v[104:107]
	v_mfma_f32_16x16x32_bf16 v[92:95], v[170:173], v[194:197], v[92:95]
	v_mfma_f32_16x16x32_bf16 v[88:91], v[178:181], v[194:197], v[88:91]
	v_mfma_f32_16x16x32_bf16 v[76:79], v[170:173], v[202:205], v[76:79]
	v_mfma_f32_16x16x32_bf16 v[72:75], v[178:181], v[202:205], v[72:75]
	v_mfma_f32_16x16x32_bf16 v[68:71], v[170:173], v[210:213], v[68:71]
	v_mfma_f32_16x16x32_bf16 v[64:67], v[178:181], v[210:213], v[64:67]
	s_barrier
; #define PG8_STAGE(bufoff, gbase, voff) do { _Pragma("unroll") for (int _i = 0; _i < 2; ++_i) \
;         __builtin_amdgcn_global_load_lds((const unsigned*)((const char*)(gbase) + (voff)[_i]), (LAS unsigned*)(lds + (bufoff) + ldsw + _i * 8192), 16, 0, 0); } while (0)
; #define PG8_LDA(dst, b, h) do { _Pragma("unroll") for (int m = 0; m < 4; ++m) _Pragma("unroll") for (int k = 0; k < 2; ++k) dst[m][k] = *(const LAS bf16x8*)(lds + PG8_SA(b, h) + aoff + m * 2048 + k * 1024); } while (0)
; #define PG8_MMA(ai, bj, At, Bt) do { __builtin_amdgcn_s_setprio(1); _Pragma("unroll") for (int m = 0; m < 4; ++m) _Pragma("unroll") for (int n = 0; n < 2; ++n) _Pragma("unroll") for (int k = 0; k < 2; ++k) \
;         acc[ai][bj][m][n] = __builtin_amdgcn_mfma_f32_16x16x32_bf16(Bt[n][k], At[m][k], acc[ai][bj][m][n], 0, 0, 0); __builtin_amdgcn_s_setprio(0); } while (0)
; #define PG8_WAIT_V(n) asm volatile("s_waitcnt vmcnt(" #n ")" ::: "memory")
; #define PG8_WAIT_L(n) asm volatile("s_waitcnt lgkmcnt(" #n ")" ::: "memory")
; #define PG8_BAR __builtin_amdgcn_s_barrier()
; #define PG8_SCHED __builtin_amdgcn_sched_barrier(0)
; template <class Epi, bool SP2 = false>
; __device__ __forceinline__ void gemm_phase(LAS unsigned char* lds, const Gemm g, const StaticOrder& S, const Epi& E) {
;     ...
;             PG8_LDA(At, 1, 1); PG8_STAGE(PG8_SB(1, 0), b3, voffB); PG8_STAGE(PG8_SB(1, 1), b3 + hstepB, voffB); PG8_STAGE(PG8_SA(1, 0), a3, voffA);
;             PG8_WAIT_V(8); PG8_WAIT_L(0); PG8_BAR; PG8_MMA(1, 0, At, B0); PG8_MMA(1, 1, At, B1); PG8_BAR; PG8_SCHED;
;     ...
;         if constexpr (SP2) { if (wr == 0) PG8_BAR; }
	s_add_i32 s48, s68, s50
	v_lshl_add_u64 v[214:215], v[214:215], 0, s[12:13]
	s_mov_b32 m0, s48
	ds_read_b128 v[182:185], v149 offset:49152
	ds_read_b128 v[186:189], v149 offset:50176
	ds_read_b128 v[190:193], v149 offset:51200
	ds_read_b128 v[194:197], v149 offset:52224
	ds_read_b128 v[198:201], v149 offset:53248
	ds_read_b128 v[202:205], v149 offset:54272
	ds_read_b128 v[206:209], v149 offset:55296
	ds_read_b128 v[210:213], v149 offset:56320
	global_load_lds_dwordx4 v[214:215], off
	s_add_i32 m0, s48, 0x2000
	s_add_u32 s46, s46, 0x40080
	v_lshl_add_u64 v[214:215], v[216:217], 0, s[12:13]
	s_addc_u32 s47, s47, 0
	s_add_i32 s48, s69, s50
	global_load_lds_dwordx4 v[214:215], off
	v_lshl_add_u64 v[214:215], s[46:47], 0, v[134:135]
	s_mov_b32 m0, s48
	s_nop 0
	global_load_lds_dwordx4 v[214:215], off
	v_lshl_add_u64 v[214:215], s[46:47], 0, v[130:131]
	s_add_i32 m0, s48, 0x2000
	s_nop 0
	global_load_lds_dwordx4 v[214:215], off
	v_lshl_add_u64 v[214:215], v[218:219], 0, s[12:13]
	s_mov_b32 m0, s59
	s_nop 0
	global_load_lds_dwordx4 v[214:215], off
	v_lshl_add_u64 v[214:215], v[220:221], 0, s[12:13]
	s_mov_b32 m0, s60
	s_nop 0
	global_load_lds_dwordx4 v[214:215], off
	s_waitcnt vmcnt(8)
	s_waitcnt lgkmcnt(0)
	s_barrier
	v_mfma_f32_16x16x32_bf16 v[60:63], v[150:153], v[182:185], v[60:63]
	v_mfma_f32_16x16x32_bf16 v[56:59], v[158:161], v[182:185], v[56:59]
	v_mfma_f32_16x16x32_bf16 v[52:55], v[150:153], v[190:193], v[52:55]
	v_mfma_f32_16x16x32_bf16 v[48:51], v[158:161], v[190:193], v[48:51]
	v_mfma_f32_16x16x32_bf16 v[36:39], v[150:153], v[198:201], v[36:39]
	v_mfma_f32_16x16x32_bf16 v[32:35], v[158:161], v[198:201], v[32:35]
	v_mfma_f32_16x16x32_bf16 v[20:23], v[150:153], v[206:209], v[20:23]
	v_mfma_f32_16x16x32_bf16 v[16:19], v[158:161], v[206:209], v[16:19]
	v_mfma_f32_16x16x32_bf16 v[60:63], v[154:157], v[186:189], v[60:63]
	v_mfma_f32_16x16x32_bf16 v[56:59], v[162:165], v[186:189], v[56:59]
	v_mfma_f32_16x16x32_bf16 v[52:55], v[154:157], v[194:197], v[52:55]
	v_mfma_f32_16x16x32_bf16 v[48:51], v[162:165], v[194:197], v[48:51]
	v_mfma_f32_16x16x32_bf16 v[36:39], v[154:157], v[202:205], v[36:39]
	v_mfma_f32_16x16x32_bf16 v[32:35], v[162:165], v[202:205], v[32:35]
	v_mfma_f32_16x16x32_bf16 v[20:23], v[154:157], v[210:213], v[20:23]
	v_mfma_f32_16x16x32_bf16 v[16:19], v[162:165], v[210:213], v[16:19]
	v_mfma_f32_16x16x32_bf16 v[44:47], v[166:169], v[182:185], v[44:47]
	v_mfma_f32_16x16x32_bf16 v[40:43], v[174:177], v[182:185], v[40:43]
	v_mfma_f32_16x16x32_bf16 v[28:31], v[166:169], v[190:193], v[28:31]
	v_mfma_f32_16x16x32_bf16 v[24:27], v[174:177], v[190:193], v[24:27]
	v_mfma_f32_16x16x32_bf16 v[12:15], v[166:169], v[198:201], v[12:15]
	v_mfma_f32_16x16x32_bf16 v[8:11], v[174:177], v[198:201], v[8:11]
	v_mfma_f32_16x16x32_bf16 v[4:7], v[166:169], v[206:209], v[4:7]
	v_mfma_f32_16x16x32_bf16 v[0:3], v[174:177], v[206:209], v[0:3]
	v_mfma_f32_16x16x32_bf16 v[44:47], v[170:173], v[186:189], v[44:47]
	v_mfma_f32_16x16x32_bf16 v[40:43], v[178:181], v[186:189], v[40:43]
	v_mfma_f32_16x16x32_bf16 v[28:31], v[170:173], v[194:197], v[28:31]
	v_mfma_f32_16x16x32_bf16 v[24:27], v[178:181], v[194:197], v[24:27]
	v_mfma_f32_16x16x32_bf16 v[12:15], v[170:173], v[202:205], v[12:15]
	v_mfma_f32_16x16x32_bf16 v[8:11], v[178:181], v[202:205], v[8:11]
	v_mfma_f32_16x16x32_bf16 v[4:7], v[170:173], v[210:213], v[4:7]
	v_mfma_f32_16x16x32_bf16 v[0:3], v[178:181], v[210:213], v[0:3]
	s_barrier
	s_add_i32 s78, s78, 2
	s_add_u32 s34, s34, 0x100
	s_addc_u32 s35, s35, 0
	s_add_u32 s76, s76, 0x100
	s_addc_u32 s77, s77, 0
	s_cmp_gt_u32 s78, 13
	s_cbranch_scc0 .LBB0_955
	s_and_b64 vcc, exec, s[26:27]
	s_cbranch_vccz .LBB0_958
	s_barrier

; #define PG8_STAGE(bufoff, gbase, voff) do { _Pragma("unroll") for (int _i = 0; _i < 2; ++_i) \
;         __builtin_amdgcn_global_load_lds((const unsigned*)((const char*)(gbase) + (voff)[_i]), (LAS unsigned*)(lds + (bufoff) + ldsw + _i * 8192), 16, 0, 0); } while (0)
; #define PG8_LDA(dst, b, h) do { _Pragma("unroll") for (int m = 0; m < 4; ++m) _Pragma("unroll") for (int k = 0; k < 2; ++k) dst[m][k] = *(const LAS bf16x8*)(lds + PG8_SA(b, h) + aoff + m * 2048 + k * 1024); } while (0)
; #define PG8_LDB(dst, b, h) do { _Pragma("unroll") for (int n = 0; n < 2; ++n) _Pragma("unroll") for (int k = 0; k < 2; ++k) dst[n][k] = *(const LAS bf16x8*)(lds + PG8_SB(b, h) + boff + n * 2048 + k * 1024); } while (0)
; #define PG8_MMA(ai, bj, At, Bt) do { __builtin_amdgcn_s_setprio(1); _Pragma("unroll") for (int m = 0; m < 4; ++m) _Pragma("unroll") for (int n = 0; n < 2; ++n) _Pragma("unroll") for (int k = 0; k < 2; ++k) \
;         acc[ai][bj][m][n] = __builtin_amdgcn_mfma_f32_16x16x32_bf16(Bt[n][k], At[m][k], acc[ai][bj][m][n], 0, 0, 0); __builtin_amdgcn_s_setprio(0); } while (0)
; #define PG8_WAIT_V(n) asm volatile("s_waitcnt vmcnt(" #n ")" ::: "memory")
; #define PG8_WAIT_L(n) asm volatile("s_waitcnt lgkmcnt(" #n ")" ::: "memory")
; #define PG8_BAR __builtin_amdgcn_s_barrier()
; #define PG8_SCHED __builtin_amdgcn_sched_barrier(0)
; template <class Epi, bool SP2 = false>
; __device__ __forceinline__ void gemm_phase(LAS unsigned char* lds, const Gemm g, const StaticOrder& S, const Epi& E) {
;     ...
;             const bool last = (t == nt - 2);
;             const char* a1 = cA + (size_t)(t + 1) * kstep;
;             const char* a2 = last ? nA : cA + (size_t)(t + 2) * kstep; const char* b2 = last ? nB : cB + (size_t)(t + 2) * kstep;
;             const char* a3 = a2 + kstep; const char* b3 = b2 + kstep;
;             if constexpr (SP2) {
;             PG8_LDB(B0, 0, 0); PG8_LDB(B1, 0, 1); PG8_SCHED; PG8_LDA(At, 0, 0); PG8_STAGE(PG8_SA(1, 1), a1 + hstepA, voffA);
;             PG8_WAIT_V(8); PG8_WAIT_L(0); PG8_BAR; PG8_MMA(0, 0, At, B0); PG8_MMA(0, 1, At, B1); PG8_BAR; PG8_SCHED;
;             PG8_LDA(At, 0, 1); PG8_STAGE(PG8_SB(0, 0), b2, voffB); PG8_STAGE(PG8_SB(0, 1), b2 + hstepB, voffB); PG8_STAGE(PG8_SA(0, 0), a2, voffA);
;             PG8_WAIT_V(8); PG8_WAIT_L(0); PG8_BAR; PG8_MMA(1, 0, At, B0); PG8_MMA(1, 1, At, B1); PG8_BAR; PG8_SCHED;
.LBB0_1077:
	ds_read_b128 v[152:155], v149
	ds_read_b128 v[156:159], v149 offset:1024
	ds_read_b128 v[160:163], v149 offset:2048
	ds_read_b128 v[164:167], v149 offset:3072
	ds_read_b128 v[168:171], v150
	ds_read_b128 v[172:175], v150 offset:1024
	ds_read_b128 v[176:179], v150 offset:2048
	ds_read_b128 v[180:183], v150 offset:3072
	s_add_u32 s30, s28, 0xfffc0080
	s_addc_u32 s31, s29, -1
	s_cmp_eq_u32 s57, 12
	s_cselect_b32 s35, s19, s31
	s_cselect_b32 s34, s53, s30
	s_cselect_b32 s31, s13, s56
	s_cselect_b32 s30, s54, s55
	v_lshl_add_u64 v[146:147], s[28:29], 0, v[138:139]
	s_add_i32 m0, s27, 0xc000
	ds_read_b128 v[184:187], v151
	ds_read_b128 v[188:191], v151 offset:1024
	ds_read_b128 v[192:195], v151 offset:2048
	ds_read_b128 v[196:199], v151 offset:3072
	ds_read_b128 v[200:203], v151 offset:4096
	ds_read_b128 v[204:207], v151 offset:5120
	ds_read_b128 v[208:211], v151 offset:6144
	ds_read_b128 v[212:215], v151 offset:7168
	global_load_lds_dwordx4 v[146:147], off
	v_lshl_add_u64 v[146:147], s[28:29], 0, v[140:141]
	s_add_i32 m0, s27, 0xe000
	s_nop 0
	global_load_lds_dwordx4 v[146:147], off
	s_waitcnt vmcnt(8)
	s_waitcnt lgkmcnt(0)
	s_barrier
	v_mfma_f32_16x16x32_bf16 v[124:127], v[152:155], v[184:187], v[124:127]
	v_mfma_f32_16x16x32_bf16 v[120:123], v[160:163], v[184:187], v[120:123]
	v_mfma_f32_16x16x32_bf16 v[108:111], v[152:155], v[192:195], v[108:111]
	v_mfma_f32_16x16x32_bf16 v[104:107], v[160:163], v[192:195], v[104:107]
	v_mfma_f32_16x16x32_bf16 v[92:95], v[152:155], v[200:203], v[92:95]
	v_mfma_f32_16x16x32_bf16 v[88:91], v[160:163], v[200:203], v[88:91]
	v_mfma_f32_16x16x32_bf16 v[76:79], v[152:155], v[208:211], v[76:79]
	v_mfma_f32_16x16x32_bf16 v[72:75], v[160:163], v[208:211], v[72:75]
	v_mfma_f32_16x16x32_bf16 v[124:127], v[156:159], v[188:191], v[124:127]
	v_mfma_f32_16x16x32_bf16 v[120:123], v[164:167], v[188:191], v[120:123]
	v_mfma_f32_16x16x32_bf16 v[108:111], v[156:159], v[196:199], v[108:111]
	v_mfma_f32_16x16x32_bf16 v[104:107], v[164:167], v[196:199], v[104:107]
	v_mfma_f32_16x16x32_bf16 v[92:95], v[156:159], v[204:207], v[92:95]
	v_mfma_f32_16x16x32_bf16 v[88:91], v[164:167], v[204:207], v[88:91]
	v_mfma_f32_16x16x32_bf16 v[76:79], v[156:159], v[212:215], v[76:79]
	v_mfma_f32_16x16x32_bf16 v[72:75], v[164:167], v[212:215], v[72:75]
	v_mfma_f32_16x16x32_bf16 v[116:119], v[168:171], v[184:187], v[116:119]
	v_mfma_f32_16x16x32_bf16 v[112:115], v[176:179], v[184:187], v[112:115]
	v_mfma_f32_16x16x32_bf16 v[100:103], v[168:171], v[192:195], v[100:103]
	v_mfma_f32_16x16x32_bf16 v[96:99], v[176:179], v[192:195], v[96:99]
	v_mfma_f32_16x16x32_bf16 v[84:87], v[168:171], v[200:203], v[84:87]
	v_mfma_f32_16x16x32_bf16 v[80:83], v[176:179], v[200:203], v[80:83]
	v_mfma_f32_16x16x32_bf16 v[68:71], v[168:171], v[208:211], v[68:71]
	v_mfma_f32_16x16x32_bf16 v[64:67], v[176:179], v[208:211], v[64:67]
	v_mfma_f32_16x16x32_bf16 v[116:119], v[172:175], v[188:191], v[116:119]
	v_mfma_f32_16x16x32_bf16 v[112:115], v[180:183], v[188:191], v[112:115]
	v_mfma_f32_16x16x32_bf16 v[100:103], v[172:175], v[196:199], v[100:103]
	v_mfma_f32_16x16x32_bf16 v[96:99], v[180:183], v[196:199], v[96:99]
	v_mfma_f32_16x16x32_bf16 v[84:87], v[172:175], v[204:207], v[84:87]
	v_mfma_f32_16x16x32_bf16 v[80:83], v[180:183], v[204:207], v[80:83]
	v_mfma_f32_16x16x32_bf16 v[68:71], v[172:175], v[212:215], v[68:71]
	v_mfma_f32_16x16x32_bf16 v[64:67], v[180:183], v[212:215], v[64:67]
	s_barrier
	s_add_i32 s58, s50, s37
	v_lshl_add_u64 v[146:147], s[30:31], 0, v[134:135]
	s_mov_b32 m0, s58
	ds_read_b128 v[184:187], v151 offset:16384
	ds_read_b128 v[188:191], v151 offset:17408
	ds_read_b128 v[192:195], v151 offset:18432
	ds_read_b128 v[196:199], v151 offset:19456
	ds_read_b128 v[200:203], v151 offset:20480
	ds_read_b128 v[204:207], v151 offset:21504
	ds_read_b128 v[208:211], v151 offset:22528
	ds_read_b128 v[212:215], v151 offset:23552
	global_load_lds_dwordx4 v[146:147], off
	s_add_i32 m0, s58, 0x2000
	s_add_u32 s58, s30, 0x40000
	v_lshl_add_u64 v[216:217], s[30:31], 0, v[130:131]
	s_addc_u32 s59, s31, 0
	s_add_i32 s60, s51, s37
	global_load_lds_dwordx4 v[216:217], off
	v_lshl_add_u64 v[218:219], s[58:59], 0, v[134:135]
	s_mov_b32 m0, s60
	v_lshl_add_u64 v[220:221], s[34:35], 0, v[132:133]
	global_load_lds_dwordx4 v[218:219], off
	v_lshl_add_u64 v[218:219], s[58:59], 0, v[130:131]
	s_add_i32 m0, s60, 0x2000
	s_nop 0
	global_load_lds_dwordx4 v[218:219], off
	v_lshl_add_u64 v[218:219], s[34:35], 0, v[136:137]
	s_mov_b32 m0, s27
	s_nop 0
	global_load_lds_dwordx4 v[218:219], off
	s_mov_b32 m0, s40
	s_nop 0
	global_load_lds_dwordx4 v[220:221], off
	s_waitcnt vmcnt(8)
	s_waitcnt lgkmcnt(0)
	s_barrier
; #define PG8_STAGE(bufoff, gbase, voff) do { _Pragma("unroll") for (int _i = 0; _i < 2; ++_i) \
;         __builtin_amdgcn_global_load_lds((const unsigned*)((const char*)(gbase) + (voff)[_i]), (LAS unsigned*)(lds + (bufoff) + ldsw + _i * 8192), 16, 0, 0); } while (0)
; #define PG8_LDA(dst, b, h) do { _Pragma("unroll") for (int m = 0; m < 4; ++m) _Pragma("unroll") for (int k = 0; k < 2; ++k) dst[m][k] = *(const LAS bf16x8*)(lds + PG8_SA(b, h) + aoff + m * 2048 + k * 1024); } while (0)
; #define PG8_LDB(dst, b, h) do { _Pragma("unroll") for (int n = 0; n < 2; ++n) _Pragma("unroll") for (int k = 0; k < 2; ++k) dst[n][k] = *(const LAS bf16x8*)(lds + PG8_SB(b, h) + boff + n * 2048 + k * 1024); } while (0)
; #define PG8_MMA(ai, bj, At, Bt) do { __builtin_amdgcn_s_setprio(1); _Pragma("unroll") for (int m = 0; m < 4; ++m) _Pragma("unroll") for (int n = 0; n < 2; ++n) _Pragma("unroll") for (int k = 0; k < 2; ++k) \
;         acc[ai][bj][m][n] = __builtin_amdgcn_mfma_f32_16x16x32_bf16(Bt[n][k], At[m][k], acc[ai][bj][m][n], 0, 0, 0); __builtin_amdgcn_s_setprio(0); } while (0)
; #define PG8_WAIT_V(n) asm volatile("s_waitcnt vmcnt(" #n ")" ::: "memory")
; #define PG8_WAIT_L(n) asm volatile("s_waitcnt lgkmcnt(" #n ")" ::: "memory")
; #define PG8_BAR __builtin_amdgcn_s_barrier()
; #define PG8_SCHED __builtin_amdgcn_sched_barrier(0)
; template <class Epi, bool SP2 = false>
; __device__ __forceinline__ void gemm_phase(LAS unsigned char* lds, const Gemm g, const StaticOrder& S, const Epi& E) {
;     ...
;             PG8_WAIT_V(8); PG8_WAIT_L(0); PG8_BAR; PG8_MMA(1, 0, At, B0); PG8_MMA(1, 1, At, B1); PG8_BAR; PG8_SCHED;
;             PG8_LDB(B0, 1, 0); PG8_LDB(B1, 1, 1); PG8_SCHED; PG8_LDA(At, 1, 0); PG8_STAGE(PG8_SA(0, 1), a2 + hstepA, voffA);
;             PG8_WAIT_V(8); PG8_WAIT_L(0); PG8_BAR; PG8_MMA(0, 0, At, B0); PG8_MMA(0, 1, At, B1); PG8_BAR; PG8_SCHED;
	v_mfma_f32_16x16x32_bf16 v[60:63], v[152:155], v[184:187], v[60:63]
	v_mfma_f32_16x16x32_bf16 v[56:59], v[160:163], v[184:187], v[56:59]
	v_mfma_f32_16x16x32_bf16 v[44:47], v[152:155], v[192:195], v[44:47]
	v_mfma_f32_16x16x32_bf16 v[40:43], v[160:163], v[192:195], v[40:43]
	v_mfma_f32_16x16x32_bf16 v[28:31], v[152:155], v[200:203], v[28:31]
	v_mfma_f32_16x16x32_bf16 v[24:27], v[160:163], v[200:203], v[24:27]
	v_mfma_f32_16x16x32_bf16 v[12:15], v[152:155], v[208:211], v[12:15]
	v_mfma_f32_16x16x32_bf16 v[8:11], v[160:163], v[208:211], v[8:11]
	v_mfma_f32_16x16x32_bf16 v[60:63], v[156:159], v[188:191], v[60:63]
	v_mfma_f32_16x16x32_bf16 v[56:59], v[164:167], v[188:191], v[56:59]
	v_mfma_f32_16x16x32_bf16 v[44:47], v[156:159], v[196:199], v[44:47]
	v_mfma_f32_16x16x32_bf16 v[40:43], v[164:167], v[196:199], v[40:43]
	v_mfma_f32_16x16x32_bf16 v[28:31], v[156:159], v[204:207], v[28:31]
	v_mfma_f32_16x16x32_bf16 v[24:27], v[164:167], v[204:207], v[24:27]
	v_mfma_f32_16x16x32_bf16 v[12:15], v[156:159], v[212:215], v[12:15]
	v_mfma_f32_16x16x32_bf16 v[8:11], v[164:167], v[212:215], v[8:11]
	v_mfma_f32_16x16x32_bf16 v[52:55], v[168:171], v[184:187], v[52:55]
	v_mfma_f32_16x16x32_bf16 v[48:51], v[176:179], v[184:187], v[48:51]
	v_mfma_f32_16x16x32_bf16 v[36:39], v[168:171], v[192:195], v[36:39]
	v_mfma_f32_16x16x32_bf16 v[32:35], v[176:179], v[192:195], v[32:35]
	v_mfma_f32_16x16x32_bf16 v[20:23], v[168:171], v[200:203], v[20:23]
	v_mfma_f32_16x16x32_bf16 v[16:19], v[176:179], v[200:203], v[16:19]
	v_mfma_f32_16x16x32_bf16 v[4:7], v[168:171], v[208:211], v[4:7]
	v_mfma_f32_16x16x32_bf16 v[0:3], v[176:179], v[208:211], v[0:3]
	v_mfma_f32_16x16x32_bf16 v[52:55], v[172:175], v[188:191], v[52:55]
	v_mfma_f32_16x16x32_bf16 v[48:51], v[180:183], v[188:191], v[48:51]
	v_mfma_f32_16x16x32_bf16 v[36:39], v[172:175], v[196:199], v[36:39]
	v_mfma_f32_16x16x32_bf16 v[32:35], v[180:183], v[196:199], v[32:35]
	v_mfma_f32_16x16x32_bf16 v[20:23], v[172:175], v[204:207], v[20:23]
	v_mfma_f32_16x16x32_bf16 v[16:19], v[180:183], v[204:207], v[16:19]
	v_mfma_f32_16x16x32_bf16 v[4:7], v[172:175], v[212:215], v[4:7]
	v_mfma_f32_16x16x32_bf16 v[0:3], v[180:183], v[212:215], v[0:3]
	s_barrier
	s_add_i32 s58, 0, 0x18000
	s_add_i32 s59, 0, 0x1c000
	v_add_u32_e32 v164, s58, v148
	v_add_u32_e32 v180, s59, v148
	ds_read_b128 v[152:155], v164
	ds_read_b128 v[156:159], v164 offset:1024
	ds_read_b128 v[160:163], v164 offset:2048
	ds_read_b128 v[164:167], v164 offset:3072
	ds_read_b128 v[168:171], v180
	ds_read_b128 v[172:175], v180 offset:1024
	ds_read_b128 v[176:179], v180 offset:2048
	ds_read_b128 v[180:183], v180 offset:3072
	s_add_u32 s34, s34, 0x40000
	s_addc_u32 s35, s35, 0
	s_mov_b32 m0, s41
	v_lshl_add_u64 v[222:223], s[34:35], 0, v[136:137]
	ds_read_b128 v[184:187], v151 offset:32768
	ds_read_b128 v[188:191], v151 offset:33792
	ds_read_b128 v[192:195], v151 offset:34816
	ds_read_b128 v[196:199], v151 offset:35840
	ds_read_b128 v[200:203], v151 offset:36864
	ds_read_b128 v[204:207], v151 offset:37888
	ds_read_b128 v[208:211], v151 offset:38912
	ds_read_b128 v[212:215], v151 offset:39936
	global_load_lds_dwordx4 v[222:223], off
	v_lshl_add_u64 v[222:223], s[34:35], 0, v[132:133]
	s_mov_b32 m0, s42
	s_nop 0
	global_load_lds_dwordx4 v[222:223], off
	s_waitcnt vmcnt(8)
	s_waitcnt lgkmcnt(0)
	s_barrier
	v_mfma_f32_16x16x32_bf16 v[124:127], v[152:155], v[184:187], v[124:127]
	v_mfma_f32_16x16x32_bf16 v[120:123], v[160:163], v[184:187], v[120:123]
	v_mfma_f32_16x16x32_bf16 v[108:111], v[152:155], v[192:195], v[108:111]
	v_mfma_f32_16x16x32_bf16 v[104:107], v[160:163], v[192:195], v[104:107]
	v_mfma_f32_16x16x32_bf16 v[92:95], v[152:155], v[200:203], v[92:95]
	v_mfma_f32_16x16x32_bf16 v[88:91], v[160:163], v[200:203], v[88:91]
	v_mfma_f32_16x16x32_bf16 v[76:79], v[152:155], v[208:211], v[76:79]
	v_mfma_f32_16x16x32_bf16 v[72:75], v[160:163], v[208:211], v[72:75]
	v_mfma_f32_16x16x32_bf16 v[124:127], v[156:159], v[188:191], v[124:127]
	v_mfma_f32_16x16x32_bf16 v[120:123], v[164:167], v[188:191], v[120:123]
	v_mfma_f32_16x16x32_bf16 v[108:111], v[156:159], v[196:199], v[108:111]
	v_mfma_f32_16x16x32_bf16 v[104:107], v[164:167], v[196:199], v[104:107]
	v_mfma_f32_16x16x32_bf16 v[92:95], v[156:159], v[204:207], v[92:95]
	v_mfma_f32_16x16x32_bf16 v[88:91], v[164:167], v[204:207], v[88:91]
	v_mfma_f32_16x16x32_bf16 v[76:79], v[156:159], v[212:215], v[76:79]
	v_mfma_f32_16x16x32_bf16 v[72:75], v[164:167], v[212:215], v[72:75]
	v_mfma_f32_16x16x32_bf16 v[116:119], v[168:171], v[184:187], v[116:119]
	v_mfma_f32_16x16x32_bf16 v[112:115], v[176:179], v[184:187], v[112:115]
	v_mfma_f32_16x16x32_bf16 v[100:103], v[168:171], v[192:195], v[100:103]
	v_mfma_f32_16x16x32_bf16 v[96:99], v[176:179], v[192:195], v[96:99]
	v_mfma_f32_16x16x32_bf16 v[84:87], v[168:171], v[200:203], v[84:87]
	v_mfma_f32_16x16x32_bf16 v[80:83], v[176:179], v[200:203], v[80:83]
	v_mfma_f32_16x16x32_bf16 v[68:71], v[168:171], v[208:211], v[68:71]
	v_mfma_f32_16x16x32_bf16 v[64:67], v[176:179], v[208:211], v[64:67]
	v_mfma_f32_16x16x32_bf16 v[116:119], v[172:175], v[188:191], v[116:119]
	v_mfma_f32_16x16x32_bf16 v[112:115], v[180:183], v[188:191], v[112:115]
	v_mfma_f32_16x16x32_bf16 v[100:103], v[172:175], v[196:199], v[100:103]
	v_mfma_f32_16x16x32_bf16 v[96:99], v[180:183], v[196:199], v[96:99]
	v_mfma_f32_16x16x32_bf16 v[84:87], v[172:175], v[204:207], v[84:87]
	v_mfma_f32_16x16x32_bf16 v[80:83], v[180:183], v[204:207], v[80:83]
	v_mfma_f32_16x16x32_bf16 v[68:71], v[172:175], v[212:215], v[68:71]
	v_mfma_f32_16x16x32_bf16 v[64:67], v[180:183], v[212:215], v[64:67]
	s_barrier
; #define PG8_STAGE(bufoff, gbase, voff) do { _Pragma("unroll") for (int _i = 0; _i < 2; ++_i) \
;         __builtin_amdgcn_global_load_lds((const unsigned*)((const char*)(gbase) + (voff)[_i]), (LAS unsigned*)(lds + (bufoff) + ldsw + _i * 8192), 16, 0, 0); } while (0)
; #define PG8_LDA(dst, b, h) do { _Pragma("unroll") for (int m = 0; m < 4; ++m) _Pragma("unroll") for (int k = 0; k < 2; ++k) dst[m][k] = *(const LAS bf16x8*)(lds + PG8_SA(b, h) + aoff + m * 2048 + k * 1024); } while (0)
; #define PG8_MMA(ai, bj, At, Bt) do { __builtin_amdgcn_s_setprio(1); _Pragma("unroll") for (int m = 0; m < 4; ++m) _Pragma("unroll") for (int n = 0; n < 2; ++n) _Pragma("unroll") for (int k = 0; k < 2; ++k) \
;         acc[ai][bj][m][n] = __builtin_amdgcn_mfma_f32_16x16x32_bf16(Bt[n][k], At[m][k], acc[ai][bj][m][n], 0, 0, 0); __builtin_amdgcn_s_setprio(0); } while (0)
; #define PG8_WAIT_V(n) asm volatile("s_waitcnt vmcnt(" #n ")" ::: "memory")
; #define PG8_WAIT_L(n) asm volatile("s_waitcnt lgkmcnt(" #n ")" ::: "memory")
; #define PG8_BAR __builtin_amdgcn_s_barrier()
; #define PG8_SCHED __builtin_amdgcn_sched_barrier(0)
; template <class Epi, bool SP2 = false>
; __device__ __forceinline__ void gemm_phase(LAS unsigned char* lds, const Gemm g, const StaticOrder& S, const Epi& E) {
;     ...
;             PG8_LDA(At, 1, 1); PG8_STAGE(PG8_SB(1, 0), b3, voffB); PG8_STAGE(PG8_SB(1, 1), b3 + hstepB, voffB); PG8_STAGE(PG8_SA(1, 0), a3, voffA);
;             PG8_WAIT_V(8); PG8_WAIT_L(0); PG8_BAR; PG8_MMA(1, 0, At, B0); PG8_MMA(1, 1, At, B1); PG8_BAR; PG8_SCHED;
;     ...
;         if constexpr (SP2) { if (wr == 0) PG8_BAR; }
	s_add_i32 s34, s58, s37
	v_lshl_add_u64 v[146:147], v[146:147], 0, s[8:9]
	s_mov_b32 m0, s34
	ds_read_b128 v[184:187], v151 offset:49152
	ds_read_b128 v[188:191], v151 offset:50176
	ds_read_b128 v[192:195], v151 offset:51200
	ds_read_b128 v[196:199], v151 offset:52224
	ds_read_b128 v[200:203], v151 offset:53248
	ds_read_b128 v[204:207], v151 offset:54272
	ds_read_b128 v[208:211], v151 offset:55296
	ds_read_b128 v[212:215], v151 offset:56320
	global_load_lds_dwordx4 v[146:147], off
	s_add_i32 m0, s34, 0x2000
	s_add_u32 s30, s30, 0x40080
	v_lshl_add_u64 v[146:147], v[216:217], 0, s[8:9]
	s_addc_u32 s31, s31, 0
	s_add_i32 s34, s59, s37
	global_load_lds_dwordx4 v[146:147], off
	v_lshl_add_u64 v[146:147], s[30:31], 0, v[134:135]
	s_mov_b32 m0, s34
	s_nop 0
	global_load_lds_dwordx4 v[146:147], off
	v_lshl_add_u64 v[146:147], s[30:31], 0, v[130:131]
	s_add_i32 m0, s34, 0x2000
	s_nop 0
	global_load_lds_dwordx4 v[146:147], off
	v_lshl_add_u64 v[146:147], v[218:219], 0, s[8:9]
	s_mov_b32 m0, s46
	s_nop 0
	global_load_lds_dwordx4 v[146:147], off
	v_lshl_add_u64 v[146:147], v[220:221], 0, s[8:9]
	s_mov_b32 m0, s47
	s_nop 0
	global_load_lds_dwordx4 v[146:147], off
	s_waitcnt vmcnt(8)
	s_waitcnt lgkmcnt(0)
	s_barrier
	v_mfma_f32_16x16x32_bf16 v[60:63], v[152:155], v[184:187], v[60:63]
	v_mfma_f32_16x16x32_bf16 v[56:59], v[160:163], v[184:187], v[56:59]
	v_mfma_f32_16x16x32_bf16 v[44:47], v[152:155], v[192:195], v[44:47]
	v_mfma_f32_16x16x32_bf16 v[40:43], v[160:163], v[192:195], v[40:43]
	v_mfma_f32_16x16x32_bf16 v[28:31], v[152:155], v[200:203], v[28:31]
	v_mfma_f32_16x16x32_bf16 v[24:27], v[160:163], v[200:203], v[24:27]
	v_mfma_f32_16x16x32_bf16 v[12:15], v[152:155], v[208:211], v[12:15]
	v_mfma_f32_16x16x32_bf16 v[8:11], v[160:163], v[208:211], v[8:11]
	v_mfma_f32_16x16x32_bf16 v[60:63], v[156:159], v[188:191], v[60:63]
	v_mfma_f32_16x16x32_bf16 v[56:59], v[164:167], v[188:191], v[56:59]
	v_mfma_f32_16x16x32_bf16 v[44:47], v[156:159], v[196:199], v[44:47]
	v_mfma_f32_16x16x32_bf16 v[40:43], v[164:167], v[196:199], v[40:43]
	v_mfma_f32_16x16x32_bf16 v[28:31], v[156:159], v[204:207], v[28:31]
	v_mfma_f32_16x16x32_bf16 v[24:27], v[164:167], v[204:207], v[24:27]
	v_mfma_f32_16x16x32_bf16 v[12:15], v[156:159], v[212:215], v[12:15]
	v_mfma_f32_16x16x32_bf16 v[8:11], v[164:167], v[212:215], v[8:11]
	v_mfma_f32_16x16x32_bf16 v[52:55], v[168:171], v[184:187], v[52:55]
	v_mfma_f32_16x16x32_bf16 v[48:51], v[176:179], v[184:187], v[48:51]
	v_mfma_f32_16x16x32_bf16 v[36:39], v[168:171], v[192:195], v[36:39]
	v_mfma_f32_16x16x32_bf16 v[32:35], v[176:179], v[192:195], v[32:35]
	v_mfma_f32_16x16x32_bf16 v[20:23], v[168:171], v[200:203], v[20:23]
	v_mfma_f32_16x16x32_bf16 v[16:19], v[176:179], v[200:203], v[16:19]
	v_mfma_f32_16x16x32_bf16 v[4:7], v[168:171], v[208:211], v[4:7]
	v_mfma_f32_16x16x32_bf16 v[0:3], v[176:179], v[208:211], v[0:3]
	v_mfma_f32_16x16x32_bf16 v[52:55], v[172:175], v[188:191], v[52:55]
	v_mfma_f32_16x16x32_bf16 v[48:51], v[180:183], v[188:191], v[48:51]
	v_mfma_f32_16x16x32_bf16 v[36:39], v[172:175], v[196:199], v[36:39]
	v_mfma_f32_16x16x32_bf16 v[32:35], v[180:183], v[196:199], v[32:35]
	v_mfma_f32_16x16x32_bf16 v[20:23], v[172:175], v[204:207], v[20:23]
	v_mfma_f32_16x16x32_bf16 v[16:19], v[180:183], v[204:207], v[16:19]
	v_mfma_f32_16x16x32_bf16 v[4:7], v[172:175], v[212:215], v[4:7]
	v_mfma_f32_16x16x32_bf16 v[0:3], v[180:183], v[212:215], v[0:3]
	s_barrier
	s_add_i32 s57, s57, 2
	s_add_u32 s28, s28, 0x100
	s_addc_u32 s29, s29, 0
	s_add_u32 s55, s55, 0x100
	s_addc_u32 s56, s56, 0
	s_cmp_gt_u32 s57, 13
	s_cbranch_scc0 .LBB0_1077
	s_and_b64 vcc, exec, s[10:11]
	s_cbranch_vccz .LBB0_1080
	s_barrier

; #define PG8_STAGE(bufoff, gbase, voff) do { _Pragma("unroll") for (int _i = 0; _i < 2; ++_i) \
;         __builtin_amdgcn_global_load_lds((const unsigned*)((const char*)(gbase) + (voff)[_i]), (LAS unsigned*)(lds + (bufoff) + ldsw + _i * 8192), 16, 0, 0); } while (0)
; #define PG8_LDA(dst, b, h) do { _Pragma("unroll") for (int m = 0; m < 4; ++m) _Pragma("unroll") for (int k = 0; k < 2; ++k) dst[m][k] = *(const LAS bf16x8*)(lds + PG8_SA(b, h) + aoff + m * 2048 + k * 1024); } while (0)
; #define PG8_LDB(dst, b, h) do { _Pragma("unroll") for (int n = 0; n < 2; ++n) _Pragma("unroll") for (int k = 0; k < 2; ++k) dst[n][k] = *(const LAS bf16x8*)(lds + PG8_SB(b, h) + boff + n * 2048 + k * 1024); } while (0)
; #define PG8_MMA(ai, bj, At, Bt) do { __builtin_amdgcn_s_setprio(1); _Pragma("unroll") for (int m = 0; m < 4; ++m) _Pragma("unroll") for (int n = 0; n < 2; ++n) _Pragma("unroll") for (int k = 0; k < 2; ++k) \
;         acc[ai][bj][m][n] = __builtin_amdgcn_mfma_f32_16x16x32_bf16(Bt[n][k], At[m][k], acc[ai][bj][m][n], 0, 0, 0); __builtin_amdgcn_s_setprio(0); } while (0)
; #define PG8_WAIT_V(n) asm volatile("s_waitcnt vmcnt(" #n ")" ::: "memory")
; #define PG8_WAIT_L(n) asm volatile("s_waitcnt lgkmcnt(" #n ")" ::: "memory")
; #define PG8_BAR __builtin_amdgcn_s_barrier()
; #define PG8_SCHED __builtin_amdgcn_sched_barrier(0)
; template <class Epi, bool SP2 = false>
; __device__ __forceinline__ void gemm_phase(LAS unsigned char* lds, const Gemm g, const StaticOrder& S, const Epi& E) {
;     ...
;             const bool last = (t == nt - 2);
;             const char* a1 = cA + (size_t)(t + 1) * kstep;
;             const char* a2 = last ? nA : cA + (size_t)(t + 2) * kstep; const char* b2 = last ? nB : cB + (size_t)(t + 2) * kstep;
;             const char* a3 = a2 + kstep; const char* b3 = b2 + kstep;
;             if constexpr (SP2) {
;             PG8_LDB(B0, 0, 0); PG8_LDB(B1, 0, 1); PG8_SCHED; PG8_LDA(At, 0, 0); PG8_STAGE(PG8_SA(1, 1), a1 + hstepA, voffA);
;             PG8_WAIT_V(8); PG8_WAIT_L(0); PG8_BAR; PG8_MMA(0, 0, At, B0); PG8_MMA(0, 1, At, B1); PG8_BAR; PG8_SCHED;
;             PG8_LDA(At, 0, 1); PG8_STAGE(PG8_SB(0, 0), b2, voffB); PG8_STAGE(PG8_SB(0, 1), b2 + hstepB, voffB); PG8_STAGE(PG8_SA(0, 0), a2, voffA);
;             PG8_WAIT_V(8); PG8_WAIT_L(0); PG8_BAR; PG8_MMA(1, 0, At, B0); PG8_MMA(1, 1, At, B1); PG8_BAR; PG8_SCHED;
.LBB0_1148:
	ds_read_b128 v[150:153], v147
	ds_read_b128 v[154:157], v147 offset:1024
	ds_read_b128 v[158:161], v147 offset:2048
	ds_read_b128 v[162:165], v147 offset:3072
	ds_read_b128 v[166:169], v148
	ds_read_b128 v[170:173], v148 offset:1024
	ds_read_b128 v[174:177], v148 offset:2048
	ds_read_b128 v[178:181], v148 offset:3072
	s_add_u32 s34, s30, 0xfff50080
	s_addc_u32 s35, s31, -1
	s_cmp_eq_u32 s64, 40
	s_cselect_b32 s37, s5, s35
	s_cselect_b32 s36, s4, s34
	s_cselect_b32 s35, s29, s63
	s_cselect_b32 s34, s28, s62
	v_lshl_add_u64 v[214:215], s[30:31], 0, v[138:139]
	s_add_i32 m0, s41, 0xc000
	ds_read_b128 v[182:185], v149
	ds_read_b128 v[186:189], v149 offset:1024
	ds_read_b128 v[190:193], v149 offset:2048
	ds_read_b128 v[194:197], v149 offset:3072
	ds_read_b128 v[198:201], v149 offset:4096
	ds_read_b128 v[202:205], v149 offset:5120
	ds_read_b128 v[206:209], v149 offset:6144
	ds_read_b128 v[210:213], v149 offset:7168
	global_load_lds_dwordx4 v[214:215], off
	v_lshl_add_u64 v[214:215], s[30:31], 0, v[140:141]
	s_add_i32 m0, s41, 0xe000
	s_nop 0
	global_load_lds_dwordx4 v[214:215], off
	s_waitcnt vmcnt(8)
	s_waitcnt lgkmcnt(0)
	s_barrier
	v_mfma_f32_16x16x32_bf16 v[124:127], v[150:153], v[182:185], v[124:127]
	v_mfma_f32_16x16x32_bf16 v[120:123], v[158:161], v[182:185], v[120:123]
	v_mfma_f32_16x16x32_bf16 v[116:119], v[150:153], v[190:193], v[116:119]
	v_mfma_f32_16x16x32_bf16 v[112:115], v[158:161], v[190:193], v[112:115]
	v_mfma_f32_16x16x32_bf16 v[100:103], v[150:153], v[198:201], v[100:103]
	v_mfma_f32_16x16x32_bf16 v[96:99], v[158:161], v[198:201], v[96:99]
	v_mfma_f32_16x16x32_bf16 v[84:87], v[150:153], v[206:209], v[84:87]
	v_mfma_f32_16x16x32_bf16 v[80:83], v[158:161], v[206:209], v[80:83]
	v_mfma_f32_16x16x32_bf16 v[124:127], v[154:157], v[186:189], v[124:127]
	v_mfma_f32_16x16x32_bf16 v[120:123], v[162:165], v[186:189], v[120:123]
	v_mfma_f32_16x16x32_bf16 v[116:119], v[154:157], v[194:197], v[116:119]
	v_mfma_f32_16x16x32_bf16 v[112:115], v[162:165], v[194:197], v[112:115]
	v_mfma_f32_16x16x32_bf16 v[100:103], v[154:157], v[202:205], v[100:103]
	v_mfma_f32_16x16x32_bf16 v[96:99], v[162:165], v[202:205], v[96:99]
	v_mfma_f32_16x16x32_bf16 v[84:87], v[154:157], v[210:213], v[84:87]
	v_mfma_f32_16x16x32_bf16 v[80:83], v[162:165], v[210:213], v[80:83]
	v_mfma_f32_16x16x32_bf16 v[108:111], v[166:169], v[182:185], v[108:111]
	v_mfma_f32_16x16x32_bf16 v[104:107], v[174:177], v[182:185], v[104:107]
	v_mfma_f32_16x16x32_bf16 v[92:95], v[166:169], v[190:193], v[92:95]
	v_mfma_f32_16x16x32_bf16 v[88:91], v[174:177], v[190:193], v[88:91]
	v_mfma_f32_16x16x32_bf16 v[76:79], v[166:169], v[198:201], v[76:79]
	v_mfma_f32_16x16x32_bf16 v[72:75], v[174:177], v[198:201], v[72:75]
	v_mfma_f32_16x16x32_bf16 v[68:71], v[166:169], v[206:209], v[68:71]
	v_mfma_f32_16x16x32_bf16 v[64:67], v[174:177], v[206:209], v[64:67]
	v_mfma_f32_16x16x32_bf16 v[108:111], v[170:173], v[186:189], v[108:111]
	v_mfma_f32_16x16x32_bf16 v[104:107], v[178:181], v[186:189], v[104:107]
	v_mfma_f32_16x16x32_bf16 v[92:95], v[170:173], v[194:197], v[92:95]
	v_mfma_f32_16x16x32_bf16 v[88:91], v[178:181], v[194:197], v[88:91]
	v_mfma_f32_16x16x32_bf16 v[76:79], v[170:173], v[202:205], v[76:79]
	v_mfma_f32_16x16x32_bf16 v[72:75], v[178:181], v[202:205], v[72:75]
	v_mfma_f32_16x16x32_bf16 v[68:71], v[170:173], v[210:213], v[68:71]
	v_mfma_f32_16x16x32_bf16 v[64:67], v[178:181], v[210:213], v[64:67]
	s_barrier
	s_add_i32 s65, s52, s38
	v_lshl_add_u64 v[214:215], s[34:35], 0, v[134:135]
	s_mov_b32 m0, s65
	ds_read_b128 v[182:185], v149 offset:16384
	ds_read_b128 v[186:189], v149 offset:17408
	ds_read_b128 v[190:193], v149 offset:18432
	ds_read_b128 v[194:197], v149 offset:19456
	ds_read_b128 v[198:201], v149 offset:20480
	ds_read_b128 v[202:205], v149 offset:21504
	ds_read_b128 v[206:209], v149 offset:22528
	ds_read_b128 v[210:213], v149 offset:23552
	global_load_lds_dwordx4 v[214:215], off
	s_add_i32 m0, s65, 0x2000
	s_add_u32 s66, s34, 0xb0000
	v_lshl_add_u64 v[216:217], s[34:35], 0, v[130:131]
	s_addc_u32 s67, s35, 0
	s_add_i32 s65, s53, s38
	global_load_lds_dwordx4 v[216:217], off
	v_lshl_add_u64 v[218:219], s[66:67], 0, v[134:135]
	s_mov_b32 m0, s65
	v_lshl_add_u64 v[220:221], s[36:37], 0, v[132:133]
	global_load_lds_dwordx4 v[218:219], off
	v_lshl_add_u64 v[218:219], s[66:67], 0, v[130:131]
	s_add_i32 m0, s65, 0x2000
	s_nop 0
	global_load_lds_dwordx4 v[218:219], off
	v_lshl_add_u64 v[218:219], s[36:37], 0, v[136:137]
	s_mov_b32 m0, s41
	s_nop 0
	global_load_lds_dwordx4 v[218:219], off
	s_mov_b32 m0, s42
	s_nop 0
	global_load_lds_dwordx4 v[220:221], off
	s_waitcnt vmcnt(8)
	s_waitcnt lgkmcnt(0)
	s_barrier
; #define PG8_STAGE(bufoff, gbase, voff) do { _Pragma("unroll") for (int _i = 0; _i < 2; ++_i) \
;         __builtin_amdgcn_global_load_lds((const unsigned*)((const char*)(gbase) + (voff)[_i]), (LAS unsigned*)(lds + (bufoff) + ldsw + _i * 8192), 16, 0, 0); } while (0)
; #define PG8_LDA(dst, b, h) do { _Pragma("unroll") for (int m = 0; m < 4; ++m) _Pragma("unroll") for (int k = 0; k < 2; ++k) dst[m][k] = *(const LAS bf16x8*)(lds + PG8_SA(b, h) + aoff + m * 2048 + k * 1024); } while (0)
; #define PG8_LDB(dst, b, h) do { _Pragma("unroll") for (int n = 0; n < 2; ++n) _Pragma("unroll") for (int k = 0; k < 2; ++k) dst[n][k] = *(const LAS bf16x8*)(lds + PG8_SB(b, h) + boff + n * 2048 + k * 1024); } while (0)
; #define PG8_MMA(ai, bj, At, Bt) do { __builtin_amdgcn_s_setprio(1); _Pragma("unroll") for (int m = 0; m < 4; ++m) _Pragma("unroll") for (int n = 0; n < 2; ++n) _Pragma("unroll") for (int k = 0; k < 2; ++k) \
;         acc[ai][bj][m][n] = __builtin_amdgcn_mfma_f32_16x16x32_bf16(Bt[n][k], At[m][k], acc[ai][bj][m][n], 0, 0, 0); __builtin_amdgcn_s_setprio(0); } while (0)
; #define PG8_WAIT_V(n) asm volatile("s_waitcnt vmcnt(" #n ")" ::: "memory")
; #define PG8_WAIT_L(n) asm volatile("s_waitcnt lgkmcnt(" #n ")" ::: "memory")
; #define PG8_BAR __builtin_amdgcn_s_barrier()
; #define PG8_SCHED __builtin_amdgcn_sched_barrier(0)
; template <class Epi, bool SP2 = false>
; __device__ __forceinline__ void gemm_phase(LAS unsigned char* lds, const Gemm g, const StaticOrder& S, const Epi& E) {
;     ...
;             PG8_WAIT_V(8); PG8_WAIT_L(0); PG8_BAR; PG8_MMA(1, 0, At, B0); PG8_MMA(1, 1, At, B1); PG8_BAR; PG8_SCHED;
;             PG8_LDB(B0, 1, 0); PG8_LDB(B1, 1, 1); PG8_SCHED; PG8_LDA(At, 1, 0); PG8_STAGE(PG8_SA(0, 1), a2 + hstepA, voffA);
;             PG8_WAIT_V(8); PG8_WAIT_L(0); PG8_BAR; PG8_MMA(0, 0, At, B0); PG8_MMA(0, 1, At, B1); PG8_BAR; PG8_SCHED;
	v_mfma_f32_16x16x32_bf16 v[60:63], v[150:153], v[182:185], v[60:63]
	v_mfma_f32_16x16x32_bf16 v[56:59], v[158:161], v[182:185], v[56:59]
	v_mfma_f32_16x16x32_bf16 v[52:55], v[150:153], v[190:193], v[52:55]
	v_mfma_f32_16x16x32_bf16 v[48:51], v[158:161], v[190:193], v[48:51]
	v_mfma_f32_16x16x32_bf16 v[36:39], v[150:153], v[198:201], v[36:39]
	v_mfma_f32_16x16x32_bf16 v[32:35], v[158:161], v[198:201], v[32:35]
	v_mfma_f32_16x16x32_bf16 v[20:23], v[150:153], v[206:209], v[20:23]
	v_mfma_f32_16x16x32_bf16 v[16:19], v[158:161], v[206:209], v[16:19]
	v_mfma_f32_16x16x32_bf16 v[60:63], v[154:157], v[186:189], v[60:63]
	v_mfma_f32_16x16x32_bf16 v[56:59], v[162:165], v[186:189], v[56:59]
	v_mfma_f32_16x16x32_bf16 v[52:55], v[154:157], v[194:197], v[52:55]
	v_mfma_f32_16x16x32_bf16 v[48:51], v[162:165], v[194:197], v[48:51]
	v_mfma_f32_16x16x32_bf16 v[36:39], v[154:157], v[202:205], v[36:39]
	v_mfma_f32_16x16x32_bf16 v[32:35], v[162:165], v[202:205], v[32:35]
	v_mfma_f32_16x16x32_bf16 v[20:23], v[154:157], v[210:213], v[20:23]
	v_mfma_f32_16x16x32_bf16 v[16:19], v[162:165], v[210:213], v[16:19]
	v_mfma_f32_16x16x32_bf16 v[44:47], v[166:169], v[182:185], v[44:47]
	v_mfma_f32_16x16x32_bf16 v[40:43], v[174:177], v[182:185], v[40:43]
	v_mfma_f32_16x16x32_bf16 v[28:31], v[166:169], v[190:193], v[28:31]
	v_mfma_f32_16x16x32_bf16 v[24:27], v[174:177], v[190:193], v[24:27]
	v_mfma_f32_16x16x32_bf16 v[12:15], v[166:169], v[198:201], v[12:15]
	v_mfma_f32_16x16x32_bf16 v[8:11], v[174:177], v[198:201], v[8:11]
	v_mfma_f32_16x16x32_bf16 v[4:7], v[166:169], v[206:209], v[4:7]
	v_mfma_f32_16x16x32_bf16 v[0:3], v[174:177], v[206:209], v[0:3]
	v_mfma_f32_16x16x32_bf16 v[44:47], v[170:173], v[186:189], v[44:47]
	v_mfma_f32_16x16x32_bf16 v[40:43], v[178:181], v[186:189], v[40:43]
	v_mfma_f32_16x16x32_bf16 v[28:31], v[170:173], v[194:197], v[28:31]
	v_mfma_f32_16x16x32_bf16 v[24:27], v[178:181], v[194:197], v[24:27]
	v_mfma_f32_16x16x32_bf16 v[12:15], v[170:173], v[202:205], v[12:15]
	v_mfma_f32_16x16x32_bf16 v[8:11], v[178:181], v[202:205], v[8:11]
	v_mfma_f32_16x16x32_bf16 v[4:7], v[170:173], v[210:213], v[4:7]
	v_mfma_f32_16x16x32_bf16 v[0:3], v[178:181], v[210:213], v[0:3]
	s_barrier
	s_add_i32 s65, 0, 0x18000
	s_add_i32 s66, 0, 0x1c000
	v_add_u32_e32 v162, s65, v146
	v_add_u32_e32 v178, s66, v146
	ds_read_b128 v[150:153], v162
	ds_read_b128 v[154:157], v162 offset:1024
	ds_read_b128 v[158:161], v162 offset:2048
	ds_read_b128 v[162:165], v162 offset:3072
	ds_read_b128 v[166:169], v178
	ds_read_b128 v[170:173], v178 offset:1024
	ds_read_b128 v[174:177], v178 offset:2048
	ds_read_b128 v[178:181], v178 offset:3072
	s_add_u32 s36, s36, 0xb0000
	s_addc_u32 s37, s37, 0
	s_mov_b32 m0, s43
	v_lshl_add_u64 v[222:223], s[36:37], 0, v[136:137]
	ds_read_b128 v[182:185], v149 offset:32768
	ds_read_b128 v[186:189], v149 offset:33792
	ds_read_b128 v[190:193], v149 offset:34816
	ds_read_b128 v[194:197], v149 offset:35840
	ds_read_b128 v[198:201], v149 offset:36864
	ds_read_b128 v[202:205], v149 offset:37888
	ds_read_b128 v[206:209], v149 offset:38912
	ds_read_b128 v[210:213], v149 offset:39936
	global_load_lds_dwordx4 v[222:223], off
	v_lshl_add_u64 v[222:223], s[36:37], 0, v[132:133]
	s_mov_b32 m0, s44
	s_nop 0
	global_load_lds_dwordx4 v[222:223], off
	s_waitcnt vmcnt(8)
	s_waitcnt lgkmcnt(0)
	s_barrier
	v_mfma_f32_16x16x32_bf16 v[124:127], v[150:153], v[182:185], v[124:127]
	v_mfma_f32_16x16x32_bf16 v[120:123], v[158:161], v[182:185], v[120:123]
	v_mfma_f32_16x16x32_bf16 v[116:119], v[150:153], v[190:193], v[116:119]
	v_mfma_f32_16x16x32_bf16 v[112:115], v[158:161], v[190:193], v[112:115]
	v_mfma_f32_16x16x32_bf16 v[100:103], v[150:153], v[198:201], v[100:103]
	v_mfma_f32_16x16x32_bf16 v[96:99], v[158:161], v[198:201], v[96:99]
	v_mfma_f32_16x16x32_bf16 v[84:87], v[150:153], v[206:209], v[84:87]
	v_mfma_f32_16x16x32_bf16 v[80:83], v[158:161], v[206:209], v[80:83]
	v_mfma_f32_16x16x32_bf16 v[124:127], v[154:157], v[186:189], v[124:127]
	v_mfma_f32_16x16x32_bf16 v[120:123], v[162:165], v[186:189], v[120:123]
	v_mfma_f32_16x16x32_bf16 v[116:119], v[154:157], v[194:197], v[116:119]
	v_mfma_f32_16x16x32_bf16 v[112:115], v[162:165], v[194:197], v[112:115]
	v_mfma_f32_16x16x32_bf16 v[100:103], v[154:157], v[202:205], v[100:103]
	v_mfma_f32_16x16x32_bf16 v[96:99], v[162:165], v[202:205], v[96:99]
	v_mfma_f32_16x16x32_bf16 v[84:87], v[154:157], v[210:213], v[84:87]
	v_mfma_f32_16x16x32_bf16 v[80:83], v[162:165], v[210:213], v[80:83]
	v_mfma_f32_16x16x32_bf16 v[108:111], v[166:169], v[182:185], v[108:111]
	v_mfma_f32_16x16x32_bf16 v[104:107], v[174:177], v[182:185], v[104:107]
	v_mfma_f32_16x16x32_bf16 v[92:95], v[166:169], v[190:193], v[92:95]
	v_mfma_f32_16x16x32_bf16 v[88:91], v[174:177], v[190:193], v[88:91]
	v_mfma_f32_16x16x32_bf16 v[76:79], v[166:169], v[198:201], v[76:79]
	v_mfma_f32_16x16x32_bf16 v[72:75], v[174:177], v[198:201], v[72:75]
	v_mfma_f32_16x16x32_bf16 v[68:71], v[166:169], v[206:209], v[68:71]
	v_mfma_f32_16x16x32_bf16 v[64:67], v[174:177], v[206:209], v[64:67]
	v_mfma_f32_16x16x32_bf16 v[108:111], v[170:173], v[186:189], v[108:111]
	v_mfma_f32_16x16x32_bf16 v[104:107], v[178:181], v[186:189], v[104:107]
	v_mfma_f32_16x16x32_bf16 v[92:95], v[170:173], v[194:197], v[92:95]
	v_mfma_f32_16x16x32_bf16 v[88:91], v[178:181], v[194:197], v[88:91]
	v_mfma_f32_16x16x32_bf16 v[76:79], v[170:173], v[202:205], v[76:79]
	v_mfma_f32_16x16x32_bf16 v[72:75], v[178:181], v[202:205], v[72:75]
	v_mfma_f32_16x16x32_bf16 v[68:71], v[170:173], v[210:213], v[68:71]
	v_mfma_f32_16x16x32_bf16 v[64:67], v[178:181], v[210:213], v[64:67]
	s_barrier
; #define PG8_STAGE(bufoff, gbase, voff) do { _Pragma("unroll") for (int _i = 0; _i < 2; ++_i) \
;         __builtin_amdgcn_global_load_lds((const unsigned*)((const char*)(gbase) + (voff)[_i]), (LAS unsigned*)(lds + (bufoff) + ldsw + _i * 8192), 16, 0, 0); } while (0)
; #define PG8_LDA(dst, b, h) do { _Pragma("unroll") for (int m = 0; m < 4; ++m) _Pragma("unroll") for (int k = 0; k < 2; ++k) dst[m][k] = *(const LAS bf16x8*)(lds + PG8_SA(b, h) + aoff + m * 2048 + k * 1024); } while (0)
; #define PG8_MMA(ai, bj, At, Bt) do { __builtin_amdgcn_s_setprio(1); _Pragma("unroll") for (int m = 0; m < 4; ++m) _Pragma("unroll") for (int n = 0; n < 2; ++n) _Pragma("unroll") for (int k = 0; k < 2; ++k) \
;         acc[ai][bj][m][n] = __builtin_amdgcn_mfma_f32_16x16x32_bf16(Bt[n][k], At[m][k], acc[ai][bj][m][n], 0, 0, 0); __builtin_amdgcn_s_setprio(0); } while (0)
; #define PG8_WAIT_V(n) asm volatile("s_waitcnt vmcnt(" #n ")" ::: "memory")
; #define PG8_WAIT_L(n) asm volatile("s_waitcnt lgkmcnt(" #n ")" ::: "memory")
; #define PG8_BAR __builtin_amdgcn_s_barrier()
; #define PG8_SCHED __builtin_amdgcn_sched_barrier(0)
; template <class Epi, bool SP2 = false>
; __device__ __forceinline__ void gemm_phase(LAS unsigned char* lds, const Gemm g, const StaticOrder& S, const Epi& E) {
;     ...
;             PG8_LDA(At, 1, 1); PG8_STAGE(PG8_SB(1, 0), b3, voffB); PG8_STAGE(PG8_SB(1, 1), b3 + hstepB, voffB); PG8_STAGE(PG8_SA(1, 0), a3, voffA);
;             PG8_WAIT_V(8); PG8_WAIT_L(0); PG8_BAR; PG8_MMA(1, 0, At, B0); PG8_MMA(1, 1, At, B1); PG8_BAR; PG8_SCHED;
;     ...
;         if constexpr (SP2) { if (wr == 0) PG8_BAR; }
	s_add_i32 s36, s65, s38
	v_lshl_add_u64 v[214:215], v[214:215], 0, s[10:11]
	s_mov_b32 m0, s36
	ds_read_b128 v[182:185], v149 offset:49152
	ds_read_b128 v[186:189], v149 offset:50176
	ds_read_b128 v[190:193], v149 offset:51200
	ds_read_b128 v[194:197], v149 offset:52224
	ds_read_b128 v[198:201], v149 offset:53248
	ds_read_b128 v[202:205], v149 offset:54272
	ds_read_b128 v[206:209], v149 offset:55296
	ds_read_b128 v[210:213], v149 offset:56320
	global_load_lds_dwordx4 v[214:215], off
	s_add_i32 m0, s36, 0x2000
	s_add_u32 s34, s34, 0xb0080
	v_lshl_add_u64 v[214:215], v[216:217], 0, s[10:11]
	s_addc_u32 s35, s35, 0
	s_add_i32 s36, s66, s38
	global_load_lds_dwordx4 v[214:215], off
	v_lshl_add_u64 v[214:215], s[34:35], 0, v[134:135]
	s_mov_b32 m0, s36
	s_nop 0
	global_load_lds_dwordx4 v[214:215], off
	v_lshl_add_u64 v[214:215], s[34:35], 0, v[130:131]
	s_add_i32 m0, s36, 0x2000
	s_nop 0
	global_load_lds_dwordx4 v[214:215], off
	v_lshl_add_u64 v[214:215], v[218:219], 0, s[10:11]
	s_mov_b32 m0, s48
	s_nop 0
	global_load_lds_dwordx4 v[214:215], off
	v_lshl_add_u64 v[214:215], v[220:221], 0, s[10:11]
	s_mov_b32 m0, s49
	s_nop 0
	global_load_lds_dwordx4 v[214:215], off
	s_waitcnt vmcnt(8)
	s_waitcnt lgkmcnt(0)
	s_barrier
	v_mfma_f32_16x16x32_bf16 v[60:63], v[150:153], v[182:185], v[60:63]
	v_mfma_f32_16x16x32_bf16 v[56:59], v[158:161], v[182:185], v[56:59]
	v_mfma_f32_16x16x32_bf16 v[52:55], v[150:153], v[190:193], v[52:55]
	v_mfma_f32_16x16x32_bf16 v[48:51], v[158:161], v[190:193], v[48:51]
	v_mfma_f32_16x16x32_bf16 v[36:39], v[150:153], v[198:201], v[36:39]
	v_mfma_f32_16x16x32_bf16 v[32:35], v[158:161], v[198:201], v[32:35]
	v_mfma_f32_16x16x32_bf16 v[20:23], v[150:153], v[206:209], v[20:23]
	v_mfma_f32_16x16x32_bf16 v[16:19], v[158:161], v[206:209], v[16:19]
	v_mfma_f32_16x16x32_bf16 v[60:63], v[154:157], v[186:189], v[60:63]
	v_mfma_f32_16x16x32_bf16 v[56:59], v[162:165], v[186:189], v[56:59]
	v_mfma_f32_16x16x32_bf16 v[52:55], v[154:157], v[194:197], v[52:55]
	v_mfma_f32_16x16x32_bf16 v[48:51], v[162:165], v[194:197], v[48:51]
	v_mfma_f32_16x16x32_bf16 v[36:39], v[154:157], v[202:205], v[36:39]
	v_mfma_f32_16x16x32_bf16 v[32:35], v[162:165], v[202:205], v[32:35]
	v_mfma_f32_16x16x32_bf16 v[20:23], v[154:157], v[210:213], v[20:23]
	v_mfma_f32_16x16x32_bf16 v[16:19], v[162:165], v[210:213], v[16:19]
	v_mfma_f32_16x16x32_bf16 v[44:47], v[166:169], v[182:185], v[44:47]
	v_mfma_f32_16x16x32_bf16 v[40:43], v[174:177], v[182:185], v[40:43]
	v_mfma_f32_16x16x32_bf16 v[28:31], v[166:169], v[190:193], v[28:31]
	v_mfma_f32_16x16x32_bf16 v[24:27], v[174:177], v[190:193], v[24:27]
	v_mfma_f32_16x16x32_bf16 v[12:15], v[166:169], v[198:201], v[12:15]
	v_mfma_f32_16x16x32_bf16 v[8:11], v[174:177], v[198:201], v[8:11]
	v_mfma_f32_16x16x32_bf16 v[4:7], v[166:169], v[206:209], v[4:7]
	v_mfma_f32_16x16x32_bf16 v[0:3], v[174:177], v[206:209], v[0:3]
	v_mfma_f32_16x16x32_bf16 v[44:47], v[170:173], v[186:189], v[44:47]
	v_mfma_f32_16x16x32_bf16 v[40:43], v[178:181], v[186:189], v[40:43]
	v_mfma_f32_16x16x32_bf16 v[28:31], v[170:173], v[194:197], v[28:31]
	v_mfma_f32_16x16x32_bf16 v[24:27], v[178:181], v[194:197], v[24:27]
	v_mfma_f32_16x16x32_bf16 v[12:15], v[170:173], v[202:205], v[12:15]
	v_mfma_f32_16x16x32_bf16 v[8:11], v[178:181], v[202:205], v[8:11]
	v_mfma_f32_16x16x32_bf16 v[4:7], v[170:173], v[210:213], v[4:7]
	v_mfma_f32_16x16x32_bf16 v[0:3], v[178:181], v[210:213], v[0:3]
	s_barrier
	s_add_i32 s64, s64, 2
	s_add_u32 s30, s30, 0x100
	s_addc_u32 s31, s31, 0
	s_add_u32 s62, s62, 0x100
	s_addc_u32 s63, s63, 0
	s_cmp_gt_u32 s64, 41
	s_cbranch_scc0 .LBB0_1148
	s_and_b64 vcc, exec, s[12:13]
	s_cbranch_vccz .LBB0_1151
	s_barrier
